# k19 plus cold q/k chunk loads sunk below the first wait in the GLA item loops so their latency overlaps the cumulative-decay computation
# baseline (speedup 1.0000x reference)
; #define LAS __attribute__((address_space(3)))
; #define TID() (wv0 * 64 + (int)__builtin_amdgcn_mbcnt_hi(~0u, __builtin_amdgcn_mbcnt_lo(~0u, 0u)))
; __device__ __forceinline__ int opaque(int x) { asm volatile("" : "+v"(x)); return x; }
;     __device__ __forceinline__ const float* in(int k) const { return (const float*)(const __attribute__((address_space(1))) float*)get(k); }
;     __device__ __forceinline__ unsigned char* ws() const { return (unsigned char*)(__attribute__((address_space(1))) unsigned char*)get(21); }
; __device__ __forceinline__ void gla_cumdecay(const Ptrs& A, int l, int n, int hd, LAS float* bl, const int wv0) {
;     const int tid = opaque(TID()), d = tid & 127, tq = __builtin_amdgcn_readfirstlane(tid >> 7);
;     const float* wa2 = A.in(4) + (size_t)l * 16 * 512 + hd * 128 + d;
;     float w[16];
; #pragma unroll
;     for (int r = 0; r < 16; ++r) w[r] = wa2[r * 512];
;     const float bias = A.in(5)[(size_t)l * 512 + hd * 128 + d];
;     LAS float* gal = bl + 29184;
;     *(LAS f32x2*)(gal + 2 * tid) = *(const f32x2*)((const float*)(A.ws() + WS_GA1) + (size_t)n * 64 * 16 + 2 * tid);
;     __syncthreads();
;     const LAS float* ga = gal + 16 * tq * 16;
;     float run = 0.f;
;     for (int tt = 0; tt < 16; ++tt) {
;         float pre = bias;
;         const f32x4 g0 = *(const LAS f32x4*)(ga + tt * 16), g1 = *(const LAS f32x4*)(ga + tt * 16 + 4), g2 = *(const LAS f32x4*)(ga + tt * 16 + 8), g3 = *(const LAS f32x4*)(ga + tt * 16 + 12);
;         pre += (g0.x * w[0] + g0.y * w[1]) + (g0.z * w[2] + g0.w * w[3]); pre += (g1.x * w[4] + g1.y * w[5]) + (g1.z * w[6] + g1.w * w[7]);
;         pre += (g2.x * w[8] + g2.y * w[9]) + (g2.z * w[10] + g2.w * w[11]); pre += (g3.x * w[12] + g3.y * w[13]) + (g3.z * w[14] + g3.w * w[15]);
;         const float la = (fminf(pre, 0.f) - __logf(1.0f + __expf(-fabsf(pre)))) * (1.0f / 16.0f);
;         run += la; bl[(16 * tq + tt) * BLS + d] = run;
; __device__ __forceinline__ void gla_state(const Ptrs& A, int l, LAS unsigned char* lds, int c, int G, int wave, int lane_, const int wv0) {
;     ...
;         u32x4 kk[2];
; #pragma unroll
;         for (int i = 0; i < 2; ++i) kk[i] = *(const u32x4*)(GK + (size_t)(t0 + lane) * 512 + hd * 128 + (wave + 8 * i) * 8);
;         gla_cumdecay(A, l, n, hd, bl, wv0);
.LBB0_211:
	s_ashr_i32 s2, s6, 2
	s_lshl_b32 s20, s2, 6
	v_or_b32_e32 v0, s20, v64
	v_ashrrev_i32_e32 v1, 31, v0
	s_and_b32 s3, s6, 3
	v_lshlrev_b64 v[0:1], 10, v[0:1]
	v_lshl_add_u64 v[0:1], s[12:13], 0, v[0:1]
	s_lshl_b32 s8, s3, 8
	v_lshl_add_u64 v[0:1], v[0:1], 0, s[8:9]
	v_lshl_add_u64 v[8:9], s[14:15], 1, v[0:1]
	v_mov_b32_e32 v34, v204
	v_mov_b32_e32 v198, v8
	v_mov_b32_e32 v199, v9
	v_mov_b32 v8, s77
	ds_read_b64 v[8:9], v8 offset:32
	s_lshl_b32 s8, s3, 9
	v_readfirstlane_b32 s3, v34
	s_waitcnt lgkmcnt(0)
	v_readfirstlane_b32 s47, v8
	v_readfirstlane_b32 s21, v9
	s_add_u32 s48, s47, s8
	v_lshlrev_b32_e32 v8, 2, v34
	s_addc_u32 s49, s21, 0
	v_and_b32_e32 v48, 0x1fc, v8
	v_lshl_add_u64 v[18:19], s[48:49], 0, v[48:49]
	v_add_co_u32_e32 v26, vcc, s5, v18
	s_ashr_i32 s21, s3, 7
	s_nop 0
	v_addc_co_u32_e32 v27, vcc, 0, v19, vcc
	v_add_co_u32_e32 v20, vcc, s7, v18
	s_nop 1
	v_addc_co_u32_e32 v21, vcc, 0, v19, vcc
	v_add_co_u32_e32 v28, vcc, s28, v18
	s_nop 1
	v_addc_co_u32_e32 v29, vcc, 0, v19, vcc
	v_add_co_u32_e32 v10, vcc, s29, v18
	s_nop 1
	v_addc_co_u32_e32 v11, vcc, 0, v19, vcc
	v_add_co_u32_e32 v30, vcc, s30, v18
	s_nop 1
	v_addc_co_u32_e32 v31, vcc, 0, v19, vcc
	v_add_co_u32_e32 v22, vcc, s31, v18
	s_nop 1
	v_addc_co_u32_e32 v23, vcc, 0, v19, vcc
	v_add_co_u32_e32 v32, vcc, s34, v18
	global_load_dword v14, v[20:21], off
	global_load_dword v16, v[20:21], off offset:2048
	global_load_dword v13, v[10:11], off offset:-4096
	global_load_dword v9, v[10:11], off
	global_load_dword v12, v[10:11], off offset:2048
	s_nop 0
	global_load_dword v10, v[22:23], off offset:-4096
	global_load_dword v8, v[22:23], off
	global_load_dword v11, v[22:23], off offset:2048
	v_addc_co_u32_e32 v33, vcc, 0, v19, vcc
	global_load_dword v22, v48, s[48:49]
	global_load_dword v24, v48, s[48:49] offset:2048
	s_nop 0
	global_load_dword v21, v[20:21], off offset:-4096
	s_nop 0
	global_load_dword v23, v[26:27], off offset:2048
	global_load_dword v20, v[28:29], off offset:2048
	global_load_dword v18, v[30:31], off offset:2048
	global_load_dword v15, v[32:33], off
	global_load_dword v17, v[32:33], off offset:2048
	v_mov_b32 v19, s77
	ds_read_b64 v[26:27], v19 offset:40
	s_waitcnt lgkmcnt(0)
	v_readfirstlane_b32 s47, v26
	v_readfirstlane_b32 s3, v27
	s_add_u32 s48, s47, s8
	s_addc_u32 s49, s3, 0
	global_load_dword v25, v48, s[48:49]
	v_mov_b32 v19, s77
	ds_read_b64 v[26:27], v19 offset:168
	s_ashr_i32 s3, s2, 31
	s_lshl_b64 s[2:3], s[2:3], 12
	v_lshl_add_u32 v19, v34, 3, s36
	s_waitcnt lgkmcnt(0)
	v_readfirstlane_b32 s48, v26
	v_readfirstlane_b32 s47, v27
	s_add_u32 s2, s48, s2
	v_lshlrev_b32_e32 v26, 1, v34
	s_addc_u32 s3, s47, s3
	v_ashrrev_i32_e32 v27, 31, v26
	v_lshl_add_u64 v[26:27], v[26:27], 2, s[2:3]
	v_add_co_u32_e32 v26, vcc, s35, v26
	s_lshl_b32 s2, s21, 10
	s_nop 0
	v_addc_co_u32_e32 v27, vcc, 0, v27, vcc
	global_load_dwordx2 v[28:29], v[26:27], off
	s_add_i32 s2, s36, s2
	v_mov_b32_e32 v27, s2
	s_mul_i32 s2, s21, 0x2100
	s_cmp_gt_i32 s21, 0
	global_load_dwordx4 v[4:7], v[198:199], off
	global_load_dwordx4 v[0:3], v[198:199], off offset:128
	s_waitcnt vmcnt(2)
	ds_write_b64 v19, v[28:29]
	s_waitcnt lgkmcnt(0)
	s_barrier
	ds_read_b128 v[28:31], v27
	ds_read_b128 v[32:35], v27 offset:16
	ds_read_b128 v[36:39], v27 offset:32
	ds_read_b128 v[40:43], v27 offset:48
	s_waitcnt lgkmcnt(3)
	v_mul_f32_e32 v19, v24, v29
	v_mul_f32_e32 v26, v23, v31
	s_waitcnt lgkmcnt(2)
	v_mul_f32_e32 v29, v16, v33
	v_mul_f32_e32 v31, v20, v35
	v_fmac_f32_e32 v19, v22, v28
	v_fmac_f32_e32 v26, v21, v30
	s_waitcnt lgkmcnt(1)
	v_mul_f32_e32 v33, v12, v37
	v_mul_f32_e32 v35, v18, v39
	v_fmac_f32_e32 v29, v14, v32
	v_fmac_f32_e32 v31, v13, v34
	v_add_f32_e32 v19, v19, v26
	s_waitcnt lgkmcnt(0)
	ds_read_b128 v[166:169], v27 offset:64
	ds_read_b128 v[170:173], v27 offset:80
	ds_read_b128 v[174:177], v27 offset:96
	ds_read_b128 v[178:181], v27 offset:112
	v_mul_f32_e32 v37, v11, v41
	v_mul_f32_e32 v39, v17, v43
	v_fmac_f32_e32 v33, v9, v36
	v_fmac_f32_e32 v35, v10, v38
	v_add_f32_e32 v26, v29, v31
	v_add_f32_e32 v19, v25, v19
	v_fmac_f32_e32 v37, v8, v40
	v_fmac_f32_e32 v39, v15, v42
	v_add_f32_e32 v28, v33, v35
	v_add_f32_e32 v19, v19, v26
	v_add_f32_e32 v29, v37, v39
	v_add_f32_e32 v19, v19, v28
	v_add_f32_e32 v28, v19, v29
	v_mul_f32_e64 v19, |v28|, s37
	v_exp_f32_e32 v19, v19
	v_min_f32_e32 v28, 0, v28
	v_add_u32_e32 v26, 0, v48
	v_add_f32_e32 v19, 1.0, v19
	v_cmp_gt_f32_e32 vcc, s38, v19
	s_nop 1
	v_cndmask_b32_e64 v29, 0, 32, vcc
	v_ldexp_f32 v19, v19, v29
	v_log_f32_e32 v29, v19
	v_cndmask_b32_e32 v30, 0, v69, vcc
	v_add_u32_e32 v19, s2, v26
	v_mul_f32_e32 v31, 0x3f317217, v29
	v_fma_f32 v31, v29, s39, -v31
	v_fmac_f32_e32 v31, 0x3377d1cf, v29
	v_fmac_f32_e32 v31, 0x3f317217, v29
	v_cmp_lt_f32_e64 vcc, |v29|, s40
	s_nop 1
	v_cndmask_b32_e32 v29, v29, v31, vcc
	v_sub_f32_e32 v29, v29, v30
	v_sub_f32_e32 v28, v28, v29
	v_fma_f32 v28, v28, s41, 0
	ds_write_b32 v19, v28
	s_waitcnt lgkmcnt(3)
	v_mul_f32_e32 v29, v24, v167
	v_mul_f32_e32 v31, v23, v169
	v_fmac_f32_e32 v29, v22, v166
	v_fmac_f32_e32 v31, v21, v168
	v_add_f32_e32 v29, v29, v31
	s_waitcnt lgkmcnt(2)
	v_mul_f32_e32 v30, v16, v171
	v_mul_f32_e32 v31, v20, v173
	v_fmac_f32_e32 v30, v14, v170
	v_fmac_f32_e32 v31, v13, v172
	v_add_f32_e32 v29, v25, v29
	v_add_f32_e32 v30, v30, v31
	v_add_f32_e32 v29, v29, v30
	s_waitcnt lgkmcnt(1)
	v_mul_f32_e32 v30, v12, v175
	v_mul_f32_e32 v31, v18, v177
	v_fmac_f32_e32 v30, v9, v174
	v_fmac_f32_e32 v31, v10, v176
	v_add_f32_e32 v30, v30, v31
	v_add_f32_e32 v29, v29, v30
	s_waitcnt lgkmcnt(0)
; #define LAS __attribute__((address_space(3)))
; __device__ __forceinline__ void gla_cumdecay(const Ptrs& A, int l, int n, int hd, LAS float* bl, const int wv0) {
;     ...
;     for (int tt = 0; tt < 16; ++tt) {
;         float pre = bias;
;         const f32x4 g0 = *(const LAS f32x4*)(ga + tt * 16), g1 = *(const LAS f32x4*)(ga + tt * 16 + 4), g2 = *(const LAS f32x4*)(ga + tt * 16 + 8), g3 = *(const LAS f32x4*)(ga + tt * 16 + 12);
;         pre += (g0.x * w[0] + g0.y * w[1]) + (g0.z * w[2] + g0.w * w[3]); pre += (g1.x * w[4] + g1.y * w[5]) + (g1.z * w[6] + g1.w * w[7]);
;         pre += (g2.x * w[8] + g2.y * w[9]) + (g2.z * w[10] + g2.w * w[11]); pre += (g3.x * w[12] + g3.y * w[13]) + (g3.z * w[14] + g3.w * w[15]);
;         const float la = (fminf(pre, 0.f) - __logf(1.0f + __expf(-fabsf(pre)))) * (1.0f / 16.0f);
;         run += la; bl[(16 * tq + tt) * BLS + d] = run;
	ds_read_b128 v[150:153], v27 offset:128
	ds_read_b128 v[154:157], v27 offset:144
	ds_read_b128 v[158:161], v27 offset:160
	ds_read_b128 v[162:165], v27 offset:176
	v_mul_f32_e32 v30, v11, v179
	v_mul_f32_e32 v31, v17, v181
	v_fmac_f32_e32 v30, v8, v178
	v_fmac_f32_e32 v31, v15, v180
	v_add_f32_e32 v30, v30, v31
	v_add_f32_e32 v29, v29, v30
	v_mul_f32_e64 v30, |v29|, s37
	v_exp_f32_e32 v30, v30
	v_min_f32_e32 v29, 0, v29
	v_add_f32_e32 v30, 1.0, v30
	v_cmp_gt_f32_e32 vcc, s38, v30
	s_nop 1
	v_cndmask_b32_e64 v31, 0, 32, vcc
	v_ldexp_f32 v30, v30, v31
	v_log_f32_e32 v30, v30
	s_nop 0
	v_mul_f32_e32 v31, 0x3f317217, v30
	v_fma_f32 v31, v30, s39, -v31
	v_fmac_f32_e32 v31, 0x3377d1cf, v30
	v_fmac_f32_e32 v31, 0x3f317217, v30
	v_cmp_lt_f32_e64 s[2:3], |v30|, s40
	s_nop 1
	v_cndmask_b32_e64 v30, v30, v31, s[2:3]
	v_cndmask_b32_e32 v31, 0, v69, vcc
	v_sub_f32_e32 v30, v30, v31
	v_sub_f32_e32 v29, v29, v30
	v_fmac_f32_e32 v28, 0x3d800000, v29
	ds_write_b32 v19, v28 offset:528
	s_waitcnt lgkmcnt(3)
	v_mul_f32_e32 v29, v24, v151
	v_fmac_f32_e32 v29, v22, v150
	v_mul_f32_e32 v30, v23, v153
	v_fmac_f32_e32 v30, v21, v152
	v_add_f32_e32 v29, v29, v30
	s_waitcnt lgkmcnt(2)
	v_mul_f32_e32 v30, v16, v155
	v_mul_f32_e32 v31, v20, v157
	v_fmac_f32_e32 v30, v14, v154
	v_fmac_f32_e32 v31, v13, v156
	v_add_f32_e32 v29, v25, v29
	v_add_f32_e32 v30, v30, v31
	v_add_f32_e32 v29, v29, v30
	s_waitcnt lgkmcnt(1)
	v_mul_f32_e32 v30, v12, v159
	v_mul_f32_e32 v31, v18, v161
	v_fmac_f32_e32 v30, v9, v158
	v_fmac_f32_e32 v31, v10, v160
	v_add_f32_e32 v30, v30, v31
	v_add_f32_e32 v29, v29, v30
	s_waitcnt lgkmcnt(0)
	ds_read_b128 v[166:169], v27 offset:192
	ds_read_b128 v[170:173], v27 offset:208
	ds_read_b128 v[174:177], v27 offset:224
	ds_read_b128 v[178:181], v27 offset:240
	v_mul_f32_e32 v30, v11, v163
	v_mul_f32_e32 v31, v17, v165
	v_fmac_f32_e32 v30, v8, v162
	v_fmac_f32_e32 v31, v15, v164
	v_add_f32_e32 v30, v30, v31
	v_add_f32_e32 v29, v29, v30
	v_mul_f32_e64 v30, |v29|, s37
	v_exp_f32_e32 v30, v30
	v_min_f32_e32 v29, 0, v29
	v_add_f32_e32 v30, 1.0, v30
	v_cmp_gt_f32_e32 vcc, s38, v30
	s_nop 1
	v_cndmask_b32_e64 v31, 0, 32, vcc
	v_ldexp_f32 v30, v30, v31
	v_log_f32_e32 v30, v30
	s_nop 0
	v_mul_f32_e32 v31, 0x3f317217, v30
	v_fma_f32 v31, v30, s39, -v31
	v_fmac_f32_e32 v31, 0x3377d1cf, v30
	v_fmac_f32_e32 v31, 0x3f317217, v30
	v_cmp_lt_f32_e64 s[2:3], |v30|, s40
	s_nop 1
	v_cndmask_b32_e64 v30, v30, v31, s[2:3]
	v_cndmask_b32_e32 v31, 0, v69, vcc
	v_sub_f32_e32 v30, v30, v31
	v_sub_f32_e32 v29, v29, v30
	v_fmac_f32_e32 v28, 0x3d800000, v29
	ds_write_b32 v19, v28 offset:1056
	s_waitcnt lgkmcnt(3)
	v_mul_f32_e32 v29, v24, v167
	v_fmac_f32_e32 v29, v22, v166
	v_mul_f32_e32 v30, v23, v169
	v_fmac_f32_e32 v30, v21, v168
	v_add_f32_e32 v29, v29, v30
	s_waitcnt lgkmcnt(2)
	v_mul_f32_e32 v30, v16, v171
	v_mul_f32_e32 v31, v20, v173
	v_fmac_f32_e32 v30, v14, v170
	v_fmac_f32_e32 v31, v13, v172
	v_add_f32_e32 v29, v25, v29
	v_add_f32_e32 v30, v30, v31
	v_add_f32_e32 v29, v29, v30
	s_waitcnt lgkmcnt(1)
	v_mul_f32_e32 v30, v12, v175
	v_mul_f32_e32 v31, v18, v177
	v_fmac_f32_e32 v30, v9, v174
	v_fmac_f32_e32 v31, v10, v176
	v_add_f32_e32 v30, v30, v31
	v_add_f32_e32 v29, v29, v30
	s_waitcnt lgkmcnt(0)
	ds_read_b128 v[150:153], v27 offset:256
	ds_read_b128 v[154:157], v27 offset:272
	ds_read_b128 v[158:161], v27 offset:288
	ds_read_b128 v[162:165], v27 offset:304
	v_mul_f32_e32 v30, v11, v179
	v_mul_f32_e32 v31, v17, v181
	v_fmac_f32_e32 v30, v8, v178
	v_fmac_f32_e32 v31, v15, v180
	v_add_f32_e32 v30, v30, v31
	v_add_f32_e32 v29, v29, v30
	v_mul_f32_e64 v30, |v29|, s37
	v_exp_f32_e32 v30, v30
	v_min_f32_e32 v29, 0, v29
	v_add_f32_e32 v30, 1.0, v30
	v_cmp_gt_f32_e32 vcc, s38, v30
	s_nop 1
	v_cndmask_b32_e64 v31, 0, 32, vcc
	v_ldexp_f32 v30, v30, v31
	v_log_f32_e32 v30, v30
	s_nop 0
	v_mul_f32_e32 v31, 0x3f317217, v30
	v_fma_f32 v31, v30, s39, -v31
	v_fmac_f32_e32 v31, 0x3377d1cf, v30
	v_fmac_f32_e32 v31, 0x3f317217, v30
	v_cmp_lt_f32_e64 s[2:3], |v30|, s40
	s_nop 1
	v_cndmask_b32_e64 v30, v30, v31, s[2:3]
	v_cndmask_b32_e32 v31, 0, v69, vcc
	v_sub_f32_e32 v30, v30, v31
	v_sub_f32_e32 v29, v29, v30
	v_fmac_f32_e32 v28, 0x3d800000, v29
	ds_write_b32 v19, v28 offset:1584
	s_waitcnt lgkmcnt(3)
	v_mul_f32_e32 v29, v24, v151
	v_fmac_f32_e32 v29, v22, v150
	v_mul_f32_e32 v30, v23, v153
	v_fmac_f32_e32 v30, v21, v152
	v_add_f32_e32 v29, v29, v30
	s_waitcnt lgkmcnt(2)
	v_mul_f32_e32 v30, v16, v155
	v_mul_f32_e32 v31, v20, v157
	v_fmac_f32_e32 v30, v14, v154
	v_fmac_f32_e32 v31, v13, v156
	v_add_f32_e32 v29, v25, v29
	v_add_f32_e32 v30, v30, v31
	v_add_f32_e32 v29, v29, v30
	s_waitcnt lgkmcnt(1)
	v_mul_f32_e32 v30, v12, v159
	v_mul_f32_e32 v31, v18, v161
	v_fmac_f32_e32 v30, v9, v158
	v_fmac_f32_e32 v31, v10, v160
	v_add_f32_e32 v30, v30, v31
	v_add_f32_e32 v29, v29, v30
	s_waitcnt lgkmcnt(0)
	ds_read_b128 v[166:169], v27 offset:320
	ds_read_b128 v[170:173], v27 offset:336
	ds_read_b128 v[174:177], v27 offset:352
	ds_read_b128 v[178:181], v27 offset:368
	v_mul_f32_e32 v30, v11, v163
	v_mul_f32_e32 v31, v17, v165
	v_fmac_f32_e32 v30, v8, v162
	v_fmac_f32_e32 v31, v15, v164
	v_add_f32_e32 v30, v30, v31
	v_add_f32_e32 v29, v29, v30
	v_mul_f32_e64 v30, |v29|, s37
	v_exp_f32_e32 v30, v30
	v_min_f32_e32 v29, 0, v29
	v_add_f32_e32 v30, 1.0, v30
	v_cmp_gt_f32_e32 vcc, s38, v30
	s_nop 1
	v_cndmask_b32_e64 v31, 0, 32, vcc
	v_ldexp_f32 v30, v30, v31
	v_log_f32_e32 v30, v30
	s_nop 0
	v_mul_f32_e32 v31, 0x3f317217, v30
	v_fma_f32 v31, v30, s39, -v31
	v_fmac_f32_e32 v31, 0x3377d1cf, v30
	v_fmac_f32_e32 v31, 0x3f317217, v30
	v_cmp_lt_f32_e64 s[2:3], |v30|, s40
	s_nop 1
	v_cndmask_b32_e64 v30, v30, v31, s[2:3]
	v_cndmask_b32_e32 v31, 0, v69, vcc
	v_sub_f32_e32 v30, v30, v31
	v_sub_f32_e32 v29, v29, v30
	v_fmac_f32_e32 v28, 0x3d800000, v29
	ds_write_b32 v19, v28 offset:2112
	s_waitcnt lgkmcnt(3)
; #define LAS __attribute__((address_space(3)))
; __device__ __forceinline__ void gla_cumdecay(const Ptrs& A, int l, int n, int hd, LAS float* bl, const int wv0) {
;     ...
;     for (int tt = 0; tt < 16; ++tt) {
;         float pre = bias;
;         const f32x4 g0 = *(const LAS f32x4*)(ga + tt * 16), g1 = *(const LAS f32x4*)(ga + tt * 16 + 4), g2 = *(const LAS f32x4*)(ga + tt * 16 + 8), g3 = *(const LAS f32x4*)(ga + tt * 16 + 12);
;         pre += (g0.x * w[0] + g0.y * w[1]) + (g0.z * w[2] + g0.w * w[3]); pre += (g1.x * w[4] + g1.y * w[5]) + (g1.z * w[6] + g1.w * w[7]);
;         pre += (g2.x * w[8] + g2.y * w[9]) + (g2.z * w[10] + g2.w * w[11]); pre += (g3.x * w[12] + g3.y * w[13]) + (g3.z * w[14] + g3.w * w[15]);
;         const float la = (fminf(pre, 0.f) - __logf(1.0f + __expf(-fabsf(pre)))) * (1.0f / 16.0f);
;         run += la; bl[(16 * tq + tt) * BLS + d] = run;
	v_mul_f32_e32 v29, v24, v167
	v_fmac_f32_e32 v29, v22, v166
	v_mul_f32_e32 v30, v23, v169
	v_fmac_f32_e32 v30, v21, v168
	v_add_f32_e32 v29, v29, v30
	s_waitcnt lgkmcnt(2)
	v_mul_f32_e32 v30, v16, v171
	v_mul_f32_e32 v31, v20, v173
	v_fmac_f32_e32 v30, v14, v170
	v_fmac_f32_e32 v31, v13, v172
	v_add_f32_e32 v29, v25, v29
	v_add_f32_e32 v30, v30, v31
	v_add_f32_e32 v29, v29, v30
	s_waitcnt lgkmcnt(1)
	v_mul_f32_e32 v30, v12, v175
	v_mul_f32_e32 v31, v18, v177
	v_fmac_f32_e32 v30, v9, v174
	v_fmac_f32_e32 v31, v10, v176
	v_add_f32_e32 v30, v30, v31
	v_add_f32_e32 v29, v29, v30
	s_waitcnt lgkmcnt(0)
	ds_read_b128 v[150:153], v27 offset:384
	ds_read_b128 v[154:157], v27 offset:400
	ds_read_b128 v[158:161], v27 offset:416
	ds_read_b128 v[162:165], v27 offset:432
	v_mul_f32_e32 v30, v11, v179
	v_mul_f32_e32 v31, v17, v181
	v_fmac_f32_e32 v30, v8, v178
	v_fmac_f32_e32 v31, v15, v180
	v_add_f32_e32 v30, v30, v31
	v_add_f32_e32 v29, v29, v30
	v_mul_f32_e64 v30, |v29|, s37
	v_exp_f32_e32 v30, v30
	v_min_f32_e32 v29, 0, v29
	v_add_f32_e32 v30, 1.0, v30
	v_cmp_gt_f32_e32 vcc, s38, v30
	s_nop 1
	v_cndmask_b32_e64 v31, 0, 32, vcc
	v_ldexp_f32 v30, v30, v31
	v_log_f32_e32 v30, v30
	s_nop 0
	v_mul_f32_e32 v31, 0x3f317217, v30
	v_fma_f32 v31, v30, s39, -v31
	v_fmac_f32_e32 v31, 0x3377d1cf, v30
	v_fmac_f32_e32 v31, 0x3f317217, v30
	v_cmp_lt_f32_e64 s[2:3], |v30|, s40
	s_nop 1
	v_cndmask_b32_e64 v30, v30, v31, s[2:3]
	v_cndmask_b32_e32 v31, 0, v69, vcc
	v_sub_f32_e32 v30, v30, v31
	v_sub_f32_e32 v29, v29, v30
	v_fmac_f32_e32 v28, 0x3d800000, v29
	ds_write_b32 v19, v28 offset:2640
	s_waitcnt lgkmcnt(3)
	v_mul_f32_e32 v29, v24, v151
	v_fmac_f32_e32 v29, v22, v150
	v_mul_f32_e32 v30, v23, v153
	v_fmac_f32_e32 v30, v21, v152
	v_add_f32_e32 v29, v29, v30
	s_waitcnt lgkmcnt(2)
	v_mul_f32_e32 v30, v16, v155
	v_mul_f32_e32 v31, v20, v157
	v_fmac_f32_e32 v30, v14, v154
	v_fmac_f32_e32 v31, v13, v156
	v_add_f32_e32 v29, v25, v29
	v_add_f32_e32 v30, v30, v31
	v_add_f32_e32 v29, v29, v30
	s_waitcnt lgkmcnt(1)
	v_mul_f32_e32 v30, v12, v159
	v_mul_f32_e32 v31, v18, v161
	v_fmac_f32_e32 v30, v9, v158
	v_fmac_f32_e32 v31, v10, v160
	v_add_f32_e32 v30, v30, v31
	v_add_f32_e32 v29, v29, v30
	s_waitcnt lgkmcnt(0)
	ds_read_b128 v[166:169], v27 offset:448
	ds_read_b128 v[170:173], v27 offset:464
	ds_read_b128 v[174:177], v27 offset:480
	ds_read_b128 v[178:181], v27 offset:496
	v_mul_f32_e32 v30, v11, v163
	v_mul_f32_e32 v31, v17, v165
	v_fmac_f32_e32 v30, v8, v162
	v_fmac_f32_e32 v31, v15, v164
	v_add_f32_e32 v30, v30, v31
	v_add_f32_e32 v29, v29, v30
	v_mul_f32_e64 v30, |v29|, s37
	v_exp_f32_e32 v30, v30
	v_min_f32_e32 v29, 0, v29
	v_add_f32_e32 v30, 1.0, v30
	v_cmp_gt_f32_e32 vcc, s38, v30
	s_nop 1
	v_cndmask_b32_e64 v31, 0, 32, vcc
	v_ldexp_f32 v30, v30, v31
	v_log_f32_e32 v30, v30
	s_nop 0
	v_mul_f32_e32 v31, 0x3f317217, v30
	v_fma_f32 v31, v30, s39, -v31
	v_fmac_f32_e32 v31, 0x3377d1cf, v30
	v_fmac_f32_e32 v31, 0x3f317217, v30
	v_cmp_lt_f32_e64 s[2:3], |v30|, s40
	s_nop 1
	v_cndmask_b32_e64 v30, v30, v31, s[2:3]
	v_cndmask_b32_e32 v31, 0, v69, vcc
	v_sub_f32_e32 v30, v30, v31
	v_sub_f32_e32 v29, v29, v30
	v_fmac_f32_e32 v28, 0x3d800000, v29
	ds_write_b32 v19, v28 offset:3168
	s_waitcnt lgkmcnt(3)
	v_mul_f32_e32 v29, v24, v167
	v_fmac_f32_e32 v29, v22, v166
	v_mul_f32_e32 v30, v23, v169
	v_fmac_f32_e32 v30, v21, v168
	v_add_f32_e32 v29, v29, v30
	s_waitcnt lgkmcnt(2)
	v_mul_f32_e32 v30, v16, v171
	v_mul_f32_e32 v31, v20, v173
	v_fmac_f32_e32 v30, v14, v170
	v_fmac_f32_e32 v31, v13, v172
	v_add_f32_e32 v29, v25, v29
	v_add_f32_e32 v30, v30, v31
	v_add_f32_e32 v29, v29, v30
	s_waitcnt lgkmcnt(1)
	v_mul_f32_e32 v30, v12, v175
	v_mul_f32_e32 v31, v18, v177
	v_fmac_f32_e32 v30, v9, v174
	v_fmac_f32_e32 v31, v10, v176
	v_add_f32_e32 v30, v30, v31
	v_add_f32_e32 v29, v29, v30
	s_waitcnt lgkmcnt(0)
	ds_read_b128 v[150:153], v27 offset:512
	ds_read_b128 v[154:157], v27 offset:528
	ds_read_b128 v[158:161], v27 offset:544
	ds_read_b128 v[162:165], v27 offset:560
	v_mul_f32_e32 v30, v11, v179
	v_mul_f32_e32 v31, v17, v181
	v_fmac_f32_e32 v30, v8, v178
	v_fmac_f32_e32 v31, v15, v180
	v_add_f32_e32 v30, v30, v31
	v_add_f32_e32 v29, v29, v30
	v_mul_f32_e64 v30, |v29|, s37
	v_exp_f32_e32 v30, v30
	v_min_f32_e32 v29, 0, v29
	v_add_f32_e32 v30, 1.0, v30
	v_cmp_gt_f32_e32 vcc, s38, v30
	s_nop 1
	v_cndmask_b32_e64 v31, 0, 32, vcc
	v_ldexp_f32 v30, v30, v31
	v_log_f32_e32 v30, v30
	s_nop 0
	v_mul_f32_e32 v31, 0x3f317217, v30
	v_fma_f32 v31, v30, s39, -v31
	v_fmac_f32_e32 v31, 0x3377d1cf, v30
	v_fmac_f32_e32 v31, 0x3f317217, v30
	v_cmp_lt_f32_e64 s[2:3], |v30|, s40
	s_nop 1
	v_cndmask_b32_e64 v30, v30, v31, s[2:3]
	v_cndmask_b32_e32 v31, 0, v69, vcc
	v_sub_f32_e32 v30, v30, v31
	v_sub_f32_e32 v29, v29, v30
	v_fmac_f32_e32 v28, 0x3d800000, v29
	ds_write_b32 v19, v28 offset:3696
	s_waitcnt lgkmcnt(3)
	v_mul_f32_e32 v29, v24, v151
	v_fmac_f32_e32 v29, v22, v150
	v_mul_f32_e32 v30, v23, v153
	v_fmac_f32_e32 v30, v21, v152
	v_add_f32_e32 v29, v29, v30
	s_waitcnt lgkmcnt(2)
	v_mul_f32_e32 v30, v16, v155
	v_mul_f32_e32 v31, v20, v157
	v_fmac_f32_e32 v30, v14, v154
	v_fmac_f32_e32 v31, v13, v156
	v_add_f32_e32 v29, v25, v29
	v_add_f32_e32 v30, v30, v31
	v_add_f32_e32 v29, v29, v30
	s_waitcnt lgkmcnt(1)
	v_mul_f32_e32 v30, v12, v159
	v_mul_f32_e32 v31, v18, v161
	v_fmac_f32_e32 v30, v9, v158
	v_fmac_f32_e32 v31, v10, v160
	v_add_f32_e32 v30, v30, v31
	v_add_f32_e32 v29, v29, v30
	s_waitcnt lgkmcnt(0)
; #define LAS __attribute__((address_space(3)))
; __device__ __forceinline__ void gla_cumdecay(const Ptrs& A, int l, int n, int hd, LAS float* bl, const int wv0) {
;     ...
;     for (int tt = 0; tt < 16; ++tt) {
;         float pre = bias;
;         const f32x4 g0 = *(const LAS f32x4*)(ga + tt * 16), g1 = *(const LAS f32x4*)(ga + tt * 16 + 4), g2 = *(const LAS f32x4*)(ga + tt * 16 + 8), g3 = *(const LAS f32x4*)(ga + tt * 16 + 12);
;         pre += (g0.x * w[0] + g0.y * w[1]) + (g0.z * w[2] + g0.w * w[3]); pre += (g1.x * w[4] + g1.y * w[5]) + (g1.z * w[6] + g1.w * w[7]);
;         pre += (g2.x * w[8] + g2.y * w[9]) + (g2.z * w[10] + g2.w * w[11]); pre += (g3.x * w[12] + g3.y * w[13]) + (g3.z * w[14] + g3.w * w[15]);
;         const float la = (fminf(pre, 0.f) - __logf(1.0f + __expf(-fabsf(pre)))) * (1.0f / 16.0f);
;         run += la; bl[(16 * tq + tt) * BLS + d] = run;
	ds_read_b128 v[166:169], v27 offset:576
	ds_read_b128 v[170:173], v27 offset:592
	ds_read_b128 v[174:177], v27 offset:608
	ds_read_b128 v[178:181], v27 offset:624
	v_mul_f32_e32 v30, v11, v163
	v_mul_f32_e32 v31, v17, v165
	v_fmac_f32_e32 v30, v8, v162
	v_fmac_f32_e32 v31, v15, v164
	v_add_f32_e32 v30, v30, v31
	v_add_f32_e32 v29, v29, v30
	v_mul_f32_e64 v30, |v29|, s37
	v_exp_f32_e32 v30, v30
	v_min_f32_e32 v29, 0, v29
	v_add_f32_e32 v30, 1.0, v30
	v_cmp_gt_f32_e32 vcc, s38, v30
	s_nop 1
	v_cndmask_b32_e64 v31, 0, 32, vcc
	v_ldexp_f32 v30, v30, v31
	v_log_f32_e32 v30, v30
	s_nop 0
	v_mul_f32_e32 v31, 0x3f317217, v30
	v_fma_f32 v31, v30, s39, -v31
	v_fmac_f32_e32 v31, 0x3377d1cf, v30
	v_fmac_f32_e32 v31, 0x3f317217, v30
	v_cmp_lt_f32_e64 s[2:3], |v30|, s40
	s_nop 1
	v_cndmask_b32_e64 v30, v30, v31, s[2:3]
	v_cndmask_b32_e32 v31, 0, v69, vcc
	v_sub_f32_e32 v30, v30, v31
	v_sub_f32_e32 v29, v29, v30
	v_fmac_f32_e32 v28, 0x3d800000, v29
	ds_write_b32 v19, v28 offset:4224
	s_waitcnt lgkmcnt(3)
	v_mul_f32_e32 v29, v24, v167
	v_fmac_f32_e32 v29, v22, v166
	v_mul_f32_e32 v30, v23, v169
	v_fmac_f32_e32 v30, v21, v168
	v_add_f32_e32 v29, v29, v30
	s_waitcnt lgkmcnt(2)
	v_mul_f32_e32 v30, v16, v171
	v_mul_f32_e32 v31, v20, v173
	v_fmac_f32_e32 v30, v14, v170
	v_fmac_f32_e32 v31, v13, v172
	v_add_f32_e32 v29, v25, v29
	v_add_f32_e32 v30, v30, v31
	v_add_f32_e32 v29, v29, v30
	s_waitcnt lgkmcnt(1)
	v_mul_f32_e32 v30, v12, v175
	v_mul_f32_e32 v31, v18, v177
	v_fmac_f32_e32 v30, v9, v174
	v_fmac_f32_e32 v31, v10, v176
	v_add_f32_e32 v30, v30, v31
	v_add_f32_e32 v29, v29, v30
	s_waitcnt lgkmcnt(0)
	ds_read_b128 v[150:153], v27 offset:640
	ds_read_b128 v[154:157], v27 offset:656
	ds_read_b128 v[158:161], v27 offset:672
	ds_read_b128 v[162:165], v27 offset:688
	v_mul_f32_e32 v30, v11, v179
	v_mul_f32_e32 v31, v17, v181
	v_fmac_f32_e32 v30, v8, v178
	v_fmac_f32_e32 v31, v15, v180
	v_add_f32_e32 v30, v30, v31
	v_add_f32_e32 v29, v29, v30
	v_mul_f32_e64 v30, |v29|, s37
	v_exp_f32_e32 v30, v30
	v_min_f32_e32 v29, 0, v29
	v_add_f32_e32 v30, 1.0, v30
	v_cmp_gt_f32_e32 vcc, s38, v30
	s_nop 1
	v_cndmask_b32_e64 v31, 0, 32, vcc
	v_ldexp_f32 v30, v30, v31
	v_log_f32_e32 v30, v30
	s_nop 0
	v_mul_f32_e32 v31, 0x3f317217, v30
	v_fma_f32 v31, v30, s39, -v31
	v_fmac_f32_e32 v31, 0x3377d1cf, v30
	v_fmac_f32_e32 v31, 0x3f317217, v30
	v_cmp_lt_f32_e64 s[2:3], |v30|, s40
	s_nop 1
	v_cndmask_b32_e64 v30, v30, v31, s[2:3]
	v_cndmask_b32_e32 v31, 0, v69, vcc
	v_sub_f32_e32 v30, v30, v31
	v_sub_f32_e32 v29, v29, v30
	v_fmac_f32_e32 v28, 0x3d800000, v29
	ds_write_b32 v19, v28 offset:4752
	s_waitcnt lgkmcnt(3)
	v_mul_f32_e32 v29, v24, v151
	v_fmac_f32_e32 v29, v22, v150
	v_mul_f32_e32 v30, v23, v153
	v_fmac_f32_e32 v30, v21, v152
	v_add_f32_e32 v29, v29, v30
	s_waitcnt lgkmcnt(2)
	v_mul_f32_e32 v30, v16, v155
	v_mul_f32_e32 v31, v20, v157
	v_fmac_f32_e32 v30, v14, v154
	v_fmac_f32_e32 v31, v13, v156
	v_add_f32_e32 v29, v25, v29
	v_add_f32_e32 v30, v30, v31
	v_add_f32_e32 v29, v29, v30
	s_waitcnt lgkmcnt(1)
	v_mul_f32_e32 v30, v12, v159
	v_mul_f32_e32 v31, v18, v161
	v_fmac_f32_e32 v30, v9, v158
	v_fmac_f32_e32 v31, v10, v160
	v_add_f32_e32 v30, v30, v31
	v_add_f32_e32 v29, v29, v30
	s_waitcnt lgkmcnt(0)
	ds_read_b128 v[166:169], v27 offset:704
	ds_read_b128 v[170:173], v27 offset:720
	ds_read_b128 v[174:177], v27 offset:736
	ds_read_b128 v[178:181], v27 offset:752
	v_mul_f32_e32 v30, v11, v163
	v_mul_f32_e32 v31, v17, v165
	v_fmac_f32_e32 v30, v8, v162
	v_fmac_f32_e32 v31, v15, v164
	v_add_f32_e32 v30, v30, v31
	v_add_f32_e32 v29, v29, v30
	v_mul_f32_e64 v30, |v29|, s37
	v_exp_f32_e32 v30, v30
	v_min_f32_e32 v29, 0, v29
	v_add_f32_e32 v30, 1.0, v30
	v_cmp_gt_f32_e32 vcc, s38, v30
	s_nop 1
	v_cndmask_b32_e64 v31, 0, 32, vcc
	v_ldexp_f32 v30, v30, v31
	v_log_f32_e32 v30, v30
	s_nop 0
	v_mul_f32_e32 v31, 0x3f317217, v30
	v_fma_f32 v31, v30, s39, -v31
	v_fmac_f32_e32 v31, 0x3377d1cf, v30
	v_fmac_f32_e32 v31, 0x3f317217, v30
	v_cmp_lt_f32_e64 s[2:3], |v30|, s40
	s_nop 1
	v_cndmask_b32_e64 v30, v30, v31, s[2:3]
	v_cndmask_b32_e32 v31, 0, v69, vcc
	v_sub_f32_e32 v30, v30, v31
	v_sub_f32_e32 v29, v29, v30
	v_fmac_f32_e32 v28, 0x3d800000, v29
	ds_write_b32 v19, v28 offset:5280
	s_waitcnt lgkmcnt(3)
	v_mul_f32_e32 v29, v24, v167
	v_fmac_f32_e32 v29, v22, v166
	v_mul_f32_e32 v30, v23, v169
	v_fmac_f32_e32 v30, v21, v168
	v_add_f32_e32 v29, v29, v30
	s_waitcnt lgkmcnt(2)
	v_mul_f32_e32 v30, v16, v171
	v_mul_f32_e32 v31, v20, v173
	v_fmac_f32_e32 v30, v14, v170
	v_fmac_f32_e32 v31, v13, v172
	v_add_f32_e32 v29, v25, v29
	v_add_f32_e32 v30, v30, v31
	v_add_f32_e32 v29, v29, v30
	s_waitcnt lgkmcnt(1)
	v_mul_f32_e32 v30, v12, v175
	v_mul_f32_e32 v31, v18, v177
	v_fmac_f32_e32 v30, v9, v174
	v_fmac_f32_e32 v31, v10, v176
	v_add_f32_e32 v30, v30, v31
	v_add_f32_e32 v29, v29, v30
	s_waitcnt lgkmcnt(0)
	ds_read_b128 v[150:153], v27 offset:768
	ds_read_b128 v[154:157], v27 offset:784
	ds_read_b128 v[158:161], v27 offset:800
	ds_read_b128 v[162:165], v27 offset:816
	v_mul_f32_e32 v30, v11, v179
	v_mul_f32_e32 v31, v17, v181
	v_fmac_f32_e32 v30, v8, v178
	v_fmac_f32_e32 v31, v15, v180
	v_add_f32_e32 v30, v30, v31
	v_add_f32_e32 v29, v29, v30
	v_mul_f32_e64 v30, |v29|, s37
	v_exp_f32_e32 v30, v30
	v_min_f32_e32 v29, 0, v29
	v_add_f32_e32 v30, 1.0, v30
	v_cmp_gt_f32_e32 vcc, s38, v30
	s_nop 1
	v_cndmask_b32_e64 v31, 0, 32, vcc
	v_ldexp_f32 v30, v30, v31
	v_log_f32_e32 v30, v30
	s_nop 0
	v_mul_f32_e32 v31, 0x3f317217, v30
	v_fma_f32 v31, v30, s39, -v31
	v_fmac_f32_e32 v31, 0x3377d1cf, v30
	v_fmac_f32_e32 v31, 0x3f317217, v30
	v_cmp_lt_f32_e64 s[2:3], |v30|, s40
	s_nop 1
	v_cndmask_b32_e64 v30, v30, v31, s[2:3]
	v_cndmask_b32_e32 v31, 0, v69, vcc
	v_sub_f32_e32 v30, v30, v31
	v_sub_f32_e32 v29, v29, v30
	v_fmac_f32_e32 v28, 0x3d800000, v29
	ds_write_b32 v19, v28 offset:5808
	s_waitcnt lgkmcnt(3)
; #define LAS __attribute__((address_space(3)))
; __device__ __forceinline__ void gla_cumdecay(const Ptrs& A, int l, int n, int hd, LAS float* bl, const int wv0) {
;     ...
;     for (int tt = 0; tt < 16; ++tt) {
;         float pre = bias;
;         const f32x4 g0 = *(const LAS f32x4*)(ga + tt * 16), g1 = *(const LAS f32x4*)(ga + tt * 16 + 4), g2 = *(const LAS f32x4*)(ga + tt * 16 + 8), g3 = *(const LAS f32x4*)(ga + tt * 16 + 12);
;         pre += (g0.x * w[0] + g0.y * w[1]) + (g0.z * w[2] + g0.w * w[3]); pre += (g1.x * w[4] + g1.y * w[5]) + (g1.z * w[6] + g1.w * w[7]);
;         pre += (g2.x * w[8] + g2.y * w[9]) + (g2.z * w[10] + g2.w * w[11]); pre += (g3.x * w[12] + g3.y * w[13]) + (g3.z * w[14] + g3.w * w[15]);
;         const float la = (fminf(pre, 0.f) - __logf(1.0f + __expf(-fabsf(pre)))) * (1.0f / 16.0f);
;         run += la; bl[(16 * tq + tt) * BLS + d] = run;
;     }
;     __syncthreads();
;     float add = 0.f;
; #pragma unroll
;     for (int q = 0; q < 3; ++q) if (q < tq) add += bl[(16 * q + 15) * BLS + d];
	v_mul_f32_e32 v29, v24, v151
	v_fmac_f32_e32 v29, v22, v150
	v_mul_f32_e32 v30, v23, v153
	v_fmac_f32_e32 v30, v21, v152
	v_add_f32_e32 v29, v29, v30
	s_waitcnt lgkmcnt(2)
	v_mul_f32_e32 v30, v16, v155
	v_mul_f32_e32 v31, v20, v157
	v_fmac_f32_e32 v30, v14, v154
	v_fmac_f32_e32 v31, v13, v156
	v_add_f32_e32 v29, v25, v29
	v_add_f32_e32 v30, v30, v31
	v_add_f32_e32 v29, v29, v30
	s_waitcnt lgkmcnt(1)
	v_mul_f32_e32 v30, v12, v159
	v_mul_f32_e32 v31, v18, v161
	v_fmac_f32_e32 v30, v9, v158
	v_fmac_f32_e32 v31, v10, v160
	v_add_f32_e32 v30, v30, v31
	v_add_f32_e32 v29, v29, v30
	s_waitcnt lgkmcnt(0)
	ds_read_b128 v[166:169], v27 offset:832
	ds_read_b128 v[170:173], v27 offset:848
	ds_read_b128 v[174:177], v27 offset:864
	ds_read_b128 v[178:181], v27 offset:880
	v_mul_f32_e32 v30, v11, v163
	v_mul_f32_e32 v31, v17, v165
	v_fmac_f32_e32 v30, v8, v162
	v_fmac_f32_e32 v31, v15, v164
	v_add_f32_e32 v30, v30, v31
	v_add_f32_e32 v29, v29, v30
	v_mul_f32_e64 v30, |v29|, s37
	v_exp_f32_e32 v30, v30
	v_min_f32_e32 v29, 0, v29
	v_add_f32_e32 v30, 1.0, v30
	v_cmp_gt_f32_e32 vcc, s38, v30
	s_nop 1
	v_cndmask_b32_e64 v31, 0, 32, vcc
	v_ldexp_f32 v30, v30, v31
	v_log_f32_e32 v30, v30
	s_nop 0
	v_mul_f32_e32 v31, 0x3f317217, v30
	v_fma_f32 v31, v30, s39, -v31
	v_fmac_f32_e32 v31, 0x3377d1cf, v30
	v_fmac_f32_e32 v31, 0x3f317217, v30
	v_cmp_lt_f32_e64 s[2:3], |v30|, s40
	s_nop 1
	v_cndmask_b32_e64 v30, v30, v31, s[2:3]
	v_cndmask_b32_e32 v31, 0, v69, vcc
	v_sub_f32_e32 v30, v30, v31
	v_sub_f32_e32 v29, v29, v30
	v_fmac_f32_e32 v28, 0x3d800000, v29
	ds_write_b32 v19, v28 offset:6336
	s_waitcnt lgkmcnt(3)
	v_mul_f32_e32 v29, v24, v167
	v_fmac_f32_e32 v29, v22, v166
	v_mul_f32_e32 v30, v23, v169
	v_fmac_f32_e32 v30, v21, v168
	v_add_f32_e32 v29, v29, v30
	s_waitcnt lgkmcnt(2)
	v_mul_f32_e32 v30, v16, v171
	v_mul_f32_e32 v31, v20, v173
	v_fmac_f32_e32 v30, v14, v170
	v_fmac_f32_e32 v31, v13, v172
	v_add_f32_e32 v29, v25, v29
	v_add_f32_e32 v30, v30, v31
	v_add_f32_e32 v29, v29, v30
	s_waitcnt lgkmcnt(1)
	v_mul_f32_e32 v30, v12, v175
	v_mul_f32_e32 v31, v18, v177
	v_fmac_f32_e32 v30, v9, v174
	v_fmac_f32_e32 v31, v10, v176
	v_add_f32_e32 v30, v30, v31
	v_add_f32_e32 v29, v29, v30
	s_waitcnt lgkmcnt(0)
	ds_read_b128 v[150:153], v27 offset:896
	ds_read_b128 v[154:157], v27 offset:912
	ds_read_b128 v[158:161], v27 offset:928
	ds_read_b128 v[162:165], v27 offset:944
	v_mul_f32_e32 v30, v11, v179
	v_mul_f32_e32 v31, v17, v181
	v_fmac_f32_e32 v30, v8, v178
	v_fmac_f32_e32 v31, v15, v180
	v_add_f32_e32 v30, v30, v31
	v_add_f32_e32 v29, v29, v30
	v_mul_f32_e64 v30, |v29|, s37
	v_exp_f32_e32 v30, v30
	v_min_f32_e32 v29, 0, v29
	v_add_f32_e32 v30, 1.0, v30
	v_cmp_gt_f32_e32 vcc, s38, v30
	s_nop 1
	v_cndmask_b32_e64 v31, 0, 32, vcc
	v_ldexp_f32 v30, v30, v31
	v_log_f32_e32 v30, v30
	s_nop 0
	v_mul_f32_e32 v31, 0x3f317217, v30
	v_fma_f32 v31, v30, s39, -v31
	v_fmac_f32_e32 v31, 0x3377d1cf, v30
	v_fmac_f32_e32 v31, 0x3f317217, v30
	v_cmp_lt_f32_e64 s[2:3], |v30|, s40
	s_nop 1
	v_cndmask_b32_e64 v30, v30, v31, s[2:3]
	v_cndmask_b32_e32 v31, 0, v69, vcc
	v_sub_f32_e32 v30, v30, v31
	v_sub_f32_e32 v29, v29, v30
	v_fmac_f32_e32 v28, 0x3d800000, v29
	ds_write_b32 v19, v28 offset:6864
	s_waitcnt lgkmcnt(3)
	v_mul_f32_e32 v29, v24, v151
	v_fmac_f32_e32 v29, v22, v150
	v_mul_f32_e32 v30, v23, v153
	v_fmac_f32_e32 v30, v21, v152
	v_add_f32_e32 v29, v29, v30
	s_waitcnt lgkmcnt(2)
	v_mul_f32_e32 v30, v16, v155
	v_mul_f32_e32 v31, v20, v157
	v_fmac_f32_e32 v30, v14, v154
	v_fmac_f32_e32 v31, v13, v156
	v_add_f32_e32 v29, v25, v29
	v_add_f32_e32 v30, v30, v31
	v_add_f32_e32 v29, v29, v30
	s_waitcnt lgkmcnt(1)
	v_mul_f32_e32 v30, v12, v159
	v_mul_f32_e32 v31, v18, v161
	v_fmac_f32_e32 v30, v9, v158
	v_fmac_f32_e32 v31, v10, v160
	v_add_f32_e32 v30, v30, v31
	v_add_f32_e32 v29, v29, v30
	s_waitcnt lgkmcnt(0)
	ds_read_b128 v[166:169], v27 offset:960
	ds_read_b128 v[170:173], v27 offset:976
	ds_read_b128 v[174:177], v27 offset:992
	ds_read_b128 v[178:181], v27 offset:1008
	v_mul_f32_e32 v30, v11, v163
	v_mul_f32_e32 v31, v17, v165
	v_fmac_f32_e32 v30, v8, v162
	v_fmac_f32_e32 v31, v15, v164
	v_add_f32_e32 v30, v30, v31
	v_add_f32_e32 v29, v29, v30
	v_mul_f32_e64 v30, |v29|, s37
	v_exp_f32_e32 v30, v30
	v_min_f32_e32 v29, 0, v29
	v_add_f32_e32 v30, 1.0, v30
	v_cmp_gt_f32_e32 vcc, s38, v30
	s_nop 1
	v_cndmask_b32_e64 v31, 0, 32, vcc
	v_ldexp_f32 v30, v30, v31
	v_log_f32_e32 v30, v30
	s_nop 0
	v_mul_f32_e32 v31, 0x3f317217, v30
	v_fma_f32 v31, v30, s39, -v31
	v_fmac_f32_e32 v31, 0x3377d1cf, v30
	v_fmac_f32_e32 v31, 0x3f317217, v30
	v_cmp_lt_f32_e64 s[2:3], |v30|, s40
	s_nop 1
	v_cndmask_b32_e64 v30, v30, v31, s[2:3]
	v_cndmask_b32_e32 v31, 0, v69, vcc
	v_sub_f32_e32 v30, v30, v31
	v_sub_f32_e32 v29, v29, v30
	v_fmac_f32_e32 v28, 0x3d800000, v29
	ds_write_b32 v19, v28 offset:7392
	s_waitcnt lgkmcnt(3)
	v_mul_f32_e32 v24, v24, v167
	v_fmac_f32_e32 v24, v22, v166
	v_mul_f32_e32 v22, v23, v169
	s_waitcnt lgkmcnt(2)
	v_mul_f32_e32 v16, v16, v171
	s_waitcnt lgkmcnt(1)
	v_mul_f32_e32 v12, v12, v175
	v_fmac_f32_e32 v22, v21, v168
	v_fmac_f32_e32 v16, v14, v170
	v_mul_f32_e32 v14, v20, v173
	v_fmac_f32_e32 v12, v9, v174
	v_mul_f32_e32 v9, v18, v177
	v_add_f32_e32 v21, v24, v22
	v_fmac_f32_e32 v14, v13, v172
	v_fmac_f32_e32 v9, v10, v176
	s_waitcnt lgkmcnt(0)
	v_mul_f32_e32 v10, v11, v179
	v_add_f32_e32 v21, v25, v21
	v_add_f32_e32 v13, v16, v14
	v_fmac_f32_e32 v10, v8, v178
	v_mul_f32_e32 v8, v17, v181
	v_add_f32_e32 v13, v21, v13
	v_add_f32_e32 v9, v12, v9
	v_fmac_f32_e32 v8, v15, v180
	v_add_f32_e32 v9, v13, v9
	v_add_f32_e32 v8, v10, v8
	v_add_f32_e32 v8, v9, v8
	v_mul_f32_e64 v9, |v8|, s37
	v_exp_f32_e32 v9, v9
	v_min_f32_e32 v8, 0, v8
	v_add_f32_e32 v9, 1.0, v9
	v_cmp_gt_f32_e32 vcc, s38, v9
	s_nop 1
	v_cndmask_b32_e64 v10, 0, 32, vcc
	v_ldexp_f32 v9, v9, v10
	v_log_f32_e32 v9, v9
	s_nop 0
	v_mul_f32_e32 v10, 0x3f317217, v9
	v_fma_f32 v10, v9, s39, -v10
	v_fmac_f32_e32 v10, 0x3377d1cf, v9
	v_fmac_f32_e32 v10, 0x3f317217, v9
	v_cmp_lt_f32_e64 s[2:3], |v9|, s40
	s_nop 1
	v_cndmask_b32_e64 v9, v9, v10, s[2:3]
	v_cndmask_b32_e32 v10, 0, v69, vcc
	v_sub_f32_e32 v9, v9, v10
	v_sub_f32_e32 v8, v8, v9
	s_cselect_b64 s[2:3], -1, 0
	v_fmac_f32_e32 v28, 0x3d800000, v8
	s_and_b64 vcc, exec, s[2:3]
	v_mov_b32_e32 v8, 0
	ds_write_b32 v19, v28 offset:7920
	s_waitcnt lgkmcnt(0)
	s_barrier
	s_cbranch_vccz .LBB0_213
	ds_read_b32 v8, v26 offset:7920
	s_waitcnt lgkmcnt(0)
	v_add_f32_e32 v8, 0, v8

; #define LAS __attribute__((address_space(3)))
; __device__ __forceinline__ unsigned f2bf(float f) { unsigned u = __builtin_bit_cast(unsigned, f); return (u + 0x7fffu + ((u >> 16) & 1u)) >> 16; }
;     __device__ __forceinline__ unsigned char* ws() const { return (unsigned char*)(__attribute__((address_space(1))) unsigned char*)get(21); }
; __device__ __forceinline__ void unpack8(const u32x4 w, float* x) { x[0] = bflo(w.x); x[1] = bfhi(w.x); x[2] = bflo(w.y); x[3] = bfhi(w.y); x[4] = bflo(w.z); x[5] = bfhi(w.z); x[6] = bflo(w.w); x[7] = bfhi(w.w); }
; __device__ __forceinline__ void gla_load_vt(const bf16* GVc, LAS bf16* VTl, int wave, int lane) {
;     u32x4 vv[4];
; #pragma unroll
;     for (int i = 0; i < 4; ++i) vv[i] = *(const u32x4*)(GVc + (size_t)lane * 1024 + (wave + 8 * i) * 8);
; #pragma unroll
;     for (int i = 0; i < 4; ++i) { const int v0 = (wave + 8 * i) * 8; LAS bf16* p = VTl + v0 * 72 + lane;
;         p[0] = (bf16)(vv[i].x & 0xffff); p[72] = (bf16)(vv[i].x >> 16); p[144] = (bf16)(vv[i].y & 0xffff); p[216] = (bf16)(vv[i].y >> 16);
;         p[288] = (bf16)(vv[i].z & 0xffff); p[360] = (bf16)(vv[i].z >> 16); p[432] = (bf16)(vv[i].w & 0xffff); p[504] = (bf16)(vv[i].w >> 16); }
; }
; __device__ __forceinline__ void gla_state(const Ptrs& A, int l, LAS unsigned char* lds, int c, int G, int wave, int lane_, const int wv0) {
;     ...
;         gla_load_vt(GV + (size_t)t0 * 1024 + hd * 256, VTl, wave, lane);
; #pragma unroll
;         for (int i = 0; i < 2; ++i) { const int d0 = (wave + 8 * i) * 8; float x[8]; unpack8(kk[i], x);
;             const f32x4 b0 = *(const LAS f32x4*)(bl + lane * BLS + d0), b1 = *(const LAS f32x4*)(bl + lane * BLS + d0 + 4);
;             const f32x4 e0 = *(const LAS f32x4*)(bl + 63 * BLS + d0), e1 = *(const LAS f32x4*)(bl + 63 * BLS + d0 + 4);
;             LAS bf16* p = KdT + d0 * 72 + lane;
;             p[0] = (bf16)f2bf(x[0] * __expf(e0.x - b0.x)); p[72] = (bf16)f2bf(x[1] * __expf(e0.y - b0.y)); p[144] = (bf16)f2bf(x[2] * __expf(e0.z - b0.z)); p[216] = (bf16)f2bf(x[3] * __expf(e0.w - b0.w));
;             p[288] = (bf16)f2bf(x[4] * __expf(e1.x - b1.x)); p[360] = (bf16)f2bf(x[5] * __expf(e1.y - b1.y)); p[432] = (bf16)f2bf(x[6] * __expf(e1.z - b1.z)); p[504] = (bf16)f2bf(x[7] * __expf(e1.w - b1.w)); }
;         if (tid < 128) ((float*)(ws + WS_DEC))[(size_t)it * 128 + tid] = __expf(bl[63 * BLS + tid]);
.LBB0_219:
	s_ashr_i32 s21, s20, 31
	s_lshl_b64 s[2:3], s[20:21], 11
	s_add_u32 s2, s22, s2
	s_addc_u32 s3, s23, s3
	s_add_u32 s2, s2, s8
	s_addc_u32 s3, s3, 0
	v_mov_b32_e32 v57, v49
	v_lshl_add_u64 v[8:9], s[2:3], 0, v[56:57]
	v_lshl_add_u64 v[24:25], s[14:15], 1, v[8:9]
	s_waitcnt lgkmcnt(0)
	s_barrier
	global_load_dwordx4 v[8:11], v[24:25], off
	global_load_dwordx4 v[12:15], v[24:25], off offset:128
	global_load_dwordx4 v[16:19], v[24:25], off offset:256
	global_load_dwordx4 v[20:23], v[24:25], off offset:384
	s_waitcnt vmcnt(4)
	v_add_u32_e32 v24, s24, v65
	v_add_u32_e32 v25, s25, v65
	v_add_u32_e32 v26, s26, v65
	v_lshlrev_b32_e32 v27, 16, v4
	v_and_b32_e32 v28, 0xffff0000, v4
	v_lshlrev_b32_e32 v29, 16, v5
	v_and_b32_e32 v30, 0xffff0000, v5
	v_lshlrev_b32_e32 v31, 16, v6
	v_and_b32_e32 v32, 0xffff0000, v6
	v_lshlrev_b32_e32 v33, 16, v7
	v_mov_b32_e32 v34, s27
	s_waitcnt vmcnt(3)
	ds_write_b16 v24, v8 offset:52224
	ds_write_b16_d16_hi v24, v8 offset:52368
	ds_write_b16 v24, v9 offset:52512
	ds_write_b16_d16_hi v24, v9 offset:52656
	ds_write_b16 v24, v10 offset:52800
	ds_write_b16_d16_hi v24, v10 offset:52944
	ds_write_b16 v24, v11 offset:53088
	ds_write_b16_d16_hi v24, v11 offset:53232
	s_waitcnt vmcnt(2)
	ds_write_b16 v25, v12 offset:52224
	ds_write_b16_d16_hi v25, v12 offset:52368
	ds_write_b16 v25, v13 offset:52512
	ds_write_b16_d16_hi v25, v13 offset:52656
	ds_write_b16 v25, v14 offset:52800
	ds_write_b16_d16_hi v25, v14 offset:52944
	ds_write_b16 v25, v15 offset:53088
	ds_write_b16_d16_hi v25, v15 offset:53232
	s_waitcnt vmcnt(1)
	ds_write_b16 v25, v16 offset:61440
	ds_write_b16_d16_hi v25, v16 offset:61584
	ds_write_b16 v25, v17 offset:61728
	ds_write_b16_d16_hi v25, v17 offset:61872
	ds_write_b16 v25, v18 offset:62016
	ds_write_b16_d16_hi v25, v18 offset:62160
	ds_write_b16 v25, v19 offset:62304
	ds_write_b16_d16_hi v25, v19 offset:62448
	s_waitcnt vmcnt(0)
	ds_write_b16 v26, v20 offset:61440
	ds_write_b16_d16_hi v26, v20 offset:61584
	ds_write_b16 v26, v21 offset:61728
	ds_write_b16_d16_hi v26, v21 offset:61872
	ds_write_b16 v26, v22 offset:62016
	ds_write_b16_d16_hi v26, v22 offset:62160
	ds_write_b16 v26, v23 offset:62304
	ds_write_b16_d16_hi v26, v23 offset:62448
	ds_read_b128 v[8:11], v68
	ds_read_b128 v[12:15], v34 offset:33264
	v_and_b32_e32 v20, 0xffff0000, v7
	ds_read_b128 v[4:7], v68 offset:16
	ds_read_b128 v[16:19], v34 offset:33280
	v_add_u32_e32 v21, s24, v66
	v_lshlrev_b32_e32 v22, 16, v2
	s_waitcnt lgkmcnt(2)
	v_sub_f32_e32 v8, v12, v8
	v_sub_f32_e32 v9, v13, v9
	s_waitcnt lgkmcnt(0)
	v_sub_f32_e32 v4, v16, v4
	v_sub_f32_e32 v10, v14, v10
	v_sub_f32_e32 v11, v15, v11
	v_mul_f32_e32 v8, 0x3fb8aa3b, v8
	v_mul_f32_e32 v4, 0x3fb8aa3b, v4
	v_mul_f32_e32 v9, 0x3fb8aa3b, v9
	v_mul_f32_e32 v10, 0x3fb8aa3b, v10
	v_mul_f32_e32 v11, 0x3fb8aa3b, v11
	v_exp_f32_e32 v8, v8
	v_exp_f32_e32 v4, v4
	v_sub_f32_e32 v5, v17, v5
	v_exp_f32_e32 v9, v9
	v_exp_f32_e32 v10, v10
	v_exp_f32_e32 v11, v11
	v_mul_f32_e32 v5, 0x3fb8aa3b, v5
	v_exp_f32_e32 v5, v5
	v_mul_f32_e32 v8, v8, v27
	v_mul_f32_e32 v4, v4, v31
	v_mul_f32_e32 v9, v9, v28
	v_mul_f32_e32 v10, v10, v29
	v_mul_f32_e32 v11, v11, v30
	v_bfe_u32 v12, v8, 16, 1
	v_bfe_u32 v16, v4, 16, 1
	v_bfe_u32 v13, v9, 16, 1
	v_bfe_u32 v14, v10, 16, 1
	v_bfe_u32 v15, v11, 16, 1
	v_add3_u32 v8, v8, v12, s44
	v_add3_u32 v4, v4, v16, s44
	v_mul_f32_e32 v5, v5, v32
	v_add3_u32 v9, v9, v13, s44
	v_add3_u32 v10, v10, v14, s44
	v_add3_u32 v11, v11, v15, s44
	ds_write_b16_d16_hi v21, v8 offset:33792
	ds_write_b16_d16_hi v21, v9 offset:33936
	ds_write_b16_d16_hi v21, v10 offset:34080
	ds_write_b16_d16_hi v21, v11 offset:34224
	ds_write_b16_d16_hi v21, v4 offset:34368
	v_sub_f32_e32 v4, v18, v6
	v_mul_f32_e32 v4, 0x3fb8aa3b, v4
	v_bfe_u32 v6, v5, 16, 1
	v_exp_f32_e32 v4, v4
	v_add3_u32 v5, v5, v6, s44
	ds_write_b16_d16_hi v21, v5 offset:34512
	v_sub_f32_e32 v5, v19, v7
	v_mul_f32_e32 v5, 0x3fb8aa3b, v5
	v_exp_f32_e32 v5, v5
	v_mul_f32_e32 v4, v4, v33
	v_bfe_u32 v6, v4, 16, 1
	v_add3_u32 v4, v4, v6, s44
	ds_write_b16_d16_hi v21, v4 offset:34656
	v_mul_f32_e32 v4, v5, v20
	v_bfe_u32 v5, v4, 16, 1
	v_add3_u32 v4, v4, v5, s44
	ds_write_b16_d16_hi v21, v4 offset:34800
	ds_read_b128 v[4:7], v68 offset:256
	ds_read_b128 v[8:11], v34 offset:33520
	v_lshlrev_b32_e32 v20, 16, v0
	ds_read_b128 v[12:15], v68 offset:272
	ds_read_b128 v[16:19], v34 offset:33536
	v_and_b32_e32 v0, 0xffff0000, v0
	v_lshlrev_b32_e32 v21, 16, v1
	s_waitcnt lgkmcnt(2)
	v_sub_f32_e32 v4, v8, v4
	v_mul_f32_e32 v4, 0x3fb8aa3b, v4
	v_exp_f32_e32 v4, v4
	v_sub_f32_e32 v5, v9, v5
	v_mul_f32_e32 v5, 0x3fb8aa3b, v5
	v_exp_f32_e32 v5, v5
	v_mul_f32_e32 v4, v4, v20
	v_bfe_u32 v20, v4, 16, 1
	v_add3_u32 v4, v4, v20, s44
	v_add_u32_e32 v9, s25, v66
	ds_write_b16_d16_hi v9, v4 offset:33792
	v_sub_f32_e32 v4, v10, v6
	v_mul_f32_e32 v4, 0x3fb8aa3b, v4
	v_exp_f32_e32 v4, v4
	v_mul_f32_e32 v0, v5, v0
	v_bfe_u32 v5, v0, 16, 1
	v_add3_u32 v0, v0, v5, s44
	ds_write_b16_d16_hi v9, v0 offset:33936
	v_mul_f32_e32 v0, v4, v21
	v_sub_f32_e32 v4, v11, v7
	v_mul_f32_e32 v4, 0x3fb8aa3b, v4
	v_exp_f32_e32 v4, v4
	v_bfe_u32 v5, v0, 16, 1
	v_and_b32_e32 v1, 0xffff0000, v1
	v_add3_u32 v0, v0, v5, s44
	ds_write_b16_d16_hi v9, v0 offset:34080
	v_mul_f32_e32 v0, v4, v1
	s_waitcnt lgkmcnt(3)
	v_sub_f32_e32 v1, v16, v12
	v_mul_f32_e32 v1, 0x3fb8aa3b, v1
	v_exp_f32_e32 v1, v1
	v_bfe_u32 v4, v0, 16, 1
	v_add3_u32 v0, v0, v4, s44
	ds_write_b16_d16_hi v9, v0 offset:34224
	v_mul_f32_e32 v0, v1, v22
	v_sub_f32_e32 v1, v17, v13
	v_mul_f32_e32 v1, 0x3fb8aa3b, v1
	v_exp_f32_e32 v1, v1
	v_bfe_u32 v4, v0, 16, 1
	v_and_b32_e32 v2, 0xffff0000, v2
	v_add3_u32 v0, v0, v4, s44
	ds_write_b16_d16_hi v9, v0 offset:34368
	v_mul_f32_e32 v0, v1, v2
	v_sub_f32_e32 v1, v18, v14
	v_mul_f32_e32 v1, 0x3fb8aa3b, v1
	v_exp_f32_e32 v1, v1
	v_bfe_u32 v2, v0, 16, 1
	v_lshlrev_b32_e32 v8, 16, v3
	v_add3_u32 v0, v0, v2, s44
	ds_write_b16_d16_hi v9, v0 offset:34512
	v_mul_f32_e32 v0, v1, v8
	v_sub_f32_e32 v1, v19, v15
	v_mul_f32_e32 v1, 0x3fb8aa3b, v1
	v_exp_f32_e32 v1, v1
	v_bfe_u32 v2, v0, 16, 1
	v_and_b32_e32 v3, 0xffff0000, v3
	v_add3_u32 v0, v0, v2, s44
	ds_write_b16_d16_hi v9, v0 offset:34656
	v_mul_f32_e32 v0, v1, v3
	v_bfe_u32 v1, v0, 16, 1
	v_add3_u32 v0, v0, v1, s44
	ds_write_b16_d16_hi v9, v0 offset:34800
	s_and_saveexec_b64 s[2:3], s[0:1]
	s_cbranch_execz .LBB0_210
	ds_read_b32 v0, v67 offset:33264
	s_waitcnt lgkmcnt(0)
	v_mul_f32_e32 v0, 0x3fb8aa3b, v0
	v_exp_f32_e32 v2, v0
	v_lshl_add_u64 v[0:1], s[10:11], 0, v[50:51]
	global_store_dword v[0:1], v2, off
	s_branch .LBB0_210

; #define LAS __attribute__((address_space(3)))
; #define TID() (wv0 * 64 + (int)__builtin_amdgcn_mbcnt_hi(~0u, __builtin_amdgcn_mbcnt_lo(~0u, 0u)))
; __device__ __forceinline__ int opaque(int x) { asm volatile("" : "+v"(x)); return x; }
;     __device__ __forceinline__ const float* in(int k) const { return (const float*)(const __attribute__((address_space(1))) float*)get(k); }
; __device__ __forceinline__ void gla_cumdecay(const Ptrs& A, int l, int n, int hd, LAS float* bl, const int wv0) {
;     const int tid = opaque(TID()), d = tid & 127, tq = __builtin_amdgcn_readfirstlane(tid >> 7);
;     const float* wa2 = A.in(4) + (size_t)l * 16 * 512 + hd * 128 + d;
;     float w[16];
; #pragma unroll
;     for (int r = 0; r < 16; ++r) w[r] = wa2[r * 512];
;     const float bias = A.in(5)[(size_t)l * 512 + hd * 128 + d];
;     LAS float* gal = bl + 29184;
;     *(LAS f32x2*)(gal + 2 * tid) = *(const f32x2*)((const float*)(A.ws() + WS_GA1) + (size_t)n * 64 * 16 + 2 * tid);
;     __syncthreads();
;     const LAS float* ga = gal + 16 * tq * 16;
;     float run = 0.f;
;     for (int tt = 0; tt < 16; ++tt) {
;         float pre = bias;
;         const f32x4 g0 = *(const LAS f32x4*)(ga + tt * 16), g1 = *(const LAS f32x4*)(ga + tt * 16 + 4), g2 = *(const LAS f32x4*)(ga + tt * 16 + 8), g3 = *(const LAS f32x4*)(ga + tt * 16 + 12);
;         pre += (g0.x * w[0] + g0.y * w[1]) + (g0.z * w[2] + g0.w * w[3]); pre += (g1.x * w[4] + g1.y * w[5]) + (g1.z * w[6] + g1.w * w[7]);
;         pre += (g2.x * w[8] + g2.y * w[9]) + (g2.z * w[10] + g2.w * w[11]); pre += (g3.x * w[12] + g3.y * w[13]) + (g3.z * w[14] + g3.w * w[15]);
;         const float la = (fminf(pre, 0.f) - __logf(1.0f + __expf(-fabsf(pre)))) * (1.0f / 16.0f);
;         run += la; bl[(16 * tq + tt) * BLS + d] = run;
; __device__ __forceinline__ void gla_out(const Ptrs& A, int l, LAS unsigned char* lds, int c, int G, int wave, int lane_, const int wv0) {
;     ...
;         const int n = it >> 2, hd = it & 3, t0 = n * 64;
;         u32x4 qq[2], kk[2];
; #pragma unroll
;         for (int i = 0; i < 2; ++i) { qq[i] = *(const u32x4*)(GQ + (size_t)(t0 + lane) * 512 + hd * 128 + (wave + 8 * i) * 8); kk[i] = *(const u32x4*)(GK + (size_t)(t0 + lane) * 512 + hd * 128 + (wave + 8 * i) * 8); }
;         gla_cumdecay(A, l, n, hd, bl, wv0);
.LBB0_383:
	s_ashr_i32 s36, s44, 2
	s_lshl_b32 s66, s36, 6
	v_or_b32_e32 v0, s66, v62
	v_ashrrev_i32_e32 v1, 31, v0
	s_and_b32 s37, s44, 3
	v_lshlrev_b64 v[0:1], 10, v[0:1]
	v_lshl_add_u64 v[2:3], s[46:47], 0, v[0:1]
	s_lshl_b32 s56, s37, 8
	v_lshl_add_u64 v[0:1], s[48:49], 0, v[0:1]
	v_lshl_add_u64 v[2:3], v[2:3], 0, s[56:57]
	v_lshl_add_u64 v[0:1], v[0:1], 0, s[56:57]
	s_lshl_b64 s[40:41], s[54:55], 1
	v_lshl_add_u64 v[2:3], v[2:3], 0, s[40:41]
	v_lshl_add_u64 v[0:1], v[0:1], 0, s[40:41]
	v_mov_b32_e32 v23, v204
	v_mov_b32_e32 v198, v0
	v_mov_b32_e32 v199, v1
	v_mov_b32_e32 v200, v2
	v_mov_b32_e32 v201, v3
	v_mov_b32 v16, s77
	ds_read_b64 v[16:17], v16 offset:32
	s_lshl_b32 s40, s37, 9
	v_readfirstlane_b32 s37, v23
	s_waitcnt lgkmcnt(0)
	v_readfirstlane_b32 s67, v16
	v_readfirstlane_b32 s41, v17
	s_add_u32 s92, s67, s40
	v_lshlrev_b32_e32 v16, 2, v23
	s_addc_u32 s93, s41, 0
	v_and_b32_e32 v48, 0x1fc, v16
	v_lshl_add_u64 v[26:27], s[92:93], 0, v[48:49]
	v_add_co_u32_e32 v34, vcc, s39, v26
	s_ashr_i32 s41, s37, 7
	s_nop 0
	v_addc_co_u32_e32 v35, vcc, 0, v27, vcc
	v_add_co_u32_e32 v28, vcc, s45, v26
	s_nop 1
	v_addc_co_u32_e32 v29, vcc, 0, v27, vcc
	v_add_co_u32_e32 v36, vcc, s72, v26
	s_nop 1
	v_addc_co_u32_e32 v37, vcc, 0, v27, vcc
	v_add_co_u32_e32 v18, vcc, s73, v26
	s_nop 1
	v_addc_co_u32_e32 v19, vcc, 0, v27, vcc
	v_add_co_u32_e32 v38, vcc, s74, v26
	s_nop 1
	v_addc_co_u32_e32 v39, vcc, 0, v27, vcc
	v_add_co_u32_e32 v30, vcc, s75, v26
	s_nop 1
	v_addc_co_u32_e32 v31, vcc, 0, v27, vcc
	v_add_co_u32_e32 v40, vcc, s80, v26
	global_load_dword v22, v[28:29], off
	global_load_dword v25, v[28:29], off offset:2048
	global_load_dword v21, v[18:19], off offset:-4096
	global_load_dword v17, v[18:19], off
	global_load_dword v20, v[18:19], off offset:2048
	s_nop 0
	global_load_dword v18, v[30:31], off offset:-4096
	global_load_dword v16, v[30:31], off
	global_load_dword v19, v[30:31], off offset:2048
	v_addc_co_u32_e32 v41, vcc, 0, v27, vcc
	global_load_dword v30, v48, s[92:93]
	global_load_dword v32, v48, s[92:93] offset:2048
	s_nop 0
	global_load_dword v29, v[28:29], off offset:-4096
	s_nop 0
	global_load_dword v31, v[34:35], off offset:2048
	global_load_dword v28, v[36:37], off offset:2048
	global_load_dword v27, v[38:39], off offset:2048
	global_load_dword v24, v[40:41], off
	global_load_dword v26, v[40:41], off offset:2048
	v_mov_b32 v33, s77
	ds_read_b64 v[34:35], v33 offset:40
	s_waitcnt lgkmcnt(0)
	v_readfirstlane_b32 s67, v34
	v_readfirstlane_b32 s37, v35
	s_add_u32 s92, s67, s40
	s_addc_u32 s93, s37, 0
	global_load_dword v33, v48, s[92:93]
	v_mov_b32 v34, s77
	ds_read_b64 v[34:35], v34 offset:168
	s_ashr_i32 s37, s36, 31
	s_lshl_b64 s[36:37], s[36:37], 12
	s_waitcnt lgkmcnt(0)
	v_readfirstlane_b32 s79, v34
	v_readfirstlane_b32 s67, v35
	s_add_u32 s36, s79, s36
	v_lshlrev_b32_e32 v34, 1, v23
	s_addc_u32 s37, s67, s37
	v_ashrrev_i32_e32 v35, 31, v34
	v_lshl_add_u64 v[34:35], v[34:35], 2, s[36:37]
	v_add_co_u32_e32 v34, vcc, s81, v34
	s_lshl_b32 s36, s41, 10
	s_nop 0
	v_addc_co_u32_e32 v35, vcc, 0, v35, vcc
	global_load_dwordx2 v[36:37], v[34:35], off
	s_add_i32 s36, s82, s36
	v_lshl_add_u32 v23, v23, 3, s82
	v_mov_b32_e32 v35, s36
	s_cmp_gt_i32 s41, 0
	global_load_dwordx4 v[12:15], v[200:201], off
	global_load_dwordx4 v[4:7], v[200:201], off offset:128
	global_load_dwordx4 v[8:11], v[198:199], off
	global_load_dwordx4 v[0:3], v[198:199], off offset:128
	s_waitcnt vmcnt(4)
	ds_write_b64 v23, v[36:37]
	s_waitcnt lgkmcnt(0)
	s_barrier
	ds_read_b128 v[36:39], v35
	ds_read_b128 v[40:43], v35 offset:16
	ds_read_b128 v[44:47], v35 offset:32
	ds_read_b128 v[96:99], v35 offset:48
	s_waitcnt lgkmcnt(3)
	v_mul_f32_e32 v23, v32, v37
	v_mul_f32_e32 v34, v31, v39
	s_waitcnt lgkmcnt(2)
	v_mul_f32_e32 v37, v25, v41
	v_mul_f32_e32 v39, v28, v43
	v_fmac_f32_e32 v23, v30, v36
	v_fmac_f32_e32 v34, v29, v38
	v_fmac_f32_e32 v37, v22, v40
	v_fmac_f32_e32 v39, v21, v42
	v_add_f32_e32 v23, v23, v34
	s_waitcnt lgkmcnt(1)
	v_mul_f32_e32 v41, v20, v45
	v_mul_f32_e32 v43, v27, v47
	v_add_f32_e32 v34, v37, v39
	v_add_f32_e32 v23, v33, v23
	s_waitcnt lgkmcnt(0)
	ds_read_b128 v[166:169], v35 offset:64
	ds_read_b128 v[170:173], v35 offset:80
	ds_read_b128 v[174:177], v35 offset:96
	ds_read_b128 v[178:181], v35 offset:112
	v_mul_f32_e32 v45, v19, v97
	v_fmac_f32_e32 v41, v17, v44
	v_fmac_f32_e32 v43, v18, v46
	v_add_f32_e32 v23, v23, v34
	v_mul_f32_e32 v34, v26, v99
	v_add_f32_e32 v36, v41, v43
	v_fmac_f32_e32 v45, v16, v96
	v_fmac_f32_e32 v34, v24, v98
	v_add_f32_e32 v23, v23, v36
	v_add_f32_e32 v34, v45, v34
	v_add_f32_e32 v23, v23, v34
	v_mul_f32_e64 v34, |v23|, s83
	v_exp_f32_e32 v34, v34
	v_min_f32_e32 v23, 0, v23
	v_add_f32_e32 v34, 1.0, v34
	v_cmp_gt_f32_e32 vcc, s84, v34
	s_nop 1
	v_cndmask_b32_e64 v36, 0, 32, vcc
	v_ldexp_f32 v34, v34, v36
	v_log_f32_e32 v36, v34
	v_add_u32_e32 v34, 0, v48
	v_mul_f32_e32 v37, 0x3f317217, v36
	v_fma_f32 v37, v36, s85, -v37
	v_fmac_f32_e32 v37, 0x3377d1cf, v36
	v_fmac_f32_e32 v37, 0x3f317217, v36
	v_cmp_lt_f32_e64 s[36:37], |v36|, s86
	s_nop 1
	v_cndmask_b32_e64 v36, v36, v37, s[36:37]
	v_cndmask_b32_e32 v37, 0, v95, vcc
	v_sub_f32_e32 v36, v36, v37
	v_sub_f32_e32 v23, v23, v36
	s_mul_i32 s36, s41, 0x2100
	v_fma_f32 v36, v23, s87, 0
	v_add_u32_e32 v23, s36, v34
	ds_write_b32 v23, v36
	s_waitcnt lgkmcnt(3)
	v_mul_f32_e32 v37, v32, v167
	v_fmac_f32_e32 v37, v30, v166
	v_mul_f32_e32 v38, v31, v169
	v_fmac_f32_e32 v38, v29, v168
	v_add_f32_e32 v37, v37, v38
	s_waitcnt lgkmcnt(2)
	v_mul_f32_e32 v38, v25, v171
	v_mul_f32_e32 v39, v28, v173
	v_fmac_f32_e32 v38, v22, v170
	v_fmac_f32_e32 v39, v21, v172
	v_add_f32_e32 v37, v33, v37
	v_add_f32_e32 v38, v38, v39
	v_add_f32_e32 v37, v37, v38
	s_waitcnt lgkmcnt(1)
; #define LAS __attribute__((address_space(3)))
; __device__ __forceinline__ void gla_cumdecay(const Ptrs& A, int l, int n, int hd, LAS float* bl, const int wv0) {
;     ...
;     for (int tt = 0; tt < 16; ++tt) {
;         float pre = bias;
;         const f32x4 g0 = *(const LAS f32x4*)(ga + tt * 16), g1 = *(const LAS f32x4*)(ga + tt * 16 + 4), g2 = *(const LAS f32x4*)(ga + tt * 16 + 8), g3 = *(const LAS f32x4*)(ga + tt * 16 + 12);
;         pre += (g0.x * w[0] + g0.y * w[1]) + (g0.z * w[2] + g0.w * w[3]); pre += (g1.x * w[4] + g1.y * w[5]) + (g1.z * w[6] + g1.w * w[7]);
;         pre += (g2.x * w[8] + g2.y * w[9]) + (g2.z * w[10] + g2.w * w[11]); pre += (g3.x * w[12] + g3.y * w[13]) + (g3.z * w[14] + g3.w * w[15]);
;         const float la = (fminf(pre, 0.f) - __logf(1.0f + __expf(-fabsf(pre)))) * (1.0f / 16.0f);
;         run += la; bl[(16 * tq + tt) * BLS + d] = run;
	v_mul_f32_e32 v38, v20, v175
	v_mul_f32_e32 v39, v27, v177
	v_fmac_f32_e32 v38, v17, v174
	v_fmac_f32_e32 v39, v18, v176
	v_add_f32_e32 v38, v38, v39
	v_add_f32_e32 v37, v37, v38
	s_waitcnt lgkmcnt(0)
	ds_read_b128 v[150:153], v35 offset:128
	ds_read_b128 v[154:157], v35 offset:144
	ds_read_b128 v[158:161], v35 offset:160
	ds_read_b128 v[162:165], v35 offset:176
	v_mul_f32_e32 v38, v19, v179
	v_mul_f32_e32 v39, v26, v181
	v_fmac_f32_e32 v38, v16, v178
	v_fmac_f32_e32 v39, v24, v180
	v_add_f32_e32 v38, v38, v39
	v_add_f32_e32 v37, v37, v38
	v_mul_f32_e64 v38, |v37|, s83
	v_exp_f32_e32 v38, v38
	v_min_f32_e32 v37, 0, v37
	v_add_f32_e32 v38, 1.0, v38
	v_cmp_gt_f32_e32 vcc, s84, v38
	s_nop 1
	v_cndmask_b32_e64 v39, 0, 32, vcc
	v_ldexp_f32 v38, v38, v39
	v_log_f32_e32 v38, v38
	s_nop 0
	v_mul_f32_e32 v39, 0x3f317217, v38
	v_fma_f32 v39, v38, s85, -v39
	v_fmac_f32_e32 v39, 0x3377d1cf, v38
	v_fmac_f32_e32 v39, 0x3f317217, v38
	v_cmp_lt_f32_e64 s[36:37], |v38|, s86
	s_nop 1
	v_cndmask_b32_e64 v38, v38, v39, s[36:37]
	v_cndmask_b32_e32 v39, 0, v95, vcc
	v_sub_f32_e32 v38, v38, v39
	v_sub_f32_e32 v37, v37, v38
	v_fmac_f32_e32 v36, 0x3d800000, v37
	ds_write_b32 v23, v36 offset:528
	s_waitcnt lgkmcnt(3)
	v_mul_f32_e32 v37, v32, v151
	v_fmac_f32_e32 v37, v30, v150
	v_mul_f32_e32 v38, v31, v153
	v_fmac_f32_e32 v38, v29, v152
	v_add_f32_e32 v37, v37, v38
	s_waitcnt lgkmcnt(2)
	v_mul_f32_e32 v38, v25, v155
	v_mul_f32_e32 v39, v28, v157
	v_fmac_f32_e32 v38, v22, v154
	v_fmac_f32_e32 v39, v21, v156
	v_add_f32_e32 v37, v33, v37
	v_add_f32_e32 v38, v38, v39
	v_add_f32_e32 v37, v37, v38
	s_waitcnt lgkmcnt(1)
	v_mul_f32_e32 v38, v20, v159
	v_mul_f32_e32 v39, v27, v161
	v_fmac_f32_e32 v38, v17, v158
	v_fmac_f32_e32 v39, v18, v160
	v_add_f32_e32 v38, v38, v39
	v_add_f32_e32 v37, v37, v38
	s_waitcnt lgkmcnt(0)
	ds_read_b128 v[166:169], v35 offset:192
	ds_read_b128 v[170:173], v35 offset:208
	ds_read_b128 v[174:177], v35 offset:224
	ds_read_b128 v[178:181], v35 offset:240
	v_mul_f32_e32 v38, v19, v163
	v_mul_f32_e32 v39, v26, v165
	v_fmac_f32_e32 v38, v16, v162
	v_fmac_f32_e32 v39, v24, v164
	v_add_f32_e32 v38, v38, v39
	v_add_f32_e32 v37, v37, v38
	v_mul_f32_e64 v38, |v37|, s83
	v_exp_f32_e32 v38, v38
	v_min_f32_e32 v37, 0, v37
	v_add_f32_e32 v38, 1.0, v38
	v_cmp_gt_f32_e32 vcc, s84, v38
	s_nop 1
	v_cndmask_b32_e64 v39, 0, 32, vcc
	v_ldexp_f32 v38, v38, v39
	v_log_f32_e32 v38, v38
	s_nop 0
	v_mul_f32_e32 v39, 0x3f317217, v38
	v_fma_f32 v39, v38, s85, -v39
	v_fmac_f32_e32 v39, 0x3377d1cf, v38
	v_fmac_f32_e32 v39, 0x3f317217, v38
	v_cmp_lt_f32_e64 s[36:37], |v38|, s86
	s_nop 1
	v_cndmask_b32_e64 v38, v38, v39, s[36:37]
	v_cndmask_b32_e32 v39, 0, v95, vcc
	v_sub_f32_e32 v38, v38, v39
	v_sub_f32_e32 v37, v37, v38
	v_fmac_f32_e32 v36, 0x3d800000, v37
	ds_write_b32 v23, v36 offset:1056
	s_waitcnt lgkmcnt(3)
	v_mul_f32_e32 v37, v32, v167
	v_fmac_f32_e32 v37, v30, v166
	v_mul_f32_e32 v38, v31, v169
	v_fmac_f32_e32 v38, v29, v168
	v_add_f32_e32 v37, v37, v38
	s_waitcnt lgkmcnt(2)
	v_mul_f32_e32 v38, v25, v171
	v_mul_f32_e32 v39, v28, v173
	v_fmac_f32_e32 v38, v22, v170
	v_fmac_f32_e32 v39, v21, v172
	v_add_f32_e32 v37, v33, v37
	v_add_f32_e32 v38, v38, v39
	v_add_f32_e32 v37, v37, v38
	s_waitcnt lgkmcnt(1)
	v_mul_f32_e32 v38, v20, v175
	v_mul_f32_e32 v39, v27, v177
	v_fmac_f32_e32 v38, v17, v174
	v_fmac_f32_e32 v39, v18, v176
	v_add_f32_e32 v38, v38, v39
	v_add_f32_e32 v37, v37, v38
	s_waitcnt lgkmcnt(0)
	ds_read_b128 v[150:153], v35 offset:256
	ds_read_b128 v[154:157], v35 offset:272
	ds_read_b128 v[158:161], v35 offset:288
	ds_read_b128 v[162:165], v35 offset:304
	v_mul_f32_e32 v38, v19, v179
	v_mul_f32_e32 v39, v26, v181
	v_fmac_f32_e32 v38, v16, v178
	v_fmac_f32_e32 v39, v24, v180
	v_add_f32_e32 v38, v38, v39
	v_add_f32_e32 v37, v37, v38
	v_mul_f32_e64 v38, |v37|, s83
	v_exp_f32_e32 v38, v38
	v_min_f32_e32 v37, 0, v37
	v_add_f32_e32 v38, 1.0, v38
	v_cmp_gt_f32_e32 vcc, s84, v38
	s_nop 1
	v_cndmask_b32_e64 v39, 0, 32, vcc
	v_ldexp_f32 v38, v38, v39
	v_log_f32_e32 v38, v38
	s_nop 0
	v_mul_f32_e32 v39, 0x3f317217, v38
	v_fma_f32 v39, v38, s85, -v39
	v_fmac_f32_e32 v39, 0x3377d1cf, v38
	v_fmac_f32_e32 v39, 0x3f317217, v38
	v_cmp_lt_f32_e64 s[36:37], |v38|, s86
	s_nop 1
	v_cndmask_b32_e64 v38, v38, v39, s[36:37]
	v_cndmask_b32_e32 v39, 0, v95, vcc
	v_sub_f32_e32 v38, v38, v39
	v_sub_f32_e32 v37, v37, v38
	v_fmac_f32_e32 v36, 0x3d800000, v37
	ds_write_b32 v23, v36 offset:1584
	s_waitcnt lgkmcnt(3)
	v_mul_f32_e32 v37, v32, v151
	v_fmac_f32_e32 v37, v30, v150
	v_mul_f32_e32 v38, v31, v153
	v_fmac_f32_e32 v38, v29, v152
	v_add_f32_e32 v37, v37, v38
	s_waitcnt lgkmcnt(2)
	v_mul_f32_e32 v38, v25, v155
	v_mul_f32_e32 v39, v28, v157
	v_fmac_f32_e32 v38, v22, v154
	v_fmac_f32_e32 v39, v21, v156
	v_add_f32_e32 v37, v33, v37
	v_add_f32_e32 v38, v38, v39
	v_add_f32_e32 v37, v37, v38
	s_waitcnt lgkmcnt(1)
	v_mul_f32_e32 v38, v20, v159
	v_mul_f32_e32 v39, v27, v161
	v_fmac_f32_e32 v38, v17, v158
	v_fmac_f32_e32 v39, v18, v160
	v_add_f32_e32 v38, v38, v39
	v_add_f32_e32 v37, v37, v38
	s_waitcnt lgkmcnt(0)
	ds_read_b128 v[166:169], v35 offset:320
	ds_read_b128 v[170:173], v35 offset:336
	ds_read_b128 v[174:177], v35 offset:352
	ds_read_b128 v[178:181], v35 offset:368
	v_mul_f32_e32 v38, v19, v163
	v_mul_f32_e32 v39, v26, v165
	v_fmac_f32_e32 v38, v16, v162
	v_fmac_f32_e32 v39, v24, v164
	v_add_f32_e32 v38, v38, v39
	v_add_f32_e32 v37, v37, v38
	v_mul_f32_e64 v38, |v37|, s83
	v_exp_f32_e32 v38, v38
	v_min_f32_e32 v37, 0, v37
	v_add_f32_e32 v38, 1.0, v38
	v_cmp_gt_f32_e32 vcc, s84, v38
	s_nop 1
	v_cndmask_b32_e64 v39, 0, 32, vcc
	v_ldexp_f32 v38, v38, v39
	v_log_f32_e32 v38, v38
	s_nop 0
	v_mul_f32_e32 v39, 0x3f317217, v38
	v_fma_f32 v39, v38, s85, -v39
	v_fmac_f32_e32 v39, 0x3377d1cf, v38
	v_fmac_f32_e32 v39, 0x3f317217, v38
	v_cmp_lt_f32_e64 s[36:37], |v38|, s86
	s_nop 1
	v_cndmask_b32_e64 v38, v38, v39, s[36:37]
	v_cndmask_b32_e32 v39, 0, v95, vcc
	v_sub_f32_e32 v38, v38, v39
	v_sub_f32_e32 v37, v37, v38
	v_fmac_f32_e32 v36, 0x3d800000, v37
	ds_write_b32 v23, v36 offset:2112
	s_waitcnt lgkmcnt(3)
; #define LAS __attribute__((address_space(3)))
; __device__ __forceinline__ void gla_cumdecay(const Ptrs& A, int l, int n, int hd, LAS float* bl, const int wv0) {
;     ...
;     const LAS float* ga = gal + 16 * tq * 16;
;     float run = 0.f;
;     for (int tt = 0; tt < 16; ++tt) {
;         float pre = bias;
;         const f32x4 g0 = *(const LAS f32x4*)(ga + tt * 16), g1 = *(const LAS f32x4*)(ga + tt * 16 + 4), g2 = *(const LAS f32x4*)(ga + tt * 16 + 8), g3 = *(const LAS f32x4*)(ga + tt * 16 + 12);
;         pre += (g0.x * w[0] + g0.y * w[1]) + (g0.z * w[2] + g0.w * w[3]); pre += (g1.x * w[4] + g1.y * w[5]) + (g1.z * w[6] + g1.w * w[7]);
;         pre += (g2.x * w[8] + g2.y * w[9]) + (g2.z * w[10] + g2.w * w[11]); pre += (g3.x * w[12] + g3.y * w[13]) + (g3.z * w[14] + g3.w * w[15]);
;         const float la = (fminf(pre, 0.f) - __logf(1.0f + __expf(-fabsf(pre)))) * (1.0f / 16.0f);
;         run += la; bl[(16 * tq + tt) * BLS + d] = run;
;     }
	v_mul_f32_e32 v37, v32, v167
	v_fmac_f32_e32 v37, v30, v166
	v_mul_f32_e32 v38, v31, v169
	v_fmac_f32_e32 v38, v29, v168
	v_add_f32_e32 v37, v37, v38
	s_waitcnt lgkmcnt(2)
	v_mul_f32_e32 v38, v25, v171
	v_mul_f32_e32 v39, v28, v173
	v_fmac_f32_e32 v38, v22, v170
	v_fmac_f32_e32 v39, v21, v172
	v_add_f32_e32 v37, v33, v37
	v_add_f32_e32 v38, v38, v39
	v_add_f32_e32 v37, v37, v38
	s_waitcnt lgkmcnt(1)
	v_mul_f32_e32 v38, v20, v175
	v_mul_f32_e32 v39, v27, v177
	v_fmac_f32_e32 v38, v17, v174
	v_fmac_f32_e32 v39, v18, v176
	v_add_f32_e32 v38, v38, v39
	v_add_f32_e32 v37, v37, v38
	s_waitcnt lgkmcnt(0)
	ds_read_b128 v[150:153], v35 offset:384
	ds_read_b128 v[154:157], v35 offset:400
	ds_read_b128 v[158:161], v35 offset:416
	ds_read_b128 v[162:165], v35 offset:432
	v_mul_f32_e32 v38, v19, v179
	v_mul_f32_e32 v39, v26, v181
	v_fmac_f32_e32 v38, v16, v178
	v_fmac_f32_e32 v39, v24, v180
	v_add_f32_e32 v38, v38, v39
	v_add_f32_e32 v37, v37, v38
	v_mul_f32_e64 v38, |v37|, s83
	v_exp_f32_e32 v38, v38
	v_min_f32_e32 v37, 0, v37
	v_add_f32_e32 v38, 1.0, v38
	v_cmp_gt_f32_e32 vcc, s84, v38
	s_nop 1
	v_cndmask_b32_e64 v39, 0, 32, vcc
	v_ldexp_f32 v38, v38, v39
	v_log_f32_e32 v38, v38
	s_nop 0
	v_mul_f32_e32 v39, 0x3f317217, v38
	v_fma_f32 v39, v38, s85, -v39
	v_fmac_f32_e32 v39, 0x3377d1cf, v38
	v_fmac_f32_e32 v39, 0x3f317217, v38
	v_cmp_lt_f32_e64 s[36:37], |v38|, s86
	s_nop 1
	v_cndmask_b32_e64 v38, v38, v39, s[36:37]
	v_cndmask_b32_e32 v39, 0, v95, vcc
	v_sub_f32_e32 v38, v38, v39
	v_sub_f32_e32 v37, v37, v38
	v_fmac_f32_e32 v36, 0x3d800000, v37
	ds_write_b32 v23, v36 offset:2640
	s_waitcnt lgkmcnt(3)
	v_mul_f32_e32 v37, v32, v151
	v_fmac_f32_e32 v37, v30, v150
	v_mul_f32_e32 v38, v31, v153
	v_fmac_f32_e32 v38, v29, v152
	v_add_f32_e32 v37, v37, v38
	s_waitcnt lgkmcnt(2)
	v_mul_f32_e32 v38, v25, v155
	v_mul_f32_e32 v39, v28, v157
	v_fmac_f32_e32 v38, v22, v154
	v_fmac_f32_e32 v39, v21, v156
	v_add_f32_e32 v37, v33, v37
	v_add_f32_e32 v38, v38, v39
	v_add_f32_e32 v37, v37, v38
	s_waitcnt lgkmcnt(1)
	v_mul_f32_e32 v38, v20, v159
	v_mul_f32_e32 v39, v27, v161
	v_fmac_f32_e32 v38, v17, v158
	v_fmac_f32_e32 v39, v18, v160
	v_add_f32_e32 v38, v38, v39
	v_add_f32_e32 v37, v37, v38
	s_waitcnt lgkmcnt(0)
	ds_read_b128 v[166:169], v35 offset:448
	ds_read_b128 v[170:173], v35 offset:464
	ds_read_b128 v[174:177], v35 offset:480
	ds_read_b128 v[178:181], v35 offset:496
	v_mul_f32_e32 v38, v19, v163
	v_mul_f32_e32 v39, v26, v165
	v_fmac_f32_e32 v38, v16, v162
	v_fmac_f32_e32 v39, v24, v164
	v_add_f32_e32 v38, v38, v39
	v_add_f32_e32 v37, v37, v38
	v_mul_f32_e64 v38, |v37|, s83
	v_exp_f32_e32 v38, v38
	v_min_f32_e32 v37, 0, v37
	v_add_f32_e32 v38, 1.0, v38
	v_cmp_gt_f32_e32 vcc, s84, v38
	s_nop 1
	v_cndmask_b32_e64 v39, 0, 32, vcc
	v_ldexp_f32 v38, v38, v39
	v_log_f32_e32 v38, v38
	s_nop 0
	v_mul_f32_e32 v39, 0x3f317217, v38
	v_fma_f32 v39, v38, s85, -v39
	v_fmac_f32_e32 v39, 0x3377d1cf, v38
	v_fmac_f32_e32 v39, 0x3f317217, v38
	v_cmp_lt_f32_e64 s[36:37], |v38|, s86
	s_nop 1
	v_cndmask_b32_e64 v38, v38, v39, s[36:37]
	v_cndmask_b32_e32 v39, 0, v95, vcc
	v_sub_f32_e32 v38, v38, v39
	v_sub_f32_e32 v37, v37, v38
	v_fmac_f32_e32 v36, 0x3d800000, v37
	ds_write_b32 v23, v36 offset:3168
	s_waitcnt lgkmcnt(3)
	v_mul_f32_e32 v37, v32, v167
	v_fmac_f32_e32 v37, v30, v166
	v_mul_f32_e32 v38, v31, v169
	v_fmac_f32_e32 v38, v29, v168
	v_add_f32_e32 v37, v37, v38
	s_waitcnt lgkmcnt(2)
	v_mul_f32_e32 v38, v25, v171
	v_mul_f32_e32 v39, v28, v173
	v_fmac_f32_e32 v38, v22, v170
	v_fmac_f32_e32 v39, v21, v172
	v_add_f32_e32 v37, v33, v37
	v_add_f32_e32 v38, v38, v39
	v_add_f32_e32 v37, v37, v38
	s_waitcnt lgkmcnt(1)
	v_mul_f32_e32 v38, v20, v175
	v_mul_f32_e32 v39, v27, v177
	v_fmac_f32_e32 v38, v17, v174
	v_fmac_f32_e32 v39, v18, v176
	v_add_f32_e32 v38, v38, v39
	v_add_f32_e32 v37, v37, v38
	s_waitcnt lgkmcnt(0)
	ds_read_b128 v[150:153], v35 offset:512
	ds_read_b128 v[154:157], v35 offset:528
	ds_read_b128 v[158:161], v35 offset:544
	ds_read_b128 v[162:165], v35 offset:560
	v_mul_f32_e32 v38, v19, v179
	v_mul_f32_e32 v39, v26, v181
	v_fmac_f32_e32 v38, v16, v178
	v_fmac_f32_e32 v39, v24, v180
	v_add_f32_e32 v38, v38, v39
	v_add_f32_e32 v37, v37, v38
	v_mul_f32_e64 v38, |v37|, s83
	v_exp_f32_e32 v38, v38
	v_min_f32_e32 v37, 0, v37
	v_add_f32_e32 v38, 1.0, v38
	v_cmp_gt_f32_e32 vcc, s84, v38
	s_nop 1
	v_cndmask_b32_e64 v39, 0, 32, vcc
	v_ldexp_f32 v38, v38, v39
	v_log_f32_e32 v38, v38
	s_nop 0
	v_mul_f32_e32 v39, 0x3f317217, v38
	v_fma_f32 v39, v38, s85, -v39
	v_fmac_f32_e32 v39, 0x3377d1cf, v38
	v_fmac_f32_e32 v39, 0x3f317217, v38
	v_cmp_lt_f32_e64 s[36:37], |v38|, s86
	s_nop 1
	v_cndmask_b32_e64 v38, v38, v39, s[36:37]
	v_cndmask_b32_e32 v39, 0, v95, vcc
	v_sub_f32_e32 v38, v38, v39
	v_sub_f32_e32 v37, v37, v38
	v_fmac_f32_e32 v36, 0x3d800000, v37
	ds_write_b32 v23, v36 offset:3696
	s_waitcnt lgkmcnt(3)
	v_mul_f32_e32 v37, v32, v151
	v_fmac_f32_e32 v37, v30, v150
	v_mul_f32_e32 v38, v31, v153
	v_fmac_f32_e32 v38, v29, v152
	v_add_f32_e32 v37, v37, v38
	s_waitcnt lgkmcnt(2)
	v_mul_f32_e32 v38, v25, v155
	v_mul_f32_e32 v39, v28, v157
	v_fmac_f32_e32 v38, v22, v154
	v_fmac_f32_e32 v39, v21, v156
	v_add_f32_e32 v37, v33, v37
	v_add_f32_e32 v38, v38, v39
	v_add_f32_e32 v37, v37, v38
	s_waitcnt lgkmcnt(1)
	v_mul_f32_e32 v38, v20, v159
	v_mul_f32_e32 v39, v27, v161
	v_fmac_f32_e32 v38, v17, v158
	v_fmac_f32_e32 v39, v18, v160
	v_add_f32_e32 v38, v38, v39
	v_add_f32_e32 v37, v37, v38
	s_waitcnt lgkmcnt(0)
; #define LAS __attribute__((address_space(3)))
; __device__ __forceinline__ void gla_cumdecay(const Ptrs& A, int l, int n, int hd, LAS float* bl, const int wv0) {
;     ...
;     const LAS float* ga = gal + 16 * tq * 16;
;     float run = 0.f;
;     for (int tt = 0; tt < 16; ++tt) {
;         float pre = bias;
;         const f32x4 g0 = *(const LAS f32x4*)(ga + tt * 16), g1 = *(const LAS f32x4*)(ga + tt * 16 + 4), g2 = *(const LAS f32x4*)(ga + tt * 16 + 8), g3 = *(const LAS f32x4*)(ga + tt * 16 + 12);
;         pre += (g0.x * w[0] + g0.y * w[1]) + (g0.z * w[2] + g0.w * w[3]); pre += (g1.x * w[4] + g1.y * w[5]) + (g1.z * w[6] + g1.w * w[7]);
;         pre += (g2.x * w[8] + g2.y * w[9]) + (g2.z * w[10] + g2.w * w[11]); pre += (g3.x * w[12] + g3.y * w[13]) + (g3.z * w[14] + g3.w * w[15]);
;         const float la = (fminf(pre, 0.f) - __logf(1.0f + __expf(-fabsf(pre)))) * (1.0f / 16.0f);
;         run += la; bl[(16 * tq + tt) * BLS + d] = run;
;     }
	ds_read_b128 v[166:169], v35 offset:576
	ds_read_b128 v[170:173], v35 offset:592
	ds_read_b128 v[174:177], v35 offset:608
	ds_read_b128 v[178:181], v35 offset:624
	v_mul_f32_e32 v38, v19, v163
	v_mul_f32_e32 v39, v26, v165
	v_fmac_f32_e32 v38, v16, v162
	v_fmac_f32_e32 v39, v24, v164
	v_add_f32_e32 v38, v38, v39
	v_add_f32_e32 v37, v37, v38
	v_mul_f32_e64 v38, |v37|, s83
	v_exp_f32_e32 v38, v38
	v_min_f32_e32 v37, 0, v37
	v_add_f32_e32 v38, 1.0, v38
	v_cmp_gt_f32_e32 vcc, s84, v38
	s_nop 1
	v_cndmask_b32_e64 v39, 0, 32, vcc
	v_ldexp_f32 v38, v38, v39
	v_log_f32_e32 v38, v38
	s_nop 0
	v_mul_f32_e32 v39, 0x3f317217, v38
	v_fma_f32 v39, v38, s85, -v39
	v_fmac_f32_e32 v39, 0x3377d1cf, v38
	v_fmac_f32_e32 v39, 0x3f317217, v38
	v_cmp_lt_f32_e64 s[36:37], |v38|, s86
	s_nop 1
	v_cndmask_b32_e64 v38, v38, v39, s[36:37]
	v_cndmask_b32_e32 v39, 0, v95, vcc
	v_sub_f32_e32 v38, v38, v39
	v_sub_f32_e32 v37, v37, v38
	v_fmac_f32_e32 v36, 0x3d800000, v37
	ds_write_b32 v23, v36 offset:4224
	s_waitcnt lgkmcnt(3)
	v_mul_f32_e32 v37, v32, v167
	v_fmac_f32_e32 v37, v30, v166
	v_mul_f32_e32 v38, v31, v169
	v_fmac_f32_e32 v38, v29, v168
	v_add_f32_e32 v37, v37, v38
	s_waitcnt lgkmcnt(2)
	v_mul_f32_e32 v38, v25, v171
	v_mul_f32_e32 v39, v28, v173
	v_fmac_f32_e32 v38, v22, v170
	v_fmac_f32_e32 v39, v21, v172
	v_add_f32_e32 v37, v33, v37
	v_add_f32_e32 v38, v38, v39
	v_add_f32_e32 v37, v37, v38
	s_waitcnt lgkmcnt(1)
	v_mul_f32_e32 v38, v20, v175
	v_mul_f32_e32 v39, v27, v177
	v_fmac_f32_e32 v38, v17, v174
	v_fmac_f32_e32 v39, v18, v176
	v_add_f32_e32 v38, v38, v39
	v_add_f32_e32 v37, v37, v38
	s_waitcnt lgkmcnt(0)
	ds_read_b128 v[150:153], v35 offset:640
	ds_read_b128 v[154:157], v35 offset:656
	ds_read_b128 v[158:161], v35 offset:672
	ds_read_b128 v[162:165], v35 offset:688
	v_mul_f32_e32 v38, v19, v179
	v_mul_f32_e32 v39, v26, v181
	v_fmac_f32_e32 v38, v16, v178
	v_fmac_f32_e32 v39, v24, v180
	v_add_f32_e32 v38, v38, v39
	v_add_f32_e32 v37, v37, v38
	v_mul_f32_e64 v38, |v37|, s83
	v_exp_f32_e32 v38, v38
	v_min_f32_e32 v37, 0, v37
	v_add_f32_e32 v38, 1.0, v38
	v_cmp_gt_f32_e32 vcc, s84, v38
	s_nop 1
	v_cndmask_b32_e64 v39, 0, 32, vcc
	v_ldexp_f32 v38, v38, v39
	v_log_f32_e32 v38, v38
	s_nop 0
	v_mul_f32_e32 v39, 0x3f317217, v38
	v_fma_f32 v39, v38, s85, -v39
	v_fmac_f32_e32 v39, 0x3377d1cf, v38
	v_fmac_f32_e32 v39, 0x3f317217, v38
	v_cmp_lt_f32_e64 s[36:37], |v38|, s86
	s_nop 1
	v_cndmask_b32_e64 v38, v38, v39, s[36:37]
	v_cndmask_b32_e32 v39, 0, v95, vcc
	v_sub_f32_e32 v38, v38, v39
	v_sub_f32_e32 v37, v37, v38
	v_fmac_f32_e32 v36, 0x3d800000, v37
	ds_write_b32 v23, v36 offset:4752
	s_waitcnt lgkmcnt(3)
	v_mul_f32_e32 v37, v32, v151
	v_fmac_f32_e32 v37, v30, v150
	v_mul_f32_e32 v38, v31, v153
	v_fmac_f32_e32 v38, v29, v152
	v_add_f32_e32 v37, v37, v38
	s_waitcnt lgkmcnt(2)
	v_mul_f32_e32 v38, v25, v155
	v_mul_f32_e32 v39, v28, v157
	v_fmac_f32_e32 v38, v22, v154
	v_fmac_f32_e32 v39, v21, v156
	v_add_f32_e32 v37, v33, v37
	v_add_f32_e32 v38, v38, v39
	v_add_f32_e32 v37, v37, v38
	s_waitcnt lgkmcnt(1)
	v_mul_f32_e32 v38, v20, v159
	v_mul_f32_e32 v39, v27, v161
	v_fmac_f32_e32 v38, v17, v158
	v_fmac_f32_e32 v39, v18, v160
	v_add_f32_e32 v38, v38, v39
	v_add_f32_e32 v37, v37, v38
	s_waitcnt lgkmcnt(0)
	ds_read_b128 v[166:169], v35 offset:704
	ds_read_b128 v[170:173], v35 offset:720
	ds_read_b128 v[174:177], v35 offset:736
	ds_read_b128 v[178:181], v35 offset:752
	v_mul_f32_e32 v38, v19, v163
	v_mul_f32_e32 v39, v26, v165
	v_fmac_f32_e32 v38, v16, v162
	v_fmac_f32_e32 v39, v24, v164
	v_add_f32_e32 v38, v38, v39
	v_add_f32_e32 v37, v37, v38
	v_mul_f32_e64 v38, |v37|, s83
	v_exp_f32_e32 v38, v38
	v_min_f32_e32 v37, 0, v37
	v_add_f32_e32 v38, 1.0, v38
	v_cmp_gt_f32_e32 vcc, s84, v38
	s_nop 1
	v_cndmask_b32_e64 v39, 0, 32, vcc
	v_ldexp_f32 v38, v38, v39
	v_log_f32_e32 v38, v38
	s_nop 0
	v_mul_f32_e32 v39, 0x3f317217, v38
	v_fma_f32 v39, v38, s85, -v39
	v_fmac_f32_e32 v39, 0x3377d1cf, v38
	v_fmac_f32_e32 v39, 0x3f317217, v38
	v_cmp_lt_f32_e64 s[36:37], |v38|, s86
	s_nop 1
	v_cndmask_b32_e64 v38, v38, v39, s[36:37]
	v_cndmask_b32_e32 v39, 0, v95, vcc
	v_sub_f32_e32 v38, v38, v39
	v_sub_f32_e32 v37, v37, v38
	v_fmac_f32_e32 v36, 0x3d800000, v37
	ds_write_b32 v23, v36 offset:5280
	s_waitcnt lgkmcnt(3)
	v_mul_f32_e32 v37, v32, v167
	v_fmac_f32_e32 v37, v30, v166
	v_mul_f32_e32 v38, v31, v169
	v_fmac_f32_e32 v38, v29, v168
	v_add_f32_e32 v37, v37, v38
	s_waitcnt lgkmcnt(2)
	v_mul_f32_e32 v38, v25, v171
	v_mul_f32_e32 v39, v28, v173
	v_fmac_f32_e32 v38, v22, v170
	v_fmac_f32_e32 v39, v21, v172
	v_add_f32_e32 v37, v33, v37
	v_add_f32_e32 v38, v38, v39
	v_add_f32_e32 v37, v37, v38
	s_waitcnt lgkmcnt(1)
	v_mul_f32_e32 v38, v20, v175
	v_mul_f32_e32 v39, v27, v177
	v_fmac_f32_e32 v38, v17, v174
	v_fmac_f32_e32 v39, v18, v176
	v_add_f32_e32 v38, v38, v39
	v_add_f32_e32 v37, v37, v38
	s_waitcnt lgkmcnt(0)
	ds_read_b128 v[150:153], v35 offset:768
	ds_read_b128 v[154:157], v35 offset:784
	ds_read_b128 v[158:161], v35 offset:800
	ds_read_b128 v[162:165], v35 offset:816
	v_mul_f32_e32 v38, v19, v179
	v_mul_f32_e32 v39, v26, v181
	v_fmac_f32_e32 v38, v16, v178
	v_fmac_f32_e32 v39, v24, v180
	v_add_f32_e32 v38, v38, v39
	v_add_f32_e32 v37, v37, v38
	v_mul_f32_e64 v38, |v37|, s83
	v_exp_f32_e32 v38, v38
	v_min_f32_e32 v37, 0, v37
	v_add_f32_e32 v38, 1.0, v38
	v_cmp_gt_f32_e32 vcc, s84, v38
	s_nop 1
	v_cndmask_b32_e64 v39, 0, 32, vcc
	v_ldexp_f32 v38, v38, v39
	v_log_f32_e32 v38, v38
	s_nop 0
	v_mul_f32_e32 v39, 0x3f317217, v38
	v_fma_f32 v39, v38, s85, -v39
	v_fmac_f32_e32 v39, 0x3377d1cf, v38
	v_fmac_f32_e32 v39, 0x3f317217, v38
	v_cmp_lt_f32_e64 s[36:37], |v38|, s86
	s_nop 1
	v_cndmask_b32_e64 v38, v38, v39, s[36:37]
	v_cndmask_b32_e32 v39, 0, v95, vcc
	v_sub_f32_e32 v38, v38, v39
	v_sub_f32_e32 v37, v37, v38
	v_fmac_f32_e32 v36, 0x3d800000, v37
	ds_write_b32 v23, v36 offset:5808
	s_waitcnt lgkmcnt(3)
; #define LAS __attribute__((address_space(3)))
; __device__ __forceinline__ void gla_cumdecay(const Ptrs& A, int l, int n, int hd, LAS float* bl, const int wv0) {
;     ...
;     for (int tt = 0; tt < 16; ++tt) {
;         float pre = bias;
;         const f32x4 g0 = *(const LAS f32x4*)(ga + tt * 16), g1 = *(const LAS f32x4*)(ga + tt * 16 + 4), g2 = *(const LAS f32x4*)(ga + tt * 16 + 8), g3 = *(const LAS f32x4*)(ga + tt * 16 + 12);
;         pre += (g0.x * w[0] + g0.y * w[1]) + (g0.z * w[2] + g0.w * w[3]); pre += (g1.x * w[4] + g1.y * w[5]) + (g1.z * w[6] + g1.w * w[7]);
;         pre += (g2.x * w[8] + g2.y * w[9]) + (g2.z * w[10] + g2.w * w[11]); pre += (g3.x * w[12] + g3.y * w[13]) + (g3.z * w[14] + g3.w * w[15]);
;         const float la = (fminf(pre, 0.f) - __logf(1.0f + __expf(-fabsf(pre)))) * (1.0f / 16.0f);
;         run += la; bl[(16 * tq + tt) * BLS + d] = run;
;     }
;     __syncthreads();
;     float add = 0.f;
; #pragma unroll
;     for (int q = 0; q < 3; ++q) if (q < tq) add += bl[(16 * q + 15) * BLS + d];
;     __syncthreads();
	v_mul_f32_e32 v37, v32, v151
	v_fmac_f32_e32 v37, v30, v150
	v_mul_f32_e32 v38, v31, v153
	v_fmac_f32_e32 v38, v29, v152
	v_add_f32_e32 v37, v37, v38
	s_waitcnt lgkmcnt(2)
	v_mul_f32_e32 v38, v25, v155
	v_mul_f32_e32 v39, v28, v157
	v_fmac_f32_e32 v38, v22, v154
	v_fmac_f32_e32 v39, v21, v156
	v_add_f32_e32 v37, v33, v37
	v_add_f32_e32 v38, v38, v39
	v_add_f32_e32 v37, v37, v38
	s_waitcnt lgkmcnt(1)
	v_mul_f32_e32 v38, v20, v159
	v_mul_f32_e32 v39, v27, v161
	v_fmac_f32_e32 v38, v17, v158
	v_fmac_f32_e32 v39, v18, v160
	v_add_f32_e32 v38, v38, v39
	v_add_f32_e32 v37, v37, v38
	s_waitcnt lgkmcnt(0)
	ds_read_b128 v[166:169], v35 offset:832
	ds_read_b128 v[170:173], v35 offset:848
	ds_read_b128 v[174:177], v35 offset:864
	ds_read_b128 v[178:181], v35 offset:880
	v_mul_f32_e32 v38, v19, v163
	v_mul_f32_e32 v39, v26, v165
	v_fmac_f32_e32 v38, v16, v162
	v_fmac_f32_e32 v39, v24, v164
	v_add_f32_e32 v38, v38, v39
	v_add_f32_e32 v37, v37, v38
	v_mul_f32_e64 v38, |v37|, s83
	v_exp_f32_e32 v38, v38
	v_min_f32_e32 v37, 0, v37
	v_add_f32_e32 v38, 1.0, v38
	v_cmp_gt_f32_e32 vcc, s84, v38
	s_nop 1
	v_cndmask_b32_e64 v39, 0, 32, vcc
	v_ldexp_f32 v38, v38, v39
	v_log_f32_e32 v38, v38
	s_nop 0
	v_mul_f32_e32 v39, 0x3f317217, v38
	v_fma_f32 v39, v38, s85, -v39
	v_fmac_f32_e32 v39, 0x3377d1cf, v38
	v_fmac_f32_e32 v39, 0x3f317217, v38
	v_cmp_lt_f32_e64 s[36:37], |v38|, s86
	s_nop 1
	v_cndmask_b32_e64 v38, v38, v39, s[36:37]
	v_cndmask_b32_e32 v39, 0, v95, vcc
	v_sub_f32_e32 v38, v38, v39
	v_sub_f32_e32 v37, v37, v38
	v_fmac_f32_e32 v36, 0x3d800000, v37
	ds_write_b32 v23, v36 offset:6336
	s_waitcnt lgkmcnt(3)
	v_mul_f32_e32 v37, v32, v167
	v_fmac_f32_e32 v37, v30, v166
	v_mul_f32_e32 v38, v31, v169
	v_fmac_f32_e32 v38, v29, v168
	v_add_f32_e32 v37, v37, v38
	s_waitcnt lgkmcnt(2)
	v_mul_f32_e32 v38, v25, v171
	v_mul_f32_e32 v39, v28, v173
	v_fmac_f32_e32 v38, v22, v170
	v_fmac_f32_e32 v39, v21, v172
	v_add_f32_e32 v37, v33, v37
	v_add_f32_e32 v38, v38, v39
	v_add_f32_e32 v37, v37, v38
	s_waitcnt lgkmcnt(1)
	v_mul_f32_e32 v38, v20, v175
	v_mul_f32_e32 v39, v27, v177
	v_fmac_f32_e32 v38, v17, v174
	v_fmac_f32_e32 v39, v18, v176
	v_add_f32_e32 v38, v38, v39
	v_add_f32_e32 v37, v37, v38
	s_waitcnt lgkmcnt(0)
	ds_read_b128 v[150:153], v35 offset:896
	ds_read_b128 v[154:157], v35 offset:912
	ds_read_b128 v[158:161], v35 offset:928
	ds_read_b128 v[162:165], v35 offset:944
	v_mul_f32_e32 v38, v19, v179
	v_mul_f32_e32 v39, v26, v181
	v_fmac_f32_e32 v38, v16, v178
	v_fmac_f32_e32 v39, v24, v180
	v_add_f32_e32 v38, v38, v39
	v_add_f32_e32 v37, v37, v38
	v_mul_f32_e64 v38, |v37|, s83
	v_exp_f32_e32 v38, v38
	v_min_f32_e32 v37, 0, v37
	v_add_f32_e32 v38, 1.0, v38
	v_cmp_gt_f32_e32 vcc, s84, v38
	s_nop 1
	v_cndmask_b32_e64 v39, 0, 32, vcc
	v_ldexp_f32 v38, v38, v39
	v_log_f32_e32 v38, v38
	s_nop 0
	v_mul_f32_e32 v39, 0x3f317217, v38
	v_fma_f32 v39, v38, s85, -v39
	v_fmac_f32_e32 v39, 0x3377d1cf, v38
	v_fmac_f32_e32 v39, 0x3f317217, v38
	v_cmp_lt_f32_e64 s[36:37], |v38|, s86
	s_nop 1
	v_cndmask_b32_e64 v38, v38, v39, s[36:37]
	v_cndmask_b32_e32 v39, 0, v95, vcc
	v_sub_f32_e32 v38, v38, v39
	v_sub_f32_e32 v37, v37, v38
	v_fmac_f32_e32 v36, 0x3d800000, v37
	ds_write_b32 v23, v36 offset:6864
	s_waitcnt lgkmcnt(3)
	v_mul_f32_e32 v37, v32, v151
	v_fmac_f32_e32 v37, v30, v150
	v_mul_f32_e32 v38, v31, v153
	v_fmac_f32_e32 v38, v29, v152
	v_add_f32_e32 v37, v37, v38
	s_waitcnt lgkmcnt(2)
	v_mul_f32_e32 v38, v25, v155
	v_mul_f32_e32 v39, v28, v157
	v_fmac_f32_e32 v38, v22, v154
	v_fmac_f32_e32 v39, v21, v156
	v_add_f32_e32 v37, v33, v37
	v_add_f32_e32 v38, v38, v39
	v_add_f32_e32 v37, v37, v38
	s_waitcnt lgkmcnt(1)
	v_mul_f32_e32 v38, v20, v159
	v_mul_f32_e32 v39, v27, v161
	v_fmac_f32_e32 v38, v17, v158
	v_fmac_f32_e32 v39, v18, v160
	v_add_f32_e32 v38, v38, v39
	v_add_f32_e32 v37, v37, v38
	s_waitcnt lgkmcnt(0)
	ds_read_b128 v[166:169], v35 offset:960
	ds_read_b128 v[170:173], v35 offset:976
	ds_read_b128 v[174:177], v35 offset:992
	ds_read_b128 v[178:181], v35 offset:1008
	v_mul_f32_e32 v38, v19, v163
	v_mul_f32_e32 v39, v26, v165
	v_fmac_f32_e32 v38, v16, v162
	v_fmac_f32_e32 v39, v24, v164
	v_add_f32_e32 v38, v38, v39
	v_add_f32_e32 v37, v37, v38
	v_mul_f32_e64 v38, |v37|, s83
	v_exp_f32_e32 v38, v38
	v_min_f32_e32 v37, 0, v37
	v_add_f32_e32 v38, 1.0, v38
	v_cmp_gt_f32_e32 vcc, s84, v38
	s_nop 1
	v_cndmask_b32_e64 v39, 0, 32, vcc
	v_ldexp_f32 v38, v38, v39
	v_log_f32_e32 v38, v38
	s_nop 0
	v_mul_f32_e32 v39, 0x3f317217, v38
	v_fma_f32 v39, v38, s85, -v39
	v_fmac_f32_e32 v39, 0x3377d1cf, v38
	v_fmac_f32_e32 v39, 0x3f317217, v38
	v_cmp_lt_f32_e64 s[36:37], |v38|, s86
	s_nop 1
	v_cndmask_b32_e64 v38, v38, v39, s[36:37]
	v_cndmask_b32_e32 v39, 0, v95, vcc
	v_sub_f32_e32 v38, v38, v39
	v_sub_f32_e32 v37, v37, v38
	v_fmac_f32_e32 v36, 0x3d800000, v37
	ds_write_b32 v23, v36 offset:7392
	s_waitcnt lgkmcnt(3)
	v_mul_f32_e32 v32, v32, v167
	v_fmac_f32_e32 v32, v30, v166
	v_mul_f32_e32 v30, v31, v169
	s_waitcnt lgkmcnt(2)
	v_mul_f32_e32 v25, v25, v171
	s_waitcnt lgkmcnt(1)
	v_mul_f32_e32 v20, v20, v175
	v_fmac_f32_e32 v30, v29, v168
	v_fmac_f32_e32 v25, v22, v170
	v_mul_f32_e32 v22, v28, v173
	v_fmac_f32_e32 v20, v17, v174
	v_mul_f32_e32 v17, v27, v177
	v_add_f32_e32 v29, v32, v30
	v_fmac_f32_e32 v22, v21, v172
	v_fmac_f32_e32 v17, v18, v176
	s_waitcnt lgkmcnt(0)
	v_mul_f32_e32 v18, v19, v179
	v_add_f32_e32 v29, v33, v29
	v_add_f32_e32 v21, v25, v22
	v_fmac_f32_e32 v18, v16, v178
	v_mul_f32_e32 v16, v26, v181
	v_add_f32_e32 v21, v29, v21
	v_add_f32_e32 v17, v20, v17
	v_fmac_f32_e32 v16, v24, v180
	v_add_f32_e32 v17, v21, v17
	v_add_f32_e32 v16, v18, v16
	v_add_f32_e32 v16, v17, v16
	v_mul_f32_e64 v17, |v16|, s83
	v_exp_f32_e32 v17, v17
	v_min_f32_e32 v16, 0, v16
	v_add_f32_e32 v17, 1.0, v17
	v_cmp_gt_f32_e32 vcc, s84, v17
	s_nop 1
	v_cndmask_b32_e64 v18, 0, 32, vcc
	v_ldexp_f32 v17, v17, v18
	v_log_f32_e32 v17, v17
	s_nop 0
	v_mul_f32_e32 v18, 0x3f317217, v17
	v_fma_f32 v18, v17, s85, -v18
	v_fmac_f32_e32 v18, 0x3377d1cf, v17
	v_fmac_f32_e32 v18, 0x3f317217, v17
	v_cmp_lt_f32_e64 s[36:37], |v17|, s86
	s_nop 1
	v_cndmask_b32_e64 v17, v17, v18, s[36:37]
	v_cndmask_b32_e32 v18, 0, v95, vcc
	v_sub_f32_e32 v17, v17, v18
	v_sub_f32_e32 v16, v16, v17
	s_cselect_b64 s[36:37], -1, 0
	v_fmac_f32_e32 v36, 0x3d800000, v16
	s_and_b64 vcc, exec, s[36:37]
	v_mov_b32_e32 v16, 0
	ds_write_b32 v23, v36 offset:7920
	s_waitcnt lgkmcnt(0)
	s_barrier
	s_cbranch_vccz .LBB0_385
	ds_read_b32 v16, v34 offset:7920
	s_waitcnt lgkmcnt(0)
	v_add_f32_e32 v16, 0, v16

; #define LAS __attribute__((address_space(3)))
; __device__ __forceinline__ unsigned pk2(float lo, float hi) { return f2bf(lo) | (f2bf(hi) << 16); }
; __device__ __forceinline__ void gla_load_vt(const bf16* GVc, LAS bf16* VTl, int wave, int lane) {
;     u32x4 vv[4];
; #pragma unroll
;     for (int i = 0; i < 4; ++i) vv[i] = *(const u32x4*)(GVc + (size_t)lane * 1024 + (wave + 8 * i) * 8);
; #pragma unroll
;     for (int i = 0; i < 4; ++i) { const int v0 = (wave + 8 * i) * 8; LAS bf16* p = VTl + v0 * 72 + lane;
;         p[0] = (bf16)(vv[i].x & 0xffff); p[72] = (bf16)(vv[i].x >> 16); p[144] = (bf16)(vv[i].y & 0xffff); p[216] = (bf16)(vv[i].y >> 16);
;         p[288] = (bf16)(vv[i].z & 0xffff); p[360] = (bf16)(vv[i].z >> 16); p[432] = (bf16)(vv[i].w & 0xffff); p[504] = (bf16)(vv[i].w >> 16); }
; }
; __device__ __forceinline__ void gla_out(const Ptrs& A, int l, LAS unsigned char* lds, int c, int G, int wave, int lane_, const int wv0) {
;     ...
;         for (int i = 0; i < 2; ++i) { const int d0 = (wave + 8 * i) * 8; float xq[8], xk[8]; unpack8(qq[i], xq); unpack8(kk[i], xk);
;             const f32x4 b0 = *(const LAS f32x4*)(bl + lane * BLS + d0), b1 = *(const LAS f32x4*)(bl + lane * BLS + d0 + 4);
;             float eb[8]; eb[0] = __expf(b0.x); eb[1] = __expf(b0.y); eb[2] = __expf(b0.z); eb[3] = __expf(b0.w); eb[4] = __expf(b1.x); eb[5] = __expf(b1.y); eb[6] = __expf(b1.z); eb[7] = __expf(b1.w);
;             u32x4 oq, ok;
;             oq.x = pk2(xq[0] * 0.08838834764831845f * eb[0], xq[1] * 0.08838834764831845f * eb[1]); oq.y = pk2(xq[2] * 0.08838834764831845f * eb[2], xq[3] * 0.08838834764831845f * eb[3]);
;             oq.z = pk2(xq[4] * 0.08838834764831845f * eb[4], xq[5] * 0.08838834764831845f * eb[5]); oq.w = pk2(xq[6] * 0.08838834764831845f * eb[6], xq[7] * 0.08838834764831845f * eb[7]);
;             ok.x = pk2(xk[0] * __builtin_amdgcn_rcpf(eb[0]), xk[1] * __builtin_amdgcn_rcpf(eb[1])); ok.y = pk2(xk[2] * __builtin_amdgcn_rcpf(eb[2]), xk[3] * __builtin_amdgcn_rcpf(eb[3]));
;             ok.z = pk2(xk[4] * __builtin_amdgcn_rcpf(eb[4]), xk[5] * __builtin_amdgcn_rcpf(eb[5])); ok.w = pk2(xk[6] * __builtin_amdgcn_rcpf(eb[6]), xk[7] * __builtin_amdgcn_rcpf(eb[7]));
;             *(LAS u32x4*)(QE + lane * 136 + d0) = oq; *(LAS u32x4*)(KE + lane * 136 + d0) = ok; }
.LBB0_391:
	s_ashr_i32 s67, s66, 31
	s_lshl_b64 s[36:37], s[66:67], 11
	s_add_u32 s36, s65, s36
	s_addc_u32 s37, s68, s37
	s_add_u32 s36, s36, s40
	s_addc_u32 s37, s37, 0
	v_mov_b32_e32 v59, v49
	v_lshl_add_u64 v[16:17], s[36:37], 0, v[58:59]
	v_lshl_add_u64 v[28:29], s[54:55], 1, v[16:17]
	s_waitcnt lgkmcnt(0)
	s_barrier
	global_load_dwordx4 v[16:19], v[28:29], off
	global_load_dwordx4 v[20:23], v[28:29], off offset:128
	global_load_dwordx4 v[24:27], v[28:29], off offset:256
	s_nop 0
	global_load_dwordx4 v[28:31], v[28:29], off offset:384
	s_waitcnt vmcnt(4)
	v_add_u32_e32 v44, s69, v63
	v_add_u32_e32 v45, s70, v63
	v_lshlrev_b32_e32 v33, 16, v13
	v_lshlrev_b32_e32 v32, 16, v12
	v_and_b32_e32 v13, 0xffff0000, v13
	v_and_b32_e32 v12, 0xffff0000, v12
	v_lshlrev_b32_e32 v35, 16, v15
	v_lshlrev_b32_e32 v34, 16, v14
	v_and_b32_e32 v15, 0xffff0000, v15
	v_and_b32_e32 v14, 0xffff0000, v14
	v_lshlrev_b32_e32 v37, 16, v9
	v_lshlrev_b32_e32 v36, 16, v8
	v_and_b32_e32 v39, 0xffff0000, v9
	v_and_b32_e32 v38, 0xffff0000, v8
	v_lshlrev_b32_e32 v41, 16, v11
	v_lshlrev_b32_e32 v40, 16, v10
	v_and_b32_e32 v43, 0xffff0000, v11
	v_and_b32_e32 v42, 0xffff0000, v10
	v_pk_mul_f32 v[32:33], v[32:33], s[64:65] op_sel_hi:[1,0]
	s_andn2_b64 vcc, exec, s[58:59]
	s_waitcnt vmcnt(3)
	ds_write_b16 v44, v16
	ds_write_b16_d16_hi v44, v16 offset:144
	ds_write_b16 v44, v17 offset:288
	ds_write_b16_d16_hi v44, v17 offset:432
	ds_write_b16 v44, v18 offset:576
	ds_write_b16_d16_hi v44, v18 offset:720
	ds_write_b16 v44, v19 offset:864
	ds_write_b16_d16_hi v44, v19 offset:1008
	s_waitcnt vmcnt(2)
	ds_write_b16 v45, v20
	ds_write_b16_d16_hi v45, v20 offset:144
	ds_write_b16 v45, v21 offset:288
	ds_write_b16_d16_hi v45, v21 offset:432
	ds_write_b16 v45, v22 offset:576
	ds_write_b16_d16_hi v45, v22 offset:720
	ds_write_b16 v45, v23 offset:864
	ds_write_b16_d16_hi v45, v23 offset:1008
	s_waitcnt vmcnt(1)
	ds_write_b16 v45, v24 offset:9216
	ds_write_b16_d16_hi v45, v24 offset:9360
	ds_write_b16 v45, v25 offset:9504
	ds_write_b16_d16_hi v45, v25 offset:9648
	ds_write_b16 v45, v26 offset:9792
	ds_write_b16_d16_hi v45, v26 offset:9936
	ds_write_b16 v45, v27 offset:10080
	ds_write_b16_d16_hi v45, v27 offset:10224
	s_waitcnt vmcnt(0)
	ds_write_b16 v45, v28 offset:18432
	ds_write_b16_d16_hi v45, v28 offset:18576
	ds_write_b16 v45, v29 offset:18720
	ds_write_b16_d16_hi v45, v29 offset:18864
	ds_write_b16 v45, v30 offset:19008
	ds_write_b16_d16_hi v45, v30 offset:19152
	ds_write_b16 v45, v31 offset:19296
	ds_write_b16_d16_hi v45, v31 offset:19440
	ds_read_b128 v[8:11], v72
	v_pk_mul_f32 v[16:17], v[12:13], s[64:65] op_sel_hi:[1,0]
	v_pk_mul_f32 v[20:21], v[14:15], s[64:65] op_sel_hi:[1,0]
	ds_read_b128 v[12:15], v72 offset:16
	v_pk_mul_f32 v[18:19], v[34:35], s[64:65] op_sel_hi:[1,0]
	s_waitcnt lgkmcnt(1)
	v_mul_f32_e32 v9, 0x3fb8aa3b, v9
	v_mul_f32_e32 v11, 0x3fb8aa3b, v11
	v_mul_f32_e32 v10, 0x3fb8aa3b, v10
	s_waitcnt lgkmcnt(0)
	v_mul_f32_e32 v22, 0x3fb8aa3b, v12
	v_mul_f32_e32 v23, 0x3fb8aa3b, v13
	v_mul_f32_e32 v25, 0x3fb8aa3b, v14
	v_mul_f32_e32 v26, 0x3fb8aa3b, v15
	v_exp_f32_e32 v14, v9
	v_exp_f32_e32 v15, v11
	v_exp_f32_e32 v22, v22
	v_exp_f32_e32 v24, v23
	v_exp_f32_e32 v23, v25
	v_exp_f32_e32 v25, v26
	v_mul_f32_e32 v8, 0x3fb8aa3b, v8
	v_exp_f32_e32 v13, v10
	v_pk_mul_f32 v[10:11], v[16:17], v[14:15]
	v_pk_mul_f32 v[16:17], v[18:19], v[22:23]
	v_pk_mul_f32 v[18:19], v[20:21], v[24:25]
	v_exp_f32_e32 v12, v8
	v_bfe_u32 v20, v19, 16, 1
	v_bfe_u32 v21, v18, 16, 1
	v_bfe_u32 v26, v11, 16, 1
	v_bfe_u32 v27, v10, 16, 1
	v_add3_u32 v27, v10, v27, s89
	v_add3_u32 v26, v11, v26, s89
	v_add3_u32 v10, v18, v21, s89
	v_add3_u32 v11, v19, v20, s89
	v_bfe_u32 v18, v16, 16, 1
	v_bfe_u32 v19, v17, 16, 1
	v_add3_u32 v17, v17, v19, s89
	v_add3_u32 v16, v16, v18, s89
	v_lshrrev_b32_e32 v16, 16, v16
	v_lshrrev_b32_e32 v17, 16, v17
	v_rcp_f32_e32 v14, v14
	v_rcp_f32_e32 v15, v15
	v_rcp_f32_e32 v18, v24
	v_rcp_f32_e32 v19, v25
	v_pk_mul_f32 v[8:9], v[32:33], v[12:13]
	v_and_or_b32 v11, v11, s88, v17
	v_and_or_b32 v10, v10, s88, v16
	v_rcp_f32_e32 v12, v12
	v_rcp_f32_e32 v13, v13
	v_rcp_f32_e32 v16, v22
	v_rcp_f32_e32 v17, v23
	v_pk_mul_f32 v[14:15], v[14:15], v[38:39]
	v_pk_mul_f32 v[18:19], v[18:19], v[42:43]
	v_bfe_u32 v28, v8, 16, 1
	v_bfe_u32 v29, v9, 16, 1
	v_pk_mul_f32 v[12:13], v[12:13], v[36:37]
	v_pk_mul_f32 v[16:17], v[16:17], v[40:41]
	v_bfe_u32 v20, v19, 16, 1
	v_bfe_u32 v21, v18, 16, 1
	v_bfe_u32 v22, v15, 16, 1
	v_bfe_u32 v23, v14, 16, 1
	v_add3_u32 v9, v9, v29, s89
	v_add3_u32 v8, v8, v28, s89
	v_add3_u32 v23, v14, v23, s89
	v_add3_u32 v22, v15, v22, s89
	v_add3_u32 v14, v18, v21, s89
	v_add3_u32 v15, v19, v20, s89
	v_bfe_u32 v18, v12, 16, 1
	v_bfe_u32 v19, v13, 16, 1
	v_bfe_u32 v20, v16, 16, 1
	v_bfe_u32 v21, v17, 16, 1
	v_lshrrev_b32_e32 v8, 16, v8
	v_lshrrev_b32_e32 v9, 16, v9
	v_add3_u32 v17, v17, v21, s89
	v_add3_u32 v16, v16, v20, s89
	v_add3_u32 v13, v13, v19, s89
	v_add3_u32 v12, v12, v18, s89
	v_and_or_b32 v9, v26, s88, v9
	v_and_or_b32 v8, v27, s88, v8
	v_lshrrev_b32_e32 v12, 16, v12
	v_lshrrev_b32_e32 v13, 16, v13
	v_lshrrev_b32_e32 v16, 16, v16
	v_lshrrev_b32_e32 v17, 16, v17
	v_and_or_b32 v15, v15, s88, v17
	v_and_or_b32 v14, v14, s88, v16
	v_and_or_b32 v13, v22, s88, v13
	v_and_or_b32 v12, v23, s88, v12
	ds_write_b128 v73, v[8:11] offset:33792
	ds_write_b128 v73, v[12:15] offset:51200
	v_lshlrev_b32_e32 v9, 16, v5
	v_lshlrev_b32_e32 v8, 16, v4
	v_and_b32_e32 v11, 0xffff0000, v5
	v_and_b32_e32 v10, 0xffff0000, v4
	v_lshlrev_b32_e32 v13, 16, v7
	v_lshlrev_b32_e32 v12, 16, v6
	v_and_b32_e32 v15, 0xffff0000, v7
	v_and_b32_e32 v14, 0xffff0000, v6
	ds_read_b128 v[4:7], v72 offset:256
	v_lshlrev_b32_e32 v17, 16, v1
	v_lshlrev_b32_e32 v16, 16, v0
	v_and_b32_e32 v19, 0xffff0000, v1
	v_and_b32_e32 v18, 0xffff0000, v0
	v_lshlrev_b32_e32 v21, 16, v3
	v_lshlrev_b32_e32 v20, 16, v2
	v_and_b32_e32 v23, 0xffff0000, v3
	v_and_b32_e32 v22, 0xffff0000, v2
	ds_read_b128 v[0:3], v72 offset:272
	s_waitcnt lgkmcnt(1)
; #define LAS __attribute__((address_space(3)))
; __device__ __forceinline__ unsigned f2bf(float f) { unsigned u = __builtin_bit_cast(unsigned, f); return (u + 0x7fffu + ((u >> 16) & 1u)) >> 16; }
; __device__ __forceinline__ void gla_out(const Ptrs& A, int l, LAS unsigned char* lds, int c, int G, int wave, int lane_, const int wv0) {
;     ...
;         for (int i = 0; i < 2; ++i) { const int d0 = (wave + 8 * i) * 8; float xq[8], xk[8]; unpack8(qq[i], xq); unpack8(kk[i], xk);
;             const f32x4 b0 = *(const LAS f32x4*)(bl + lane * BLS + d0), b1 = *(const LAS f32x4*)(bl + lane * BLS + d0 + 4);
;             float eb[8]; eb[0] = __expf(b0.x); eb[1] = __expf(b0.y); eb[2] = __expf(b0.z); eb[3] = __expf(b0.w); eb[4] = __expf(b1.x); eb[5] = __expf(b1.y); eb[6] = __expf(b1.z); eb[7] = __expf(b1.w);
;             u32x4 oq, ok;
;             oq.x = pk2(xq[0] * 0.08838834764831845f * eb[0], xq[1] * 0.08838834764831845f * eb[1]); oq.y = pk2(xq[2] * 0.08838834764831845f * eb[2], xq[3] * 0.08838834764831845f * eb[3]);
;             oq.z = pk2(xq[4] * 0.08838834764831845f * eb[4], xq[5] * 0.08838834764831845f * eb[5]); oq.w = pk2(xq[6] * 0.08838834764831845f * eb[6], xq[7] * 0.08838834764831845f * eb[7]);
;             ok.x = pk2(xk[0] * __builtin_amdgcn_rcpf(eb[0]), xk[1] * __builtin_amdgcn_rcpf(eb[1])); ok.y = pk2(xk[2] * __builtin_amdgcn_rcpf(eb[2]), xk[3] * __builtin_amdgcn_rcpf(eb[3]));
;             ok.z = pk2(xk[4] * __builtin_amdgcn_rcpf(eb[4]), xk[5] * __builtin_amdgcn_rcpf(eb[5])); ok.w = pk2(xk[6] * __builtin_amdgcn_rcpf(eb[6]), xk[7] * __builtin_amdgcn_rcpf(eb[7]));
;             *(LAS u32x4*)(QE + lane * 136 + d0) = oq; *(LAS u32x4*)(KE + lane * 136 + d0) = ok; }
;         __syncthreads();
;         if (wave < 4) { const int ti = wave >> 1, tj = wave & 1; f32x16 acc = {};
;             if (tj <= ti) {
; #pragma unroll
;                 for (int ks = 0; ks < 8; ++ks) { const bf16x8 a = *(const LAS bf16x8*)(QE + (32 * ti + r32) * 136 + 16 * ks + 8 * hi), b = *(const LAS bf16x8*)(KE + (32 * tj + r32) * 136 + 16 * ks + 8 * hi);
;                     acc = __builtin_amdgcn_mfma_f32_32x32x16_bf16(a, b, acc, 0, 0, 0); } }
; #pragma unroll
;             for (int r = 0; r < 16; ++r) { const int t = 32 * ti + crow(r, hi), sx = 32 * tj + r32; SM[t * 72 + sx] = (bf16)f2bf(sx <= t ? acc[r] : 0.f); } }
	v_mul_f32_e32 v5, 0x3fb8aa3b, v5
	v_exp_f32_e32 v24, v5
	v_mul_f32_e32 v5, 0x3fb8aa3b, v6
	v_mul_f32_e32 v6, 0x3fb8aa3b, v7
	s_waitcnt lgkmcnt(0)
	v_mul_f32_e32 v0, 0x3fb8aa3b, v0
	v_exp_f32_e32 v25, v6
	v_exp_f32_e32 v6, v0
	v_mul_f32_e32 v0, 0x3fb8aa3b, v1
	v_exp_f32_e32 v26, v0
	v_mul_f32_e32 v0, 0x3fb8aa3b, v2
	v_exp_f32_e32 v7, v0
	v_mul_f32_e32 v0, 0x3fb8aa3b, v3
	v_exp_f32_e32 v27, v0
	v_mul_f32_e32 v4, 0x3fb8aa3b, v4
	v_exp_f32_e32 v4, v4
	v_exp_f32_e32 v5, v5
	v_pk_mul_f32 v[2:3], v[10:11], s[64:65] op_sel_hi:[1,0]
	v_pk_mul_f32 v[10:11], v[14:15], s[64:65] op_sel_hi:[1,0]
	v_pk_mul_f32 v[0:1], v[8:9], s[64:65] op_sel_hi:[1,0]
	v_pk_mul_f32 v[2:3], v[2:3], v[24:25]
	v_pk_mul_f32 v[8:9], v[12:13], s[64:65] op_sel_hi:[1,0]
	v_pk_mul_f32 v[10:11], v[10:11], v[26:27]
	v_pk_mul_f32 v[8:9], v[8:9], v[6:7]
	v_bfe_u32 v12, v11, 16, 1
	v_bfe_u32 v13, v10, 16, 1
	v_bfe_u32 v14, v3, 16, 1
	v_bfe_u32 v15, v2, 16, 1
	v_add3_u32 v15, v2, v15, s89
	v_add3_u32 v14, v3, v14, s89
	v_add3_u32 v2, v10, v13, s89
	v_add3_u32 v3, v11, v12, s89
	v_bfe_u32 v12, v8, 16, 1
	v_bfe_u32 v13, v9, 16, 1
	v_pk_mul_f32 v[0:1], v[0:1], v[4:5]
	v_add3_u32 v9, v9, v13, s89
	v_add3_u32 v8, v8, v12, s89
	v_bfe_u32 v10, v0, 16, 1
	v_bfe_u32 v11, v1, 16, 1
	v_lshrrev_b32_e32 v8, 16, v8
	v_lshrrev_b32_e32 v9, 16, v9
	v_add3_u32 v1, v1, v11, s89
	v_add3_u32 v0, v0, v10, s89
	v_and_or_b32 v3, v3, s88, v9
	v_and_or_b32 v2, v2, s88, v8
	v_rcp_f32_e32 v8, v24
	v_rcp_f32_e32 v9, v25
	v_rcp_f32_e32 v10, v26
	v_rcp_f32_e32 v11, v27
	v_rcp_f32_e32 v4, v4
	v_rcp_f32_e32 v5, v5
	v_rcp_f32_e32 v6, v6
	v_rcp_f32_e32 v7, v7
	v_lshrrev_b32_e32 v0, 16, v0
	v_lshrrev_b32_e32 v1, 16, v1
	v_pk_mul_f32 v[8:9], v[8:9], v[18:19]
	v_pk_mul_f32 v[10:11], v[10:11], v[22:23]
	v_and_or_b32 v1, v14, s88, v1
	v_and_or_b32 v0, v15, s88, v0
	v_pk_mul_f32 v[4:5], v[4:5], v[16:17]
	v_pk_mul_f32 v[6:7], v[6:7], v[20:21]
	v_bfe_u32 v12, v11, 16, 1
	v_bfe_u32 v13, v10, 16, 1
	v_bfe_u32 v14, v9, 16, 1
	v_bfe_u32 v15, v8, 16, 1
	v_add3_u32 v8, v8, v15, s89
	v_add3_u32 v9, v9, v14, s89
	v_add3_u32 v10, v10, v13, s89
	v_add3_u32 v11, v11, v12, s89
	v_bfe_u32 v12, v4, 16, 1
	v_bfe_u32 v13, v5, 16, 1
	v_bfe_u32 v14, v6, 16, 1
	v_bfe_u32 v15, v7, 16, 1
	v_add3_u32 v7, v7, v15, s89
	v_add3_u32 v6, v6, v14, s89
	v_add3_u32 v5, v5, v13, s89
	v_add3_u32 v4, v4, v12, s89
	v_lshrrev_b32_e32 v4, 16, v4
	v_lshrrev_b32_e32 v5, 16, v5
	v_lshrrev_b32_e32 v6, 16, v6
	v_lshrrev_b32_e32 v7, 16, v7
	v_and_or_b32 v7, v11, s88, v7
	v_and_or_b32 v6, v10, s88, v6
	v_and_or_b32 v5, v9, s88, v5
	v_and_or_b32 v4, v8, s88, v4
	ds_write_b128 v73, v[0:3] offset:33920
	ds_write_b128 v73, v[4:7] offset:51328
	s_waitcnt lgkmcnt(0)
	s_barrier
	s_cbranch_vccnz .LBB0_395
	v_mov_b32_e32 v0, 0
	s_andn2_b64 vcc, exec, s[60:61]
	v_mov_b32_e32 v1, 0
	v_mov_b32_e32 v2, 0
	v_mov_b32_e32 v3, 0
	v_mov_b32_e32 v4, 0
	v_mov_b32_e32 v5, 0
	v_mov_b32_e32 v6, 0
	v_mov_b32_e32 v7, 0
	v_mov_b32_e32 v8, 0
	v_mov_b32_e32 v9, 0
	v_mov_b32_e32 v10, 0
	v_mov_b32_e32 v11, 0
	v_mov_b32_e32 v12, 0
	v_mov_b32_e32 v13, 0
	v_mov_b32_e32 v14, 0
	v_mov_b32_e32 v15, 0
	s_cbranch_vccnz .LBB0_394
	ds_read_b128 v[0:3], v65 offset:33792
	ds_read_b128 v[4:7], v66 offset:51200
	ds_read_b128 v[16:19], v65 offset:33824
	ds_read_b128 v[20:23], v66 offset:51232
	s_waitcnt lgkmcnt(2)
	v_mfma_f32_32x32x16_bf16 v[0:15], v[0:3], v[4:7], 0
	s_waitcnt lgkmcnt(0)
	v_mfma_f32_32x32x16_bf16 v[0:15], v[16:19], v[20:23], v[0:15]
	ds_read_b128 v[16:19], v65 offset:33856
	ds_read_b128 v[20:23], v66 offset:51264
	ds_read_b128 v[24:27], v65 offset:33888
	ds_read_b128 v[28:31], v66 offset:51296
	s_waitcnt lgkmcnt(2)
	v_mfma_f32_32x32x16_bf16 v[0:15], v[16:19], v[20:23], v[0:15]
	s_waitcnt lgkmcnt(0)
	v_mfma_f32_32x32x16_bf16 v[0:15], v[24:27], v[28:31], v[0:15]
	ds_read_b128 v[16:19], v65 offset:33920
	ds_read_b128 v[20:23], v66 offset:51328
	ds_read_b128 v[24:27], v65 offset:33952
	ds_read_b128 v[28:31], v66 offset:51360
	s_waitcnt lgkmcnt(2)
	v_mfma_f32_32x32x16_bf16 v[0:15], v[16:19], v[20:23], v[0:15]
	s_waitcnt lgkmcnt(0)
	v_mfma_f32_32x32x16_bf16 v[0:15], v[24:27], v[28:31], v[0:15]
	ds_read_b128 v[16:19], v65 offset:33984
	ds_read_b128 v[20:23], v66 offset:51392
	ds_read_b128 v[24:27], v65 offset:34016
	ds_read_b128 v[28:31], v66 offset:51424
	s_waitcnt lgkmcnt(2)
	v_mfma_f32_32x32x16_bf16 v[0:15], v[16:19], v[20:23], v[0:15]
	s_waitcnt lgkmcnt(0)
	v_mfma_f32_32x32x16_bf16 v[0:15], v[24:27], v[28:31], v[0:15]

; #define LAS __attribute__((address_space(3)))
; #define TID() (wv0 * 64 + (int)__builtin_amdgcn_mbcnt_hi(~0u, __builtin_amdgcn_mbcnt_lo(~0u, 0u)))
; __device__ __forceinline__ int opaque(int x) { asm volatile("" : "+v"(x)); return x; }
;     __device__ __forceinline__ const float* in(int k) const { return (const float*)(const __attribute__((address_space(1))) float*)get(k); }
;     __device__ __forceinline__ unsigned char* ws() const { return (unsigned char*)(__attribute__((address_space(1))) unsigned char*)get(21); }
; __device__ __forceinline__ void gla_cumdecay(const Ptrs& A, int l, int n, int hd, LAS float* bl, const int wv0) {
;     const int tid = opaque(TID()), d = tid & 127, tq = __builtin_amdgcn_readfirstlane(tid >> 7);
;     const float* wa2 = A.in(4) + (size_t)l * 16 * 512 + hd * 128 + d;
;     float w[16];
; #pragma unroll
;     for (int r = 0; r < 16; ++r) w[r] = wa2[r * 512];
;     const float bias = A.in(5)[(size_t)l * 512 + hd * 128 + d];
;     LAS float* gal = bl + 29184;
;     *(LAS f32x2*)(gal + 2 * tid) = *(const f32x2*)((const float*)(A.ws() + WS_GA1) + (size_t)n * 64 * 16 + 2 * tid);
;     __syncthreads();
;     const LAS float* ga = gal + 16 * tq * 16;
;     float run = 0.f;
;     for (int tt = 0; tt < 16; ++tt) {
;         float pre = bias;
;         const f32x4 g0 = *(const LAS f32x4*)(ga + tt * 16), g1 = *(const LAS f32x4*)(ga + tt * 16 + 4), g2 = *(const LAS f32x4*)(ga + tt * 16 + 8), g3 = *(const LAS f32x4*)(ga + tt * 16 + 12);
;         pre += (g0.x * w[0] + g0.y * w[1]) + (g0.z * w[2] + g0.w * w[3]); pre += (g1.x * w[4] + g1.y * w[5]) + (g1.z * w[6] + g1.w * w[7]);
;         pre += (g2.x * w[8] + g2.y * w[9]) + (g2.z * w[10] + g2.w * w[11]); pre += (g3.x * w[12] + g3.y * w[13]) + (g3.z * w[14] + g3.w * w[15]);
;         const float la = (fminf(pre, 0.f) - __logf(1.0f + __expf(-fabsf(pre)))) * (1.0f / 16.0f);
;         run += la; bl[(16 * tq + tt) * BLS + d] = run;
;     }
; __device__ __forceinline__ void gla_state(const Ptrs& A, int l, LAS unsigned char* lds, int c, int G, int wave, int lane_, const int wv0) {
;     ...
;     for (int it = c; it < 1024; it += G) {
;         const int n = it >> 2, hd = it & 3, t0 = n * 64;
;         u32x4 kk[2];
; #pragma unroll
;         for (int i = 0; i < 2; ++i) kk[i] = *(const u32x4*)(GK + (size_t)(t0 + lane) * 512 + hd * 128 + (wave + 8 * i) * 8);
;         gla_cumdecay(A, l, n, hd, bl, wv0);
.LBB0_1158:
	s_ashr_i32 s2, s6, 2
	s_lshl_b32 s22, s2, 6
	v_or_b32_e32 v0, s22, v64
	v_ashrrev_i32_e32 v1, 31, v0
	s_and_b32 s3, s6, 3
	v_lshlrev_b64 v[0:1], 10, v[0:1]
	v_lshl_add_u64 v[0:1], s[10:11], 0, v[0:1]
	s_lshl_b32 s14, s3, 8
	v_lshl_add_u64 v[0:1], v[0:1], 0, s[14:15]
	v_lshl_add_u64 v[0:1], s[12:13], 1, v[0:1]
	v_mov_b32_e32 v34, v204
	v_mov_b32_e32 v198, v0
	v_mov_b32_e32 v199, v1
	v_mov_b32 v8, s77
	ds_read_b64 v[8:9], v8 offset:32
	s_lshl_b32 s14, s3, 9
	v_readfirstlane_b32 s3, v34
	s_waitcnt lgkmcnt(0)
	v_readfirstlane_b32 s49, v8
	v_readfirstlane_b32 s23, v9
	s_add_u32 s50, s49, s14
	v_lshlrev_b32_e32 v8, 2, v34
	s_addc_u32 s51, s23, 0
	v_and_b32_e32 v48, 0x1fc, v8
	v_lshl_add_u64 v[8:9], s[50:51], 0, v[48:49]
	v_add_co_u32_e32 v12, vcc, s5, v8
	v_lshl_add_u64 v[10:11], v[8:9], 0, s[20:21]
	s_nop 0
	v_addc_co_u32_e32 v13, vcc, 0, v9, vcc
	v_add_co_u32_e32 v16, vcc, s7, v8
	s_ashr_i32 s23, s3, 7
	s_nop 0
	v_addc_co_u32_e32 v17, vcc, 0, v9, vcc
	v_add_co_u32_e32 v24, vcc, s30, v8
	s_nop 1
	v_addc_co_u32_e32 v25, vcc, 0, v9, vcc
	v_add_co_u32_e32 v26, vcc, s31, v8
	s_nop 1
	v_addc_co_u32_e32 v27, vcc, 0, v9, vcc
	v_add_co_u32_e32 v28, vcc, s34, v8
	s_nop 1
	v_addc_co_u32_e32 v29, vcc, 0, v9, vcc
	v_add_co_u32_e32 v30, vcc, s35, v8
	s_nop 1
	v_addc_co_u32_e32 v31, vcc, 0, v9, vcc
	v_add_co_u32_e32 v32, vcc, s36, v8
	s_nop 1
	v_addc_co_u32_e32 v33, vcc, 0, v9, vcc
	global_load_dword v20, v[12:13], off offset:-4096
	global_load_dword v23, v[10:11], off offset:2048
	global_load_dword v18, v[12:13], off
	global_load_dword v22, v[12:13], off offset:2048
	global_load_dword v15, v[24:25], off offset:-4096
	global_load_dword v19, v[16:17], off offset:2048
	s_nop 0
	global_load_dword v10, v[26:27], off offset:2048
	global_load_dword v8, v[30:31], off offset:2048
	global_load_dword v21, v[24:25], off
	s_nop 0
	global_load_dword v24, v[24:25], off offset:2048
	s_nop 0
	global_load_dword v16, v[28:29], off offset:-4096
	global_load_dword v14, v[28:29], off
	global_load_dword v17, v[28:29], off offset:2048
	global_load_dword v11, v[32:33], off offset:-4096
	global_load_dword v9, v[32:33], off
	global_load_dword v12, v[32:33], off offset:2048
	v_mov_b32 v13, s77
	ds_read_b64 v[26:27], v13 offset:40
	s_waitcnt lgkmcnt(0)
	v_readfirstlane_b32 s49, v26
	v_readfirstlane_b32 s3, v27
	s_add_u32 s50, s49, s14
	s_addc_u32 s51, s3, 0
	global_load_dword v25, v48, s[50:51] offset:2048
	v_mov_b32 v13, s77
	ds_read_b64 v[26:27], v13 offset:168
	s_ashr_i32 s3, s2, 31
	s_lshl_b64 s[2:3], s[2:3], 12
	v_lshl_add_u32 v13, v34, 3, s38
	s_waitcnt lgkmcnt(0)
	v_readfirstlane_b32 s50, v26
	v_readfirstlane_b32 s49, v27
	s_add_u32 s2, s50, s2
	v_lshlrev_b32_e32 v26, 1, v34
	s_addc_u32 s3, s49, s3
	v_ashrrev_i32_e32 v27, 31, v26
	v_lshl_add_u64 v[26:27], v[26:27], 2, s[2:3]
	v_add_co_u32_e32 v26, vcc, s37, v26
	s_lshl_b32 s2, s23, 10
	s_nop 0
	v_addc_co_u32_e32 v27, vcc, 0, v27, vcc
	global_load_dwordx2 v[28:29], v[26:27], off
	s_add_i32 s2, s38, s2
	v_mov_b32_e32 v27, s2
	s_mul_i32 s2, s23, 0x2100
	s_cmp_gt_i32 s23, 0
	global_load_dwordx4 v[4:7], v[198:199], off
	global_load_dwordx4 v[0:3], v[198:199], off offset:128
	s_waitcnt vmcnt(2)
	ds_write_b64 v13, v[28:29]
	s_waitcnt lgkmcnt(0)
	s_barrier
	ds_read_b128 v[28:31], v27
	ds_read_b128 v[32:35], v27 offset:16
	ds_read_b128 v[36:39], v27 offset:32
	ds_read_b128 v[40:43], v27 offset:48
	s_waitcnt lgkmcnt(3)
	v_mul_f32_e32 v13, v23, v29
	v_mul_f32_e32 v26, v22, v31
	s_waitcnt lgkmcnt(2)
	v_mul_f32_e32 v29, v19, v33
	v_mul_f32_e32 v31, v24, v35
	v_fmac_f32_e32 v13, v20, v28
	v_fmac_f32_e32 v26, v18, v30
	s_waitcnt lgkmcnt(1)
	v_mul_f32_e32 v33, v10, v37
	v_mul_f32_e32 v35, v17, v39
	v_fmac_f32_e32 v29, v15, v32
	v_fmac_f32_e32 v31, v21, v34
	v_add_f32_e32 v13, v13, v26
	s_waitcnt lgkmcnt(0)
	ds_read_b128 v[166:169], v27 offset:64
	ds_read_b128 v[170:173], v27 offset:80
	ds_read_b128 v[174:177], v27 offset:96
	ds_read_b128 v[178:181], v27 offset:112
	v_mul_f32_e32 v37, v8, v41
	v_mul_f32_e32 v39, v12, v43
	v_fmac_f32_e32 v33, v16, v36
	v_fmac_f32_e32 v35, v14, v38
	v_add_f32_e32 v26, v29, v31
	v_add_f32_e32 v13, v25, v13
	v_fmac_f32_e32 v37, v11, v40
	v_fmac_f32_e32 v39, v9, v42
	v_add_f32_e32 v28, v33, v35
	v_add_f32_e32 v13, v13, v26
	v_add_f32_e32 v29, v37, v39
	v_add_f32_e32 v13, v13, v28
	v_add_f32_e32 v28, v13, v29
	v_mul_f32_e64 v13, |v28|, s39
	v_exp_f32_e32 v13, v13
	v_min_f32_e32 v28, 0, v28
	v_add_u32_e32 v26, 0, v48
	v_add_f32_e32 v13, 1.0, v13
	v_cmp_gt_f32_e32 vcc, s40, v13
	s_nop 1
	v_cndmask_b32_e64 v29, 0, 32, vcc
	v_ldexp_f32 v13, v13, v29
	v_log_f32_e32 v29, v13
	v_cndmask_b32_e32 v30, 0, v69, vcc
	v_add_u32_e32 v13, s2, v26
	v_mul_f32_e32 v31, 0x3f317217, v29
	v_fma_f32 v31, v29, s41, -v31
	v_fmac_f32_e32 v31, 0x3377d1cf, v29
	v_fmac_f32_e32 v31, 0x3f317217, v29
	v_cmp_lt_f32_e64 vcc, |v29|, s44
	s_nop 1
	v_cndmask_b32_e32 v29, v29, v31, vcc
	v_sub_f32_e32 v29, v29, v30
	v_sub_f32_e32 v28, v28, v29
	v_fma_f32 v28, v28, s45, 0
	ds_write_b32 v13, v28
	s_waitcnt lgkmcnt(3)
	v_mul_f32_e32 v29, v23, v167
	v_mul_f32_e32 v31, v22, v169
	v_fmac_f32_e32 v29, v20, v166
	v_fmac_f32_e32 v31, v18, v168
	v_add_f32_e32 v29, v29, v31
	s_waitcnt lgkmcnt(2)
	v_mul_f32_e32 v30, v19, v171
	v_mul_f32_e32 v31, v24, v173
	v_fmac_f32_e32 v30, v15, v170
	v_fmac_f32_e32 v31, v21, v172
	v_add_f32_e32 v29, v25, v29
	v_add_f32_e32 v30, v30, v31
	v_add_f32_e32 v29, v29, v30
	s_waitcnt lgkmcnt(1)
	v_mul_f32_e32 v30, v10, v175
	v_mul_f32_e32 v31, v17, v177
	v_fmac_f32_e32 v30, v16, v174
	v_fmac_f32_e32 v31, v14, v176
	v_add_f32_e32 v30, v30, v31
	v_add_f32_e32 v29, v29, v30
	s_waitcnt lgkmcnt(0)
; #define LAS __attribute__((address_space(3)))
; __device__ __forceinline__ void gla_cumdecay(const Ptrs& A, int l, int n, int hd, LAS float* bl, const int wv0) {
;     ...
;     const LAS float* ga = gal + 16 * tq * 16;
;     float run = 0.f;
;     for (int tt = 0; tt < 16; ++tt) {
;         float pre = bias;
;         const f32x4 g0 = *(const LAS f32x4*)(ga + tt * 16), g1 = *(const LAS f32x4*)(ga + tt * 16 + 4), g2 = *(const LAS f32x4*)(ga + tt * 16 + 8), g3 = *(const LAS f32x4*)(ga + tt * 16 + 12);
;         pre += (g0.x * w[0] + g0.y * w[1]) + (g0.z * w[2] + g0.w * w[3]); pre += (g1.x * w[4] + g1.y * w[5]) + (g1.z * w[6] + g1.w * w[7]);
;         pre += (g2.x * w[8] + g2.y * w[9]) + (g2.z * w[10] + g2.w * w[11]); pre += (g3.x * w[12] + g3.y * w[13]) + (g3.z * w[14] + g3.w * w[15]);
;         const float la = (fminf(pre, 0.f) - __logf(1.0f + __expf(-fabsf(pre)))) * (1.0f / 16.0f);
;         run += la; bl[(16 * tq + tt) * BLS + d] = run;
;     }
	ds_read_b128 v[150:153], v27 offset:128
	ds_read_b128 v[154:157], v27 offset:144
	ds_read_b128 v[158:161], v27 offset:160
	ds_read_b128 v[162:165], v27 offset:176
	v_mul_f32_e32 v30, v8, v179
	v_mul_f32_e32 v31, v12, v181
	v_fmac_f32_e32 v30, v11, v178
	v_fmac_f32_e32 v31, v9, v180
	v_add_f32_e32 v30, v30, v31
	v_add_f32_e32 v29, v29, v30
	v_mul_f32_e64 v30, |v29|, s39
	v_exp_f32_e32 v30, v30
	v_min_f32_e32 v29, 0, v29
	v_add_f32_e32 v30, 1.0, v30
	v_cmp_gt_f32_e32 vcc, s40, v30
	s_nop 1
	v_cndmask_b32_e64 v31, 0, 32, vcc
	v_ldexp_f32 v30, v30, v31
	v_log_f32_e32 v30, v30
	s_nop 0
	v_mul_f32_e32 v31, 0x3f317217, v30
	v_fma_f32 v31, v30, s41, -v31
	v_fmac_f32_e32 v31, 0x3377d1cf, v30
	v_fmac_f32_e32 v31, 0x3f317217, v30
	v_cmp_lt_f32_e64 s[2:3], |v30|, s44
	s_nop 1
	v_cndmask_b32_e64 v30, v30, v31, s[2:3]
	v_cndmask_b32_e32 v31, 0, v69, vcc
	v_sub_f32_e32 v30, v30, v31
	v_sub_f32_e32 v29, v29, v30
	v_fmac_f32_e32 v28, 0x3d800000, v29
	ds_write_b32 v13, v28 offset:528
	s_waitcnt lgkmcnt(3)
	v_mul_f32_e32 v29, v23, v151
	v_fmac_f32_e32 v29, v20, v150
	v_mul_f32_e32 v30, v22, v153
	v_fmac_f32_e32 v30, v18, v152
	v_add_f32_e32 v29, v29, v30
	s_waitcnt lgkmcnt(2)
	v_mul_f32_e32 v30, v19, v155
	v_mul_f32_e32 v31, v24, v157
	v_fmac_f32_e32 v30, v15, v154
	v_fmac_f32_e32 v31, v21, v156
	v_add_f32_e32 v29, v25, v29
	v_add_f32_e32 v30, v30, v31
	v_add_f32_e32 v29, v29, v30
	s_waitcnt lgkmcnt(1)
	v_mul_f32_e32 v30, v10, v159
	v_mul_f32_e32 v31, v17, v161
	v_fmac_f32_e32 v30, v16, v158
	v_fmac_f32_e32 v31, v14, v160
	v_add_f32_e32 v30, v30, v31
	v_add_f32_e32 v29, v29, v30
	s_waitcnt lgkmcnt(0)
	ds_read_b128 v[166:169], v27 offset:192
	ds_read_b128 v[170:173], v27 offset:208
	ds_read_b128 v[174:177], v27 offset:224
	ds_read_b128 v[178:181], v27 offset:240
	v_mul_f32_e32 v30, v8, v163
	v_mul_f32_e32 v31, v12, v165
	v_fmac_f32_e32 v30, v11, v162
	v_fmac_f32_e32 v31, v9, v164
	v_add_f32_e32 v30, v30, v31
	v_add_f32_e32 v29, v29, v30
	v_mul_f32_e64 v30, |v29|, s39
	v_exp_f32_e32 v30, v30
	v_min_f32_e32 v29, 0, v29
	v_add_f32_e32 v30, 1.0, v30
	v_cmp_gt_f32_e32 vcc, s40, v30
	s_nop 1
	v_cndmask_b32_e64 v31, 0, 32, vcc
	v_ldexp_f32 v30, v30, v31
	v_log_f32_e32 v30, v30
	s_nop 0
	v_mul_f32_e32 v31, 0x3f317217, v30
	v_fma_f32 v31, v30, s41, -v31
	v_fmac_f32_e32 v31, 0x3377d1cf, v30
	v_fmac_f32_e32 v31, 0x3f317217, v30
	v_cmp_lt_f32_e64 s[2:3], |v30|, s44
	s_nop 1
	v_cndmask_b32_e64 v30, v30, v31, s[2:3]
	v_cndmask_b32_e32 v31, 0, v69, vcc
	v_sub_f32_e32 v30, v30, v31
	v_sub_f32_e32 v29, v29, v30
	v_fmac_f32_e32 v28, 0x3d800000, v29
	ds_write_b32 v13, v28 offset:1056
	s_waitcnt lgkmcnt(3)
	v_mul_f32_e32 v29, v23, v167
	v_fmac_f32_e32 v29, v20, v166
	v_mul_f32_e32 v30, v22, v169
	v_fmac_f32_e32 v30, v18, v168
	v_add_f32_e32 v29, v29, v30
	s_waitcnt lgkmcnt(2)
	v_mul_f32_e32 v30, v19, v171
	v_mul_f32_e32 v31, v24, v173
	v_fmac_f32_e32 v30, v15, v170
	v_fmac_f32_e32 v31, v21, v172
	v_add_f32_e32 v29, v25, v29
	v_add_f32_e32 v30, v30, v31
	v_add_f32_e32 v29, v29, v30
	s_waitcnt lgkmcnt(1)
	v_mul_f32_e32 v30, v10, v175
	v_mul_f32_e32 v31, v17, v177
	v_fmac_f32_e32 v30, v16, v174
	v_fmac_f32_e32 v31, v14, v176
	v_add_f32_e32 v30, v30, v31
	v_add_f32_e32 v29, v29, v30
	s_waitcnt lgkmcnt(0)
	ds_read_b128 v[150:153], v27 offset:256
	ds_read_b128 v[154:157], v27 offset:272
	ds_read_b128 v[158:161], v27 offset:288
	ds_read_b128 v[162:165], v27 offset:304
	v_mul_f32_e32 v30, v8, v179
	v_mul_f32_e32 v31, v12, v181
	v_fmac_f32_e32 v30, v11, v178
	v_fmac_f32_e32 v31, v9, v180
	v_add_f32_e32 v30, v30, v31
	v_add_f32_e32 v29, v29, v30
	v_mul_f32_e64 v30, |v29|, s39
	v_exp_f32_e32 v30, v30
	v_min_f32_e32 v29, 0, v29
	v_add_f32_e32 v30, 1.0, v30
	v_cmp_gt_f32_e32 vcc, s40, v30
	s_nop 1
	v_cndmask_b32_e64 v31, 0, 32, vcc
	v_ldexp_f32 v30, v30, v31
	v_log_f32_e32 v30, v30
	s_nop 0
	v_mul_f32_e32 v31, 0x3f317217, v30
	v_fma_f32 v31, v30, s41, -v31
	v_fmac_f32_e32 v31, 0x3377d1cf, v30
	v_fmac_f32_e32 v31, 0x3f317217, v30
	v_cmp_lt_f32_e64 s[2:3], |v30|, s44
	s_nop 1
	v_cndmask_b32_e64 v30, v30, v31, s[2:3]
	v_cndmask_b32_e32 v31, 0, v69, vcc
	v_sub_f32_e32 v30, v30, v31
	v_sub_f32_e32 v29, v29, v30
	v_fmac_f32_e32 v28, 0x3d800000, v29
	ds_write_b32 v13, v28 offset:1584
	s_waitcnt lgkmcnt(3)
	v_mul_f32_e32 v29, v23, v151
	v_fmac_f32_e32 v29, v20, v150
	v_mul_f32_e32 v30, v22, v153
	v_fmac_f32_e32 v30, v18, v152
	v_add_f32_e32 v29, v29, v30
	s_waitcnt lgkmcnt(2)
	v_mul_f32_e32 v30, v19, v155
	v_mul_f32_e32 v31, v24, v157
	v_fmac_f32_e32 v30, v15, v154
	v_fmac_f32_e32 v31, v21, v156
	v_add_f32_e32 v29, v25, v29
	v_add_f32_e32 v30, v30, v31
	v_add_f32_e32 v29, v29, v30
	s_waitcnt lgkmcnt(1)
	v_mul_f32_e32 v30, v10, v159
	v_mul_f32_e32 v31, v17, v161
	v_fmac_f32_e32 v30, v16, v158
	v_fmac_f32_e32 v31, v14, v160
	v_add_f32_e32 v30, v30, v31
	v_add_f32_e32 v29, v29, v30
	s_waitcnt lgkmcnt(0)
	ds_read_b128 v[166:169], v27 offset:320
	ds_read_b128 v[170:173], v27 offset:336
	ds_read_b128 v[174:177], v27 offset:352
	ds_read_b128 v[178:181], v27 offset:368
	v_mul_f32_e32 v30, v8, v163
	v_mul_f32_e32 v31, v12, v165
	v_fmac_f32_e32 v30, v11, v162
	v_fmac_f32_e32 v31, v9, v164
	v_add_f32_e32 v30, v30, v31
	v_add_f32_e32 v29, v29, v30
	v_mul_f32_e64 v30, |v29|, s39
	v_exp_f32_e32 v30, v30
	v_min_f32_e32 v29, 0, v29
	v_add_f32_e32 v30, 1.0, v30
	v_cmp_gt_f32_e32 vcc, s40, v30
	s_nop 1
	v_cndmask_b32_e64 v31, 0, 32, vcc
	v_ldexp_f32 v30, v30, v31
	v_log_f32_e32 v30, v30
	s_nop 0
	v_mul_f32_e32 v31, 0x3f317217, v30
	v_fma_f32 v31, v30, s41, -v31
	v_fmac_f32_e32 v31, 0x3377d1cf, v30
	v_fmac_f32_e32 v31, 0x3f317217, v30
	v_cmp_lt_f32_e64 s[2:3], |v30|, s44
	s_nop 1
	v_cndmask_b32_e64 v30, v30, v31, s[2:3]
	v_cndmask_b32_e32 v31, 0, v69, vcc
	v_sub_f32_e32 v30, v30, v31
	v_sub_f32_e32 v29, v29, v30
	v_fmac_f32_e32 v28, 0x3d800000, v29
	ds_write_b32 v13, v28 offset:2112
	s_waitcnt lgkmcnt(3)
; #define LAS __attribute__((address_space(3)))
; __device__ __forceinline__ void gla_cumdecay(const Ptrs& A, int l, int n, int hd, LAS float* bl, const int wv0) {
;     ...
;     const LAS float* ga = gal + 16 * tq * 16;
;     float run = 0.f;
;     for (int tt = 0; tt < 16; ++tt) {
;         float pre = bias;
;         const f32x4 g0 = *(const LAS f32x4*)(ga + tt * 16), g1 = *(const LAS f32x4*)(ga + tt * 16 + 4), g2 = *(const LAS f32x4*)(ga + tt * 16 + 8), g3 = *(const LAS f32x4*)(ga + tt * 16 + 12);
;         pre += (g0.x * w[0] + g0.y * w[1]) + (g0.z * w[2] + g0.w * w[3]); pre += (g1.x * w[4] + g1.y * w[5]) + (g1.z * w[6] + g1.w * w[7]);
;         pre += (g2.x * w[8] + g2.y * w[9]) + (g2.z * w[10] + g2.w * w[11]); pre += (g3.x * w[12] + g3.y * w[13]) + (g3.z * w[14] + g3.w * w[15]);
;         const float la = (fminf(pre, 0.f) - __logf(1.0f + __expf(-fabsf(pre)))) * (1.0f / 16.0f);
;         run += la; bl[(16 * tq + tt) * BLS + d] = run;
;     }
	v_mul_f32_e32 v29, v23, v167
	v_fmac_f32_e32 v29, v20, v166
	v_mul_f32_e32 v30, v22, v169
	v_fmac_f32_e32 v30, v18, v168
	v_add_f32_e32 v29, v29, v30
	s_waitcnt lgkmcnt(2)
	v_mul_f32_e32 v30, v19, v171
	v_mul_f32_e32 v31, v24, v173
	v_fmac_f32_e32 v30, v15, v170
	v_fmac_f32_e32 v31, v21, v172
	v_add_f32_e32 v29, v25, v29
	v_add_f32_e32 v30, v30, v31
	v_add_f32_e32 v29, v29, v30
	s_waitcnt lgkmcnt(1)
	v_mul_f32_e32 v30, v10, v175
	v_mul_f32_e32 v31, v17, v177
	v_fmac_f32_e32 v30, v16, v174
	v_fmac_f32_e32 v31, v14, v176
	v_add_f32_e32 v30, v30, v31
	v_add_f32_e32 v29, v29, v30
	s_waitcnt lgkmcnt(0)
	ds_read_b128 v[150:153], v27 offset:384
	ds_read_b128 v[154:157], v27 offset:400
	ds_read_b128 v[158:161], v27 offset:416
	ds_read_b128 v[162:165], v27 offset:432
	v_mul_f32_e32 v30, v8, v179
	v_mul_f32_e32 v31, v12, v181
	v_fmac_f32_e32 v30, v11, v178
	v_fmac_f32_e32 v31, v9, v180
	v_add_f32_e32 v30, v30, v31
	v_add_f32_e32 v29, v29, v30
	v_mul_f32_e64 v30, |v29|, s39
	v_exp_f32_e32 v30, v30
	v_min_f32_e32 v29, 0, v29
	v_add_f32_e32 v30, 1.0, v30
	v_cmp_gt_f32_e32 vcc, s40, v30
	s_nop 1
	v_cndmask_b32_e64 v31, 0, 32, vcc
	v_ldexp_f32 v30, v30, v31
	v_log_f32_e32 v30, v30
	s_nop 0
	v_mul_f32_e32 v31, 0x3f317217, v30
	v_fma_f32 v31, v30, s41, -v31
	v_fmac_f32_e32 v31, 0x3377d1cf, v30
	v_fmac_f32_e32 v31, 0x3f317217, v30
	v_cmp_lt_f32_e64 s[2:3], |v30|, s44
	s_nop 1
	v_cndmask_b32_e64 v30, v30, v31, s[2:3]
	v_cndmask_b32_e32 v31, 0, v69, vcc
	v_sub_f32_e32 v30, v30, v31
	v_sub_f32_e32 v29, v29, v30
	v_fmac_f32_e32 v28, 0x3d800000, v29
	ds_write_b32 v13, v28 offset:2640
	s_waitcnt lgkmcnt(3)
	v_mul_f32_e32 v29, v23, v151
	v_fmac_f32_e32 v29, v20, v150
	v_mul_f32_e32 v30, v22, v153
	v_fmac_f32_e32 v30, v18, v152
	v_add_f32_e32 v29, v29, v30
	s_waitcnt lgkmcnt(2)
	v_mul_f32_e32 v30, v19, v155
	v_mul_f32_e32 v31, v24, v157
	v_fmac_f32_e32 v30, v15, v154
	v_fmac_f32_e32 v31, v21, v156
	v_add_f32_e32 v29, v25, v29
	v_add_f32_e32 v30, v30, v31
	v_add_f32_e32 v29, v29, v30
	s_waitcnt lgkmcnt(1)
	v_mul_f32_e32 v30, v10, v159
	v_mul_f32_e32 v31, v17, v161
	v_fmac_f32_e32 v30, v16, v158
	v_fmac_f32_e32 v31, v14, v160
	v_add_f32_e32 v30, v30, v31
	v_add_f32_e32 v29, v29, v30
	s_waitcnt lgkmcnt(0)
	ds_read_b128 v[166:169], v27 offset:448
	ds_read_b128 v[170:173], v27 offset:464
	ds_read_b128 v[174:177], v27 offset:480
	ds_read_b128 v[178:181], v27 offset:496
	v_mul_f32_e32 v30, v8, v163
	v_mul_f32_e32 v31, v12, v165
	v_fmac_f32_e32 v30, v11, v162
	v_fmac_f32_e32 v31, v9, v164
	v_add_f32_e32 v30, v30, v31
	v_add_f32_e32 v29, v29, v30
	v_mul_f32_e64 v30, |v29|, s39
	v_exp_f32_e32 v30, v30
	v_min_f32_e32 v29, 0, v29
	v_add_f32_e32 v30, 1.0, v30
	v_cmp_gt_f32_e32 vcc, s40, v30
	s_nop 1
	v_cndmask_b32_e64 v31, 0, 32, vcc
	v_ldexp_f32 v30, v30, v31
	v_log_f32_e32 v30, v30
	s_nop 0
	v_mul_f32_e32 v31, 0x3f317217, v30
	v_fma_f32 v31, v30, s41, -v31
	v_fmac_f32_e32 v31, 0x3377d1cf, v30
	v_fmac_f32_e32 v31, 0x3f317217, v30
	v_cmp_lt_f32_e64 s[2:3], |v30|, s44
	s_nop 1
	v_cndmask_b32_e64 v30, v30, v31, s[2:3]
	v_cndmask_b32_e32 v31, 0, v69, vcc
	v_sub_f32_e32 v30, v30, v31
	v_sub_f32_e32 v29, v29, v30
	v_fmac_f32_e32 v28, 0x3d800000, v29
	ds_write_b32 v13, v28 offset:3168
	s_waitcnt lgkmcnt(3)
	v_mul_f32_e32 v29, v23, v167
	v_fmac_f32_e32 v29, v20, v166
	v_mul_f32_e32 v30, v22, v169
	v_fmac_f32_e32 v30, v18, v168
	v_add_f32_e32 v29, v29, v30
	s_waitcnt lgkmcnt(2)
	v_mul_f32_e32 v30, v19, v171
	v_mul_f32_e32 v31, v24, v173
	v_fmac_f32_e32 v30, v15, v170
	v_fmac_f32_e32 v31, v21, v172
	v_add_f32_e32 v29, v25, v29
	v_add_f32_e32 v30, v30, v31
	v_add_f32_e32 v29, v29, v30
	s_waitcnt lgkmcnt(1)
	v_mul_f32_e32 v30, v10, v175
	v_mul_f32_e32 v31, v17, v177
	v_fmac_f32_e32 v30, v16, v174
	v_fmac_f32_e32 v31, v14, v176
	v_add_f32_e32 v30, v30, v31
	v_add_f32_e32 v29, v29, v30
	s_waitcnt lgkmcnt(0)
	ds_read_b128 v[150:153], v27 offset:512
	ds_read_b128 v[154:157], v27 offset:528
	ds_read_b128 v[158:161], v27 offset:544
	ds_read_b128 v[162:165], v27 offset:560
	v_mul_f32_e32 v30, v8, v179
	v_mul_f32_e32 v31, v12, v181
	v_fmac_f32_e32 v30, v11, v178
	v_fmac_f32_e32 v31, v9, v180
	v_add_f32_e32 v30, v30, v31
	v_add_f32_e32 v29, v29, v30
	v_mul_f32_e64 v30, |v29|, s39
	v_exp_f32_e32 v30, v30
	v_min_f32_e32 v29, 0, v29
	v_add_f32_e32 v30, 1.0, v30
	v_cmp_gt_f32_e32 vcc, s40, v30
	s_nop 1
	v_cndmask_b32_e64 v31, 0, 32, vcc
	v_ldexp_f32 v30, v30, v31
	v_log_f32_e32 v30, v30
	s_nop 0
	v_mul_f32_e32 v31, 0x3f317217, v30
	v_fma_f32 v31, v30, s41, -v31
	v_fmac_f32_e32 v31, 0x3377d1cf, v30
	v_fmac_f32_e32 v31, 0x3f317217, v30
	v_cmp_lt_f32_e64 s[2:3], |v30|, s44
	s_nop 1
	v_cndmask_b32_e64 v30, v30, v31, s[2:3]
	v_cndmask_b32_e32 v31, 0, v69, vcc
	v_sub_f32_e32 v30, v30, v31
	v_sub_f32_e32 v29, v29, v30
	v_fmac_f32_e32 v28, 0x3d800000, v29
	ds_write_b32 v13, v28 offset:3696
	s_waitcnt lgkmcnt(3)
	v_mul_f32_e32 v29, v23, v151
	v_fmac_f32_e32 v29, v20, v150
	v_mul_f32_e32 v30, v22, v153
	v_fmac_f32_e32 v30, v18, v152
	v_add_f32_e32 v29, v29, v30
	s_waitcnt lgkmcnt(2)
	v_mul_f32_e32 v30, v19, v155
	v_mul_f32_e32 v31, v24, v157
	v_fmac_f32_e32 v30, v15, v154
	v_fmac_f32_e32 v31, v21, v156
	v_add_f32_e32 v29, v25, v29
	v_add_f32_e32 v30, v30, v31
	v_add_f32_e32 v29, v29, v30
	s_waitcnt lgkmcnt(1)
	v_mul_f32_e32 v30, v10, v159
	v_mul_f32_e32 v31, v17, v161
	v_fmac_f32_e32 v30, v16, v158
	v_fmac_f32_e32 v31, v14, v160
	v_add_f32_e32 v30, v30, v31
	v_add_f32_e32 v29, v29, v30
	s_waitcnt lgkmcnt(0)
; #define LAS __attribute__((address_space(3)))
; __device__ __forceinline__ void gla_cumdecay(const Ptrs& A, int l, int n, int hd, LAS float* bl, const int wv0) {
;     ...
;     const LAS float* ga = gal + 16 * tq * 16;
;     float run = 0.f;
;     for (int tt = 0; tt < 16; ++tt) {
;         float pre = bias;
;         const f32x4 g0 = *(const LAS f32x4*)(ga + tt * 16), g1 = *(const LAS f32x4*)(ga + tt * 16 + 4), g2 = *(const LAS f32x4*)(ga + tt * 16 + 8), g3 = *(const LAS f32x4*)(ga + tt * 16 + 12);
;         pre += (g0.x * w[0] + g0.y * w[1]) + (g0.z * w[2] + g0.w * w[3]); pre += (g1.x * w[4] + g1.y * w[5]) + (g1.z * w[6] + g1.w * w[7]);
;         pre += (g2.x * w[8] + g2.y * w[9]) + (g2.z * w[10] + g2.w * w[11]); pre += (g3.x * w[12] + g3.y * w[13]) + (g3.z * w[14] + g3.w * w[15]);
;         const float la = (fminf(pre, 0.f) - __logf(1.0f + __expf(-fabsf(pre)))) * (1.0f / 16.0f);
;         run += la; bl[(16 * tq + tt) * BLS + d] = run;
;     }
	ds_read_b128 v[166:169], v27 offset:576
	ds_read_b128 v[170:173], v27 offset:592
	ds_read_b128 v[174:177], v27 offset:608
	ds_read_b128 v[178:181], v27 offset:624
	v_mul_f32_e32 v30, v8, v163
	v_mul_f32_e32 v31, v12, v165
	v_fmac_f32_e32 v30, v11, v162
	v_fmac_f32_e32 v31, v9, v164
	v_add_f32_e32 v30, v30, v31
	v_add_f32_e32 v29, v29, v30
	v_mul_f32_e64 v30, |v29|, s39
	v_exp_f32_e32 v30, v30
	v_min_f32_e32 v29, 0, v29
	v_add_f32_e32 v30, 1.0, v30
	v_cmp_gt_f32_e32 vcc, s40, v30
	s_nop 1
	v_cndmask_b32_e64 v31, 0, 32, vcc
	v_ldexp_f32 v30, v30, v31
	v_log_f32_e32 v30, v30
	s_nop 0
	v_mul_f32_e32 v31, 0x3f317217, v30
	v_fma_f32 v31, v30, s41, -v31
	v_fmac_f32_e32 v31, 0x3377d1cf, v30
	v_fmac_f32_e32 v31, 0x3f317217, v30
	v_cmp_lt_f32_e64 s[2:3], |v30|, s44
	s_nop 1
	v_cndmask_b32_e64 v30, v30, v31, s[2:3]
	v_cndmask_b32_e32 v31, 0, v69, vcc
	v_sub_f32_e32 v30, v30, v31
	v_sub_f32_e32 v29, v29, v30
	v_fmac_f32_e32 v28, 0x3d800000, v29
	ds_write_b32 v13, v28 offset:4224
	s_waitcnt lgkmcnt(3)
	v_mul_f32_e32 v29, v23, v167
	v_fmac_f32_e32 v29, v20, v166
	v_mul_f32_e32 v30, v22, v169
	v_fmac_f32_e32 v30, v18, v168
	v_add_f32_e32 v29, v29, v30
	s_waitcnt lgkmcnt(2)
	v_mul_f32_e32 v30, v19, v171
	v_mul_f32_e32 v31, v24, v173
	v_fmac_f32_e32 v30, v15, v170
	v_fmac_f32_e32 v31, v21, v172
	v_add_f32_e32 v29, v25, v29
	v_add_f32_e32 v30, v30, v31
	v_add_f32_e32 v29, v29, v30
	s_waitcnt lgkmcnt(1)
	v_mul_f32_e32 v30, v10, v175
	v_mul_f32_e32 v31, v17, v177
	v_fmac_f32_e32 v30, v16, v174
	v_fmac_f32_e32 v31, v14, v176
	v_add_f32_e32 v30, v30, v31
	v_add_f32_e32 v29, v29, v30
	s_waitcnt lgkmcnt(0)
	ds_read_b128 v[150:153], v27 offset:640
	ds_read_b128 v[154:157], v27 offset:656
	ds_read_b128 v[158:161], v27 offset:672
	ds_read_b128 v[162:165], v27 offset:688
	v_mul_f32_e32 v30, v8, v179
	v_mul_f32_e32 v31, v12, v181
	v_fmac_f32_e32 v30, v11, v178
	v_fmac_f32_e32 v31, v9, v180
	v_add_f32_e32 v30, v30, v31
	v_add_f32_e32 v29, v29, v30
	v_mul_f32_e64 v30, |v29|, s39
	v_exp_f32_e32 v30, v30
	v_min_f32_e32 v29, 0, v29
	v_add_f32_e32 v30, 1.0, v30
	v_cmp_gt_f32_e32 vcc, s40, v30
	s_nop 1
	v_cndmask_b32_e64 v31, 0, 32, vcc
	v_ldexp_f32 v30, v30, v31
	v_log_f32_e32 v30, v30
	s_nop 0
	v_mul_f32_e32 v31, 0x3f317217, v30
	v_fma_f32 v31, v30, s41, -v31
	v_fmac_f32_e32 v31, 0x3377d1cf, v30
	v_fmac_f32_e32 v31, 0x3f317217, v30
	v_cmp_lt_f32_e64 s[2:3], |v30|, s44
	s_nop 1
	v_cndmask_b32_e64 v30, v30, v31, s[2:3]
	v_cndmask_b32_e32 v31, 0, v69, vcc
	v_sub_f32_e32 v30, v30, v31
	v_sub_f32_e32 v29, v29, v30
	v_fmac_f32_e32 v28, 0x3d800000, v29
	ds_write_b32 v13, v28 offset:4752
	s_waitcnt lgkmcnt(3)
	v_mul_f32_e32 v29, v23, v151
	v_fmac_f32_e32 v29, v20, v150
	v_mul_f32_e32 v30, v22, v153
	v_fmac_f32_e32 v30, v18, v152
	v_add_f32_e32 v29, v29, v30
	s_waitcnt lgkmcnt(2)
	v_mul_f32_e32 v30, v19, v155
	v_mul_f32_e32 v31, v24, v157
	v_fmac_f32_e32 v30, v15, v154
	v_fmac_f32_e32 v31, v21, v156
	v_add_f32_e32 v29, v25, v29
	v_add_f32_e32 v30, v30, v31
	v_add_f32_e32 v29, v29, v30
	s_waitcnt lgkmcnt(1)
	v_mul_f32_e32 v30, v10, v159
	v_mul_f32_e32 v31, v17, v161
	v_fmac_f32_e32 v30, v16, v158
	v_fmac_f32_e32 v31, v14, v160
	v_add_f32_e32 v30, v30, v31
	v_add_f32_e32 v29, v29, v30
	s_waitcnt lgkmcnt(0)
	ds_read_b128 v[166:169], v27 offset:704
	ds_read_b128 v[170:173], v27 offset:720
	ds_read_b128 v[174:177], v27 offset:736
	ds_read_b128 v[178:181], v27 offset:752
	v_mul_f32_e32 v30, v8, v163
	v_mul_f32_e32 v31, v12, v165
	v_fmac_f32_e32 v30, v11, v162
	v_fmac_f32_e32 v31, v9, v164
	v_add_f32_e32 v30, v30, v31
	v_add_f32_e32 v29, v29, v30
	v_mul_f32_e64 v30, |v29|, s39
	v_exp_f32_e32 v30, v30
	v_min_f32_e32 v29, 0, v29
	v_add_f32_e32 v30, 1.0, v30
	v_cmp_gt_f32_e32 vcc, s40, v30
	s_nop 1
	v_cndmask_b32_e64 v31, 0, 32, vcc
	v_ldexp_f32 v30, v30, v31
	v_log_f32_e32 v30, v30
	s_nop 0
	v_mul_f32_e32 v31, 0x3f317217, v30
	v_fma_f32 v31, v30, s41, -v31
	v_fmac_f32_e32 v31, 0x3377d1cf, v30
	v_fmac_f32_e32 v31, 0x3f317217, v30
	v_cmp_lt_f32_e64 s[2:3], |v30|, s44
	s_nop 1
	v_cndmask_b32_e64 v30, v30, v31, s[2:3]
	v_cndmask_b32_e32 v31, 0, v69, vcc
	v_sub_f32_e32 v30, v30, v31
	v_sub_f32_e32 v29, v29, v30
	v_fmac_f32_e32 v28, 0x3d800000, v29
	ds_write_b32 v13, v28 offset:5280
	s_waitcnt lgkmcnt(3)
	v_mul_f32_e32 v29, v23, v167
	v_fmac_f32_e32 v29, v20, v166
	v_mul_f32_e32 v30, v22, v169
	v_fmac_f32_e32 v30, v18, v168
	v_add_f32_e32 v29, v29, v30
	s_waitcnt lgkmcnt(2)
	v_mul_f32_e32 v30, v19, v171
	v_mul_f32_e32 v31, v24, v173
	v_fmac_f32_e32 v30, v15, v170
	v_fmac_f32_e32 v31, v21, v172
	v_add_f32_e32 v29, v25, v29
	v_add_f32_e32 v30, v30, v31
	v_add_f32_e32 v29, v29, v30
	s_waitcnt lgkmcnt(1)
	v_mul_f32_e32 v30, v10, v175
	v_mul_f32_e32 v31, v17, v177
	v_fmac_f32_e32 v30, v16, v174
	v_fmac_f32_e32 v31, v14, v176
	v_add_f32_e32 v30, v30, v31
	v_add_f32_e32 v29, v29, v30
	s_waitcnt lgkmcnt(0)
	ds_read_b128 v[150:153], v27 offset:768
	ds_read_b128 v[154:157], v27 offset:784
	ds_read_b128 v[158:161], v27 offset:800
	ds_read_b128 v[162:165], v27 offset:816
	v_mul_f32_e32 v30, v8, v179
	v_mul_f32_e32 v31, v12, v181
	v_fmac_f32_e32 v30, v11, v178
	v_fmac_f32_e32 v31, v9, v180
	v_add_f32_e32 v30, v30, v31
	v_add_f32_e32 v29, v29, v30
	v_mul_f32_e64 v30, |v29|, s39
	v_exp_f32_e32 v30, v30
	v_min_f32_e32 v29, 0, v29
	v_add_f32_e32 v30, 1.0, v30
	v_cmp_gt_f32_e32 vcc, s40, v30
	s_nop 1
	v_cndmask_b32_e64 v31, 0, 32, vcc
	v_ldexp_f32 v30, v30, v31
	v_log_f32_e32 v30, v30
	s_nop 0
	v_mul_f32_e32 v31, 0x3f317217, v30
	v_fma_f32 v31, v30, s41, -v31
	v_fmac_f32_e32 v31, 0x3377d1cf, v30
	v_fmac_f32_e32 v31, 0x3f317217, v30
	v_cmp_lt_f32_e64 s[2:3], |v30|, s44
	s_nop 1
	v_cndmask_b32_e64 v30, v30, v31, s[2:3]
	v_cndmask_b32_e32 v31, 0, v69, vcc
	v_sub_f32_e32 v30, v30, v31
	v_sub_f32_e32 v29, v29, v30
	v_fmac_f32_e32 v28, 0x3d800000, v29
	ds_write_b32 v13, v28 offset:5808
	s_waitcnt lgkmcnt(3)
; #define LAS __attribute__((address_space(3)))
; __device__ __forceinline__ void gla_cumdecay(const Ptrs& A, int l, int n, int hd, LAS float* bl, const int wv0) {
;     ...
;     for (int tt = 0; tt < 16; ++tt) {
;         float pre = bias;
;         const f32x4 g0 = *(const LAS f32x4*)(ga + tt * 16), g1 = *(const LAS f32x4*)(ga + tt * 16 + 4), g2 = *(const LAS f32x4*)(ga + tt * 16 + 8), g3 = *(const LAS f32x4*)(ga + tt * 16 + 12);
;         pre += (g0.x * w[0] + g0.y * w[1]) + (g0.z * w[2] + g0.w * w[3]); pre += (g1.x * w[4] + g1.y * w[5]) + (g1.z * w[6] + g1.w * w[7]);
;         pre += (g2.x * w[8] + g2.y * w[9]) + (g2.z * w[10] + g2.w * w[11]); pre += (g3.x * w[12] + g3.y * w[13]) + (g3.z * w[14] + g3.w * w[15]);
;         const float la = (fminf(pre, 0.f) - __logf(1.0f + __expf(-fabsf(pre)))) * (1.0f / 16.0f);
;         run += la; bl[(16 * tq + tt) * BLS + d] = run;
;     }
;     __syncthreads();
;     float add = 0.f;
; #pragma unroll
;     for (int q = 0; q < 3; ++q) if (q < tq) add += bl[(16 * q + 15) * BLS + d];
;     __syncthreads();
	v_mul_f32_e32 v29, v23, v151
	v_fmac_f32_e32 v29, v20, v150
	v_mul_f32_e32 v30, v22, v153
	v_fmac_f32_e32 v30, v18, v152
	v_add_f32_e32 v29, v29, v30
	s_waitcnt lgkmcnt(2)
	v_mul_f32_e32 v30, v19, v155
	v_mul_f32_e32 v31, v24, v157
	v_fmac_f32_e32 v30, v15, v154
	v_fmac_f32_e32 v31, v21, v156
	v_add_f32_e32 v29, v25, v29
	v_add_f32_e32 v30, v30, v31
	v_add_f32_e32 v29, v29, v30
	s_waitcnt lgkmcnt(1)
	v_mul_f32_e32 v30, v10, v159
	v_mul_f32_e32 v31, v17, v161
	v_fmac_f32_e32 v30, v16, v158
	v_fmac_f32_e32 v31, v14, v160
	v_add_f32_e32 v30, v30, v31
	v_add_f32_e32 v29, v29, v30
	s_waitcnt lgkmcnt(0)
	ds_read_b128 v[166:169], v27 offset:832
	ds_read_b128 v[170:173], v27 offset:848
	ds_read_b128 v[174:177], v27 offset:864
	ds_read_b128 v[178:181], v27 offset:880
	v_mul_f32_e32 v30, v8, v163
	v_mul_f32_e32 v31, v12, v165
	v_fmac_f32_e32 v30, v11, v162
	v_fmac_f32_e32 v31, v9, v164
	v_add_f32_e32 v30, v30, v31
	v_add_f32_e32 v29, v29, v30
	v_mul_f32_e64 v30, |v29|, s39
	v_exp_f32_e32 v30, v30
	v_min_f32_e32 v29, 0, v29
	v_add_f32_e32 v30, 1.0, v30
	v_cmp_gt_f32_e32 vcc, s40, v30
	s_nop 1
	v_cndmask_b32_e64 v31, 0, 32, vcc
	v_ldexp_f32 v30, v30, v31
	v_log_f32_e32 v30, v30
	s_nop 0
	v_mul_f32_e32 v31, 0x3f317217, v30
	v_fma_f32 v31, v30, s41, -v31
	v_fmac_f32_e32 v31, 0x3377d1cf, v30
	v_fmac_f32_e32 v31, 0x3f317217, v30
	v_cmp_lt_f32_e64 s[2:3], |v30|, s44
	s_nop 1
	v_cndmask_b32_e64 v30, v30, v31, s[2:3]
	v_cndmask_b32_e32 v31, 0, v69, vcc
	v_sub_f32_e32 v30, v30, v31
	v_sub_f32_e32 v29, v29, v30
	v_fmac_f32_e32 v28, 0x3d800000, v29
	ds_write_b32 v13, v28 offset:6336
	s_waitcnt lgkmcnt(3)
	v_mul_f32_e32 v29, v23, v167
	v_fmac_f32_e32 v29, v20, v166
	v_mul_f32_e32 v30, v22, v169
	v_fmac_f32_e32 v30, v18, v168
	v_add_f32_e32 v29, v29, v30
	s_waitcnt lgkmcnt(2)
	v_mul_f32_e32 v30, v19, v171
	v_mul_f32_e32 v31, v24, v173
	v_fmac_f32_e32 v30, v15, v170
	v_fmac_f32_e32 v31, v21, v172
	v_add_f32_e32 v29, v25, v29
	v_add_f32_e32 v30, v30, v31
	v_add_f32_e32 v29, v29, v30
	s_waitcnt lgkmcnt(1)
	v_mul_f32_e32 v30, v10, v175
	v_mul_f32_e32 v31, v17, v177
	v_fmac_f32_e32 v30, v16, v174
	v_fmac_f32_e32 v31, v14, v176
	v_add_f32_e32 v30, v30, v31
	v_add_f32_e32 v29, v29, v30
	s_waitcnt lgkmcnt(0)
	ds_read_b128 v[150:153], v27 offset:896
	ds_read_b128 v[154:157], v27 offset:912
	ds_read_b128 v[158:161], v27 offset:928
	ds_read_b128 v[162:165], v27 offset:944
	v_mul_f32_e32 v30, v8, v179
	v_mul_f32_e32 v31, v12, v181
	v_fmac_f32_e32 v30, v11, v178
	v_fmac_f32_e32 v31, v9, v180
	v_add_f32_e32 v30, v30, v31
	v_add_f32_e32 v29, v29, v30
	v_mul_f32_e64 v30, |v29|, s39
	v_exp_f32_e32 v30, v30
	v_min_f32_e32 v29, 0, v29
	v_add_f32_e32 v30, 1.0, v30
	v_cmp_gt_f32_e32 vcc, s40, v30
	s_nop 1
	v_cndmask_b32_e64 v31, 0, 32, vcc
	v_ldexp_f32 v30, v30, v31
	v_log_f32_e32 v30, v30
	s_nop 0
	v_mul_f32_e32 v31, 0x3f317217, v30
	v_fma_f32 v31, v30, s41, -v31
	v_fmac_f32_e32 v31, 0x3377d1cf, v30
	v_fmac_f32_e32 v31, 0x3f317217, v30
	v_cmp_lt_f32_e64 s[2:3], |v30|, s44
	s_nop 1
	v_cndmask_b32_e64 v30, v30, v31, s[2:3]
	v_cndmask_b32_e32 v31, 0, v69, vcc
	v_sub_f32_e32 v30, v30, v31
	v_sub_f32_e32 v29, v29, v30
	v_fmac_f32_e32 v28, 0x3d800000, v29
	ds_write_b32 v13, v28 offset:6864
	s_waitcnt lgkmcnt(3)
	v_mul_f32_e32 v29, v23, v151
	v_fmac_f32_e32 v29, v20, v150
	v_mul_f32_e32 v30, v22, v153
	v_fmac_f32_e32 v30, v18, v152
	v_add_f32_e32 v29, v29, v30
	s_waitcnt lgkmcnt(2)
	v_mul_f32_e32 v30, v19, v155
	v_mul_f32_e32 v31, v24, v157
	v_fmac_f32_e32 v30, v15, v154
	v_fmac_f32_e32 v31, v21, v156
	v_add_f32_e32 v29, v25, v29
	v_add_f32_e32 v30, v30, v31
	v_add_f32_e32 v29, v29, v30
	s_waitcnt lgkmcnt(1)
	v_mul_f32_e32 v30, v10, v159
	v_mul_f32_e32 v31, v17, v161
	v_fmac_f32_e32 v30, v16, v158
	v_fmac_f32_e32 v31, v14, v160
	v_add_f32_e32 v30, v30, v31
	v_add_f32_e32 v29, v29, v30
	s_waitcnt lgkmcnt(0)
	ds_read_b128 v[166:169], v27 offset:960
	ds_read_b128 v[170:173], v27 offset:976
	ds_read_b128 v[174:177], v27 offset:992
	ds_read_b128 v[178:181], v27 offset:1008
	v_mul_f32_e32 v30, v8, v163
	v_mul_f32_e32 v31, v12, v165
	v_fmac_f32_e32 v30, v11, v162
	v_fmac_f32_e32 v31, v9, v164
	v_add_f32_e32 v30, v30, v31
	v_add_f32_e32 v29, v29, v30
	v_mul_f32_e64 v30, |v29|, s39
	v_exp_f32_e32 v30, v30
	v_min_f32_e32 v29, 0, v29
	v_add_f32_e32 v30, 1.0, v30
	v_cmp_gt_f32_e32 vcc, s40, v30
	s_nop 1
	v_cndmask_b32_e64 v31, 0, 32, vcc
	v_ldexp_f32 v30, v30, v31
	v_log_f32_e32 v30, v30
	s_nop 0
	v_mul_f32_e32 v31, 0x3f317217, v30
	v_fma_f32 v31, v30, s41, -v31
	v_fmac_f32_e32 v31, 0x3377d1cf, v30
	v_fmac_f32_e32 v31, 0x3f317217, v30
	v_cmp_lt_f32_e64 s[2:3], |v30|, s44
	s_nop 1
	v_cndmask_b32_e64 v30, v30, v31, s[2:3]
	v_cndmask_b32_e32 v31, 0, v69, vcc
	v_sub_f32_e32 v30, v30, v31
	v_sub_f32_e32 v29, v29, v30
	v_fmac_f32_e32 v28, 0x3d800000, v29
	ds_write_b32 v13, v28 offset:7392
	s_waitcnt lgkmcnt(3)
	v_mul_f32_e32 v23, v23, v167
	v_fmac_f32_e32 v23, v20, v166
	v_mul_f32_e32 v20, v22, v169
	s_waitcnt lgkmcnt(2)
	v_mul_f32_e32 v19, v19, v171
	v_fmac_f32_e32 v20, v18, v168
	v_fmac_f32_e32 v19, v15, v170
	v_mul_f32_e32 v15, v24, v173
	s_waitcnt lgkmcnt(1)
	v_mul_f32_e32 v10, v10, v175
	v_add_f32_e32 v18, v23, v20
	v_fmac_f32_e32 v15, v21, v172
	v_fmac_f32_e32 v10, v16, v174
	v_mul_f32_e32 v16, v17, v177
	s_waitcnt lgkmcnt(0)
	v_mul_f32_e32 v8, v8, v179
	v_add_f32_e32 v18, v25, v18
	v_add_f32_e32 v15, v19, v15
	v_fmac_f32_e32 v16, v14, v176
	v_fmac_f32_e32 v8, v11, v178
	v_mul_f32_e32 v11, v12, v181
	v_add_f32_e32 v15, v18, v15
	v_add_f32_e32 v10, v10, v16
	v_fmac_f32_e32 v11, v9, v180
	v_add_f32_e32 v10, v15, v10
	v_add_f32_e32 v8, v8, v11
	v_add_f32_e32 v8, v10, v8
	v_mul_f32_e64 v9, |v8|, s39
	v_exp_f32_e32 v9, v9
	v_min_f32_e32 v8, 0, v8
	v_add_f32_e32 v9, 1.0, v9
	v_cmp_gt_f32_e32 vcc, s40, v9
	s_nop 1
	v_cndmask_b32_e64 v10, 0, 32, vcc
	v_ldexp_f32 v9, v9, v10
	v_log_f32_e32 v9, v9
	s_nop 0
	v_mul_f32_e32 v10, 0x3f317217, v9
	v_fma_f32 v10, v9, s41, -v10
	v_fmac_f32_e32 v10, 0x3377d1cf, v9
	v_fmac_f32_e32 v10, 0x3f317217, v9
	v_cmp_lt_f32_e64 s[2:3], |v9|, s44
	s_nop 1
	v_cndmask_b32_e64 v9, v9, v10, s[2:3]
	v_cndmask_b32_e32 v10, 0, v69, vcc
	v_sub_f32_e32 v9, v9, v10
	v_sub_f32_e32 v8, v8, v9
	s_cselect_b64 s[2:3], -1, 0
	v_fmac_f32_e32 v28, 0x3d800000, v8
	s_and_b64 vcc, exec, s[2:3]
	v_mov_b32_e32 v8, 0
	ds_write_b32 v13, v28 offset:7920
	s_waitcnt lgkmcnt(0)
	s_barrier
	s_cbranch_vccz .LBB0_1160
	ds_read_b32 v8, v26 offset:7920
	s_waitcnt lgkmcnt(0)
	v_add_f32_e32 v8, 0, v8

; #define LAS __attribute__((address_space(3)))
; __device__ __forceinline__ unsigned f2bf(float f) { unsigned u = __builtin_bit_cast(unsigned, f); return (u + 0x7fffu + ((u >> 16) & 1u)) >> 16; }
;     __device__ __forceinline__ unsigned char* ws() const { return (unsigned char*)(__attribute__((address_space(1))) unsigned char*)get(21); }
; __device__ __forceinline__ void unpack8(const u32x4 w, float* x) { x[0] = bflo(w.x); x[1] = bfhi(w.x); x[2] = bflo(w.y); x[3] = bfhi(w.y); x[4] = bflo(w.z); x[5] = bfhi(w.z); x[6] = bflo(w.w); x[7] = bfhi(w.w); }
; __device__ __forceinline__ void gla_load_vt(const bf16* GVc, LAS bf16* VTl, int wave, int lane) {
;     u32x4 vv[4];
; #pragma unroll
;     for (int i = 0; i < 4; ++i) vv[i] = *(const u32x4*)(GVc + (size_t)lane * 1024 + (wave + 8 * i) * 8);
; #pragma unroll
;     for (int i = 0; i < 4; ++i) { const int v0 = (wave + 8 * i) * 8; LAS bf16* p = VTl + v0 * 72 + lane;
;         p[0] = (bf16)(vv[i].x & 0xffff); p[72] = (bf16)(vv[i].x >> 16); p[144] = (bf16)(vv[i].y & 0xffff); p[216] = (bf16)(vv[i].y >> 16);
;         p[288] = (bf16)(vv[i].z & 0xffff); p[360] = (bf16)(vv[i].z >> 16); p[432] = (bf16)(vv[i].w & 0xffff); p[504] = (bf16)(vv[i].w >> 16); }
; }
; __device__ __forceinline__ void gla_state(const Ptrs& A, int l, LAS unsigned char* lds, int c, int G, int wave, int lane_, const int wv0) {
;     ...
;         for (int i = 0; i < 2; ++i) { const int d0 = (wave + 8 * i) * 8; float x[8]; unpack8(kk[i], x);
;             const f32x4 b0 = *(const LAS f32x4*)(bl + lane * BLS + d0), b1 = *(const LAS f32x4*)(bl + lane * BLS + d0 + 4);
;             const f32x4 e0 = *(const LAS f32x4*)(bl + 63 * BLS + d0), e1 = *(const LAS f32x4*)(bl + 63 * BLS + d0 + 4);
;             LAS bf16* p = KdT + d0 * 72 + lane;
;             p[0] = (bf16)f2bf(x[0] * __expf(e0.x - b0.x)); p[72] = (bf16)f2bf(x[1] * __expf(e0.y - b0.y)); p[144] = (bf16)f2bf(x[2] * __expf(e0.z - b0.z)); p[216] = (bf16)f2bf(x[3] * __expf(e0.w - b0.w));
;             p[288] = (bf16)f2bf(x[4] * __expf(e1.x - b1.x)); p[360] = (bf16)f2bf(x[5] * __expf(e1.y - b1.y)); p[432] = (bf16)f2bf(x[6] * __expf(e1.z - b1.z)); p[504] = (bf16)f2bf(x[7] * __expf(e1.w - b1.w)); }
;         if (tid < 128) ((float*)(ws + WS_DEC))[(size_t)it * 128 + tid] = __expf(bl[63 * BLS + tid]);
.LBB0_1166:
	s_ashr_i32 s23, s22, 31
	s_lshl_b64 s[2:3], s[22:23], 11
	s_add_u32 s2, s24, s2
	s_addc_u32 s3, s25, s3
	s_add_u32 s2, s2, s14
	s_addc_u32 s3, s3, 0
	v_mov_b32_e32 v57, v49
	v_lshl_add_u64 v[8:9], s[2:3], 0, v[56:57]
	v_lshl_add_u64 v[24:25], s[12:13], 1, v[8:9]
	s_waitcnt lgkmcnt(0)
	s_barrier
	global_load_dwordx4 v[8:11], v[24:25], off
	global_load_dwordx4 v[12:15], v[24:25], off offset:128
	global_load_dwordx4 v[16:19], v[24:25], off offset:256
	global_load_dwordx4 v[20:23], v[24:25], off offset:384
	s_waitcnt vmcnt(4)
	v_add_u32_e32 v24, s26, v65
	v_add_u32_e32 v25, s27, v65
	v_add_u32_e32 v26, s28, v65
	v_lshlrev_b32_e32 v27, 16, v4
	v_and_b32_e32 v28, 0xffff0000, v4
	v_lshlrev_b32_e32 v29, 16, v5
	v_and_b32_e32 v30, 0xffff0000, v5
	v_lshlrev_b32_e32 v31, 16, v6
	v_and_b32_e32 v32, 0xffff0000, v6
	v_lshlrev_b32_e32 v33, 16, v7
	v_mov_b32_e32 v34, s29
	s_waitcnt vmcnt(3)
	ds_write_b16 v24, v8 offset:52224
	ds_write_b16_d16_hi v24, v8 offset:52368
	ds_write_b16 v24, v9 offset:52512
	ds_write_b16_d16_hi v24, v9 offset:52656
	ds_write_b16 v24, v10 offset:52800
	ds_write_b16_d16_hi v24, v10 offset:52944
	ds_write_b16 v24, v11 offset:53088
	ds_write_b16_d16_hi v24, v11 offset:53232
	s_waitcnt vmcnt(2)
	ds_write_b16 v25, v12 offset:52224
	ds_write_b16_d16_hi v25, v12 offset:52368
	ds_write_b16 v25, v13 offset:52512
	ds_write_b16_d16_hi v25, v13 offset:52656
	ds_write_b16 v25, v14 offset:52800
	ds_write_b16_d16_hi v25, v14 offset:52944
	ds_write_b16 v25, v15 offset:53088
	ds_write_b16_d16_hi v25, v15 offset:53232
	s_waitcnt vmcnt(1)
	ds_write_b16 v25, v16 offset:61440
	ds_write_b16_d16_hi v25, v16 offset:61584
	ds_write_b16 v25, v17 offset:61728
	ds_write_b16_d16_hi v25, v17 offset:61872
	ds_write_b16 v25, v18 offset:62016
	ds_write_b16_d16_hi v25, v18 offset:62160
	ds_write_b16 v25, v19 offset:62304
	ds_write_b16_d16_hi v25, v19 offset:62448
	s_waitcnt vmcnt(0)
	ds_write_b16 v26, v20 offset:61440
	ds_write_b16_d16_hi v26, v20 offset:61584
	ds_write_b16 v26, v21 offset:61728
	ds_write_b16_d16_hi v26, v21 offset:61872
	ds_write_b16 v26, v22 offset:62016
	ds_write_b16_d16_hi v26, v22 offset:62160
	ds_write_b16 v26, v23 offset:62304
	ds_write_b16_d16_hi v26, v23 offset:62448
	ds_read_b128 v[8:11], v68
	ds_read_b128 v[12:15], v34 offset:33264
	v_and_b32_e32 v20, 0xffff0000, v7
	ds_read_b128 v[4:7], v68 offset:16
	ds_read_b128 v[16:19], v34 offset:33280
	v_add_u32_e32 v21, s26, v66
	v_lshlrev_b32_e32 v22, 16, v2
	s_waitcnt lgkmcnt(2)
	v_sub_f32_e32 v8, v12, v8
	v_sub_f32_e32 v9, v13, v9
	s_waitcnt lgkmcnt(0)
	v_sub_f32_e32 v4, v16, v4
	v_sub_f32_e32 v10, v14, v10
	v_sub_f32_e32 v11, v15, v11
	v_mul_f32_e32 v8, 0x3fb8aa3b, v8
	v_mul_f32_e32 v4, 0x3fb8aa3b, v4
	v_mul_f32_e32 v9, 0x3fb8aa3b, v9
	v_mul_f32_e32 v10, 0x3fb8aa3b, v10
	v_mul_f32_e32 v11, 0x3fb8aa3b, v11
	v_exp_f32_e32 v8, v8
	v_exp_f32_e32 v4, v4
	v_sub_f32_e32 v5, v17, v5
	v_exp_f32_e32 v9, v9
	v_exp_f32_e32 v10, v10
	v_exp_f32_e32 v11, v11
	v_mul_f32_e32 v5, 0x3fb8aa3b, v5
	v_exp_f32_e32 v5, v5
	v_mul_f32_e32 v8, v8, v27
	v_mul_f32_e32 v4, v4, v31
	v_mul_f32_e32 v9, v9, v28
	v_mul_f32_e32 v10, v10, v29
	v_mul_f32_e32 v11, v11, v30
	v_bfe_u32 v12, v8, 16, 1
	v_bfe_u32 v16, v4, 16, 1
	v_bfe_u32 v13, v9, 16, 1
	v_bfe_u32 v14, v10, 16, 1
	v_bfe_u32 v15, v11, 16, 1
	v_add3_u32 v8, v8, v12, s46
	v_add3_u32 v4, v4, v16, s46
	v_mul_f32_e32 v5, v5, v32
	v_add3_u32 v9, v9, v13, s46
	v_add3_u32 v10, v10, v14, s46
	v_add3_u32 v11, v11, v15, s46
	ds_write_b16_d16_hi v21, v8 offset:33792
	ds_write_b16_d16_hi v21, v9 offset:33936
	ds_write_b16_d16_hi v21, v10 offset:34080
	ds_write_b16_d16_hi v21, v11 offset:34224
	ds_write_b16_d16_hi v21, v4 offset:34368
	v_sub_f32_e32 v4, v18, v6
	v_mul_f32_e32 v4, 0x3fb8aa3b, v4
	v_bfe_u32 v6, v5, 16, 1
	v_exp_f32_e32 v4, v4
	v_add3_u32 v5, v5, v6, s46
	ds_write_b16_d16_hi v21, v5 offset:34512
	v_sub_f32_e32 v5, v19, v7
	v_mul_f32_e32 v5, 0x3fb8aa3b, v5
	v_exp_f32_e32 v5, v5
	v_mul_f32_e32 v4, v4, v33
	v_bfe_u32 v6, v4, 16, 1
	v_add3_u32 v4, v4, v6, s46
	ds_write_b16_d16_hi v21, v4 offset:34656
	v_mul_f32_e32 v4, v5, v20
	v_bfe_u32 v5, v4, 16, 1
	v_add3_u32 v4, v4, v5, s46
	ds_write_b16_d16_hi v21, v4 offset:34800
	ds_read_b128 v[4:7], v68 offset:256
	ds_read_b128 v[8:11], v34 offset:33520
	v_lshlrev_b32_e32 v20, 16, v0
	ds_read_b128 v[12:15], v68 offset:272
	ds_read_b128 v[16:19], v34 offset:33536
	v_and_b32_e32 v0, 0xffff0000, v0
	v_lshlrev_b32_e32 v21, 16, v1
	s_waitcnt lgkmcnt(2)
	v_sub_f32_e32 v4, v8, v4
	v_mul_f32_e32 v4, 0x3fb8aa3b, v4
	v_exp_f32_e32 v4, v4
	v_sub_f32_e32 v5, v9, v5
	v_mul_f32_e32 v5, 0x3fb8aa3b, v5
	v_exp_f32_e32 v5, v5
	v_mul_f32_e32 v4, v4, v20
	v_bfe_u32 v20, v4, 16, 1
	v_add3_u32 v4, v4, v20, s46
	v_add_u32_e32 v9, s27, v66
	ds_write_b16_d16_hi v9, v4 offset:33792
	v_sub_f32_e32 v4, v10, v6
	v_mul_f32_e32 v4, 0x3fb8aa3b, v4
	v_exp_f32_e32 v4, v4
	v_mul_f32_e32 v0, v5, v0
	v_bfe_u32 v5, v0, 16, 1
	v_add3_u32 v0, v0, v5, s46
	ds_write_b16_d16_hi v9, v0 offset:33936
	v_mul_f32_e32 v0, v4, v21
	v_sub_f32_e32 v4, v11, v7
	v_mul_f32_e32 v4, 0x3fb8aa3b, v4
	v_exp_f32_e32 v4, v4
	v_bfe_u32 v5, v0, 16, 1
	v_and_b32_e32 v1, 0xffff0000, v1
	v_add3_u32 v0, v0, v5, s46
	ds_write_b16_d16_hi v9, v0 offset:34080
	v_mul_f32_e32 v0, v4, v1
	s_waitcnt lgkmcnt(3)
	v_sub_f32_e32 v1, v16, v12
	v_mul_f32_e32 v1, 0x3fb8aa3b, v1
	v_exp_f32_e32 v1, v1
	v_bfe_u32 v4, v0, 16, 1
	v_add3_u32 v0, v0, v4, s46
	ds_write_b16_d16_hi v9, v0 offset:34224
	v_mul_f32_e32 v0, v1, v22
	v_sub_f32_e32 v1, v17, v13
	v_mul_f32_e32 v1, 0x3fb8aa3b, v1
	v_exp_f32_e32 v1, v1
	v_bfe_u32 v4, v0, 16, 1
	v_and_b32_e32 v2, 0xffff0000, v2
	v_add3_u32 v0, v0, v4, s46
	ds_write_b16_d16_hi v9, v0 offset:34368
	v_mul_f32_e32 v0, v1, v2
	v_sub_f32_e32 v1, v18, v14
	v_mul_f32_e32 v1, 0x3fb8aa3b, v1
	v_exp_f32_e32 v1, v1
	v_bfe_u32 v2, v0, 16, 1
	v_lshlrev_b32_e32 v8, 16, v3
	v_add3_u32 v0, v0, v2, s46
	ds_write_b16_d16_hi v9, v0 offset:34512
	v_mul_f32_e32 v0, v1, v8
	v_sub_f32_e32 v1, v19, v15
	v_mul_f32_e32 v1, 0x3fb8aa3b, v1
	v_exp_f32_e32 v1, v1
	v_bfe_u32 v2, v0, 16, 1
	v_and_b32_e32 v3, 0xffff0000, v3
	v_add3_u32 v0, v0, v2, s46
	ds_write_b16_d16_hi v9, v0 offset:34656
	v_mul_f32_e32 v0, v1, v3
	v_bfe_u32 v1, v0, 16, 1
	v_add3_u32 v0, v0, v1, s46
	ds_write_b16_d16_hi v9, v0 offset:34800
	s_and_saveexec_b64 s[2:3], s[0:1]
	s_cbranch_execz .LBB0_1157
	ds_read_b32 v0, v67 offset:33264
	s_waitcnt lgkmcnt(0)
	v_mul_f32_e32 v0, 0x3fb8aa3b, v0
	v_exp_f32_e32 v2, v0
	v_lshl_add_u64 v[0:1], s[8:9], 0, v[50:51]
	global_store_dword v[0:1], v2, off
	s_branch .LBB0_1157

; #define LAS __attribute__((address_space(3)))
; #define TID() (wv0 * 64 + (int)__builtin_amdgcn_mbcnt_hi(~0u, __builtin_amdgcn_mbcnt_lo(~0u, 0u)))
; __device__ __forceinline__ int opaque(int x) { asm volatile("" : "+v"(x)); return x; }
;     __device__ __forceinline__ const float* in(int k) const { return (const float*)(const __attribute__((address_space(1))) float*)get(k); }
; __device__ __forceinline__ void gla_cumdecay(const Ptrs& A, int l, int n, int hd, LAS float* bl, const int wv0) {
;     const int tid = opaque(TID()), d = tid & 127, tq = __builtin_amdgcn_readfirstlane(tid >> 7);
;     const float* wa2 = A.in(4) + (size_t)l * 16 * 512 + hd * 128 + d;
;     float w[16];
; #pragma unroll
;     for (int r = 0; r < 16; ++r) w[r] = wa2[r * 512];
;     const float bias = A.in(5)[(size_t)l * 512 + hd * 128 + d];
;     LAS float* gal = bl + 29184;
;     *(LAS f32x2*)(gal + 2 * tid) = *(const f32x2*)((const float*)(A.ws() + WS_GA1) + (size_t)n * 64 * 16 + 2 * tid);
;     __syncthreads();
;     const LAS float* ga = gal + 16 * tq * 16;
;     float run = 0.f;
;     for (int tt = 0; tt < 16; ++tt) {
;         float pre = bias;
;         const f32x4 g0 = *(const LAS f32x4*)(ga + tt * 16), g1 = *(const LAS f32x4*)(ga + tt * 16 + 4), g2 = *(const LAS f32x4*)(ga + tt * 16 + 8), g3 = *(const LAS f32x4*)(ga + tt * 16 + 12);
;         pre += (g0.x * w[0] + g0.y * w[1]) + (g0.z * w[2] + g0.w * w[3]); pre += (g1.x * w[4] + g1.y * w[5]) + (g1.z * w[6] + g1.w * w[7]);
;         pre += (g2.x * w[8] + g2.y * w[9]) + (g2.z * w[10] + g2.w * w[11]); pre += (g3.x * w[12] + g3.y * w[13]) + (g3.z * w[14] + g3.w * w[15]);
;         const float la = (fminf(pre, 0.f) - __logf(1.0f + __expf(-fabsf(pre)))) * (1.0f / 16.0f);
;         run += la; bl[(16 * tq + tt) * BLS + d] = run;
;     }
; __device__ __forceinline__ void gla_out(const Ptrs& A, int l, LAS unsigned char* lds, int c, int G, int wave, int lane_, const int wv0) {
;     ...
;         const int n = it >> 2, hd = it & 3, t0 = n * 64;
;         u32x4 qq[2], kk[2];
; #pragma unroll
;         for (int i = 0; i < 2; ++i) { qq[i] = *(const u32x4*)(GQ + (size_t)(t0 + lane) * 512 + hd * 128 + (wave + 8 * i) * 8); kk[i] = *(const u32x4*)(GK + (size_t)(t0 + lane) * 512 + hd * 128 + (wave + 8 * i) * 8); }
;         gla_cumdecay(A, l, n, hd, bl, wv0);
.LBB0_1324:
	s_ashr_i32 s36, s44, 2
	s_lshl_b32 s68, s36, 6
	v_or_b32_e32 v0, s68, v62
	v_ashrrev_i32_e32 v1, 31, v0
	s_and_b32 s37, s44, 3
	v_lshlrev_b64 v[0:1], 10, v[0:1]
	v_lshl_add_u64 v[2:3], s[46:47], 0, v[0:1]
	s_lshl_b32 s56, s37, 8
	v_lshl_add_u64 v[0:1], s[48:49], 0, v[0:1]
	v_lshl_add_u64 v[2:3], v[2:3], 0, s[56:57]
	v_lshl_add_u64 v[0:1], v[0:1], 0, s[56:57]
	s_lshl_b64 s[40:41], s[54:55], 1
	v_lshl_add_u64 v[2:3], v[2:3], 0, s[40:41]
	v_lshl_add_u64 v[0:1], v[0:1], 0, s[40:41]
	v_mov_b32_e32 v42, v204
	v_mov_b32_e32 v198, v0
	v_mov_b32_e32 v199, v1
	v_mov_b32_e32 v200, v2
	v_mov_b32_e32 v201, v3
	v_mov_b32 v16, s77
	ds_read_b64 v[16:17], v16 offset:32
	s_lshl_b32 s40, s37, 9
	v_readfirstlane_b32 s37, v42
	s_waitcnt lgkmcnt(0)
	v_readfirstlane_b32 s69, v16
	v_readfirstlane_b32 s41, v17
	s_add_u32 s92, s69, s40
	v_lshlrev_b32_e32 v16, 2, v42
	s_addc_u32 s93, s41, 0
	v_and_b32_e32 v48, 0x1fc, v16
	v_lshl_add_u64 v[16:17], s[92:93], 0, v[48:49]
	v_add_co_u32_e32 v20, vcc, s39, v16
	v_lshl_add_u64 v[18:19], v[16:17], 0, s[64:65]
	s_nop 0
	v_addc_co_u32_e32 v21, vcc, 0, v17, vcc
	v_add_co_u32_e32 v24, vcc, s45, v16
	s_ashr_i32 s41, s37, 7
	s_nop 0
	v_addc_co_u32_e32 v25, vcc, 0, v17, vcc
	v_add_co_u32_e32 v32, vcc, s74, v16
	s_nop 1
	v_addc_co_u32_e32 v33, vcc, 0, v17, vcc
	v_add_co_u32_e32 v34, vcc, s75, v16
	s_nop 1
	v_addc_co_u32_e32 v35, vcc, 0, v17, vcc
	v_add_co_u32_e32 v36, vcc, s79, v16
	s_nop 1
	v_addc_co_u32_e32 v37, vcc, 0, v17, vcc
	v_add_co_u32_e32 v38, vcc, s80, v16
	s_nop 1
	v_addc_co_u32_e32 v39, vcc, 0, v17, vcc
	v_add_co_u32_e32 v40, vcc, s81, v16
	s_nop 1
	v_addc_co_u32_e32 v41, vcc, 0, v17, vcc
	global_load_dword v28, v[20:21], off offset:-4096
	global_load_dword v31, v[18:19], off offset:2048
	global_load_dword v26, v[20:21], off
	global_load_dword v30, v[20:21], off offset:2048
	global_load_dword v23, v[32:33], off offset:-4096
	global_load_dword v27, v[24:25], off offset:2048
	s_nop 0
	global_load_dword v19, v[34:35], off offset:2048
	global_load_dword v17, v[38:39], off offset:2048
	global_load_dword v29, v[32:33], off
	s_nop 0
	global_load_dword v32, v[32:33], off offset:2048
	s_nop 0
	global_load_dword v24, v[36:37], off offset:-4096
	global_load_dword v22, v[36:37], off
	global_load_dword v25, v[36:37], off offset:2048
	global_load_dword v20, v[40:41], off offset:-4096
	global_load_dword v18, v[40:41], off
	global_load_dword v21, v[40:41], off offset:2048
	v_mov_b32 v16, s77
	ds_read_b64 v[34:35], v16 offset:40
	s_waitcnt lgkmcnt(0)
	v_readfirstlane_b32 s69, v34
	v_readfirstlane_b32 s37, v35
	s_add_u32 s92, s69, s40
	s_addc_u32 s93, s37, 0
	global_load_dword v33, v48, s[92:93] offset:2048
	v_mov_b32 v16, s77
	ds_read_b64 v[34:35], v16 offset:168
	s_ashr_i32 s37, s36, 31
	s_lshl_b64 s[36:37], s[36:37], 12
	v_lshl_add_u32 v16, v42, 3, s83
	s_waitcnt lgkmcnt(0)
	v_readfirstlane_b32 s92, v34
	v_readfirstlane_b32 s69, v35
	s_add_u32 s36, s92, s36
	v_lshlrev_b32_e32 v34, 1, v42
	s_addc_u32 s37, s69, s37
	v_ashrrev_i32_e32 v35, 31, v34
	v_lshl_add_u64 v[34:35], v[34:35], 2, s[36:37]
	v_add_co_u32_e32 v34, vcc, s82, v34
	s_lshl_b32 s36, s41, 10
	s_nop 0
	v_addc_co_u32_e32 v35, vcc, 0, v35, vcc
	global_load_dwordx2 v[36:37], v[34:35], off
	s_add_i32 s36, s83, s36
	v_mov_b32_e32 v35, s36
	s_cmp_gt_i32 s41, 0
	global_load_dwordx4 v[12:15], v[200:201], off
	global_load_dwordx4 v[4:7], v[200:201], off offset:128
	global_load_dwordx4 v[8:11], v[198:199], off
	global_load_dwordx4 v[0:3], v[198:199], off offset:128
	s_waitcnt vmcnt(4)
	ds_write_b64 v16, v[36:37]
	s_waitcnt lgkmcnt(0)
	s_barrier
	ds_read_b128 v[36:39], v35
	ds_read_b128 v[40:43], v35 offset:16
	ds_read_b128 v[44:47], v35 offset:32
	ds_read_b128 v[96:99], v35 offset:48
	s_waitcnt lgkmcnt(3)
	v_mul_f32_e32 v16, v31, v37
	v_mul_f32_e32 v34, v30, v39
	s_waitcnt lgkmcnt(2)
	v_mul_f32_e32 v37, v27, v41
	v_mul_f32_e32 v39, v32, v43
	v_fmac_f32_e32 v16, v28, v36
	v_fmac_f32_e32 v34, v26, v38
	s_waitcnt lgkmcnt(1)
	v_mul_f32_e32 v41, v19, v45
	v_mul_f32_e32 v43, v25, v47
	v_fmac_f32_e32 v37, v23, v40
	v_fmac_f32_e32 v39, v29, v42
	v_add_f32_e32 v16, v16, v34
	v_fmac_f32_e32 v41, v24, v44
	v_fmac_f32_e32 v43, v22, v46
	v_add_f32_e32 v34, v37, v39
	v_add_f32_e32 v16, v33, v16
	v_add_f32_e32 v36, v41, v43
	v_add_f32_e32 v16, v16, v34
	v_add_f32_e32 v16, v16, v36
	s_waitcnt lgkmcnt(0)
	ds_read_b128 v[166:169], v35 offset:64
	ds_read_b128 v[170:173], v35 offset:80
	ds_read_b128 v[174:177], v35 offset:96
	ds_read_b128 v[178:181], v35 offset:112
	v_mul_f32_e32 v34, v17, v97
	v_mul_f32_e32 v36, v21, v99
	v_fmac_f32_e32 v34, v20, v96
	v_fmac_f32_e32 v36, v18, v98
	v_add_f32_e32 v34, v34, v36
	v_add_f32_e32 v16, v16, v34
	v_mul_f32_e64 v34, |v16|, s84
	v_exp_f32_e32 v34, v34
	v_min_f32_e32 v16, 0, v16
	v_add_f32_e32 v34, 1.0, v34
	v_cmp_gt_f32_e32 vcc, s85, v34
	s_nop 1
	v_cndmask_b32_e64 v36, 0, 32, vcc
	v_ldexp_f32 v34, v34, v36
	v_log_f32_e32 v36, v34
	v_add_u32_e32 v34, 0, v48
	v_mul_f32_e32 v37, 0x3f317217, v36
	v_fma_f32 v37, v36, s86, -v37
	v_fmac_f32_e32 v37, 0x3377d1cf, v36
	v_fmac_f32_e32 v37, 0x3f317217, v36
	v_cmp_lt_f32_e64 s[36:37], |v36|, s87
	s_nop 1
	v_cndmask_b32_e64 v36, v36, v37, s[36:37]
	v_cndmask_b32_e32 v37, 0, v95, vcc
	v_sub_f32_e32 v36, v36, v37
	v_sub_f32_e32 v16, v16, v36
	s_mul_i32 s36, s41, 0x2100
	v_fma_f32 v36, v16, s88, 0
	v_add_u32_e32 v16, s36, v34
	ds_write_b32 v16, v36
	s_waitcnt lgkmcnt(3)
	v_mul_f32_e32 v37, v31, v167
	v_fmac_f32_e32 v37, v28, v166
	v_mul_f32_e32 v38, v30, v169
	v_fmac_f32_e32 v38, v26, v168
	v_add_f32_e32 v37, v37, v38
	s_waitcnt lgkmcnt(2)
; #define LAS __attribute__((address_space(3)))
; __device__ __forceinline__ void gla_cumdecay(const Ptrs& A, int l, int n, int hd, LAS float* bl, const int wv0) {
;     ...
;     const LAS float* ga = gal + 16 * tq * 16;
;     float run = 0.f;
;     for (int tt = 0; tt < 16; ++tt) {
;         float pre = bias;
;         const f32x4 g0 = *(const LAS f32x4*)(ga + tt * 16), g1 = *(const LAS f32x4*)(ga + tt * 16 + 4), g2 = *(const LAS f32x4*)(ga + tt * 16 + 8), g3 = *(const LAS f32x4*)(ga + tt * 16 + 12);
;         pre += (g0.x * w[0] + g0.y * w[1]) + (g0.z * w[2] + g0.w * w[3]); pre += (g1.x * w[4] + g1.y * w[5]) + (g1.z * w[6] + g1.w * w[7]);
;         pre += (g2.x * w[8] + g2.y * w[9]) + (g2.z * w[10] + g2.w * w[11]); pre += (g3.x * w[12] + g3.y * w[13]) + (g3.z * w[14] + g3.w * w[15]);
;         const float la = (fminf(pre, 0.f) - __logf(1.0f + __expf(-fabsf(pre)))) * (1.0f / 16.0f);
;         run += la; bl[(16 * tq + tt) * BLS + d] = run;
;     }
	v_mul_f32_e32 v38, v27, v171
	v_mul_f32_e32 v39, v32, v173
	v_fmac_f32_e32 v38, v23, v170
	v_fmac_f32_e32 v39, v29, v172
	v_add_f32_e32 v37, v33, v37
	v_add_f32_e32 v38, v38, v39
	v_add_f32_e32 v37, v37, v38
	s_waitcnt lgkmcnt(1)
	v_mul_f32_e32 v38, v19, v175
	v_mul_f32_e32 v39, v25, v177
	v_fmac_f32_e32 v38, v24, v174
	v_fmac_f32_e32 v39, v22, v176
	v_add_f32_e32 v38, v38, v39
	v_add_f32_e32 v37, v37, v38
	s_waitcnt lgkmcnt(0)
	ds_read_b128 v[150:153], v35 offset:128
	ds_read_b128 v[154:157], v35 offset:144
	ds_read_b128 v[158:161], v35 offset:160
	ds_read_b128 v[162:165], v35 offset:176
	v_mul_f32_e32 v38, v17, v179
	v_mul_f32_e32 v39, v21, v181
	v_fmac_f32_e32 v38, v20, v178
	v_fmac_f32_e32 v39, v18, v180
	v_add_f32_e32 v38, v38, v39
	v_add_f32_e32 v37, v37, v38
	v_mul_f32_e64 v38, |v37|, s84
	v_exp_f32_e32 v38, v38
	v_min_f32_e32 v37, 0, v37
	v_add_f32_e32 v38, 1.0, v38
	v_cmp_gt_f32_e32 vcc, s85, v38
	s_nop 1
	v_cndmask_b32_e64 v39, 0, 32, vcc
	v_ldexp_f32 v38, v38, v39
	v_log_f32_e32 v38, v38
	s_nop 0
	v_mul_f32_e32 v39, 0x3f317217, v38
	v_fma_f32 v39, v38, s86, -v39
	v_fmac_f32_e32 v39, 0x3377d1cf, v38
	v_fmac_f32_e32 v39, 0x3f317217, v38
	v_cmp_lt_f32_e64 s[36:37], |v38|, s87
	s_nop 1
	v_cndmask_b32_e64 v38, v38, v39, s[36:37]
	v_cndmask_b32_e32 v39, 0, v95, vcc
	v_sub_f32_e32 v38, v38, v39
	v_sub_f32_e32 v37, v37, v38
	v_fmac_f32_e32 v36, 0x3d800000, v37
	ds_write_b32 v16, v36 offset:528
	s_waitcnt lgkmcnt(3)
	v_mul_f32_e32 v37, v31, v151
	v_fmac_f32_e32 v37, v28, v150
	v_mul_f32_e32 v38, v30, v153
	v_fmac_f32_e32 v38, v26, v152
	v_add_f32_e32 v37, v37, v38
	s_waitcnt lgkmcnt(2)
	v_mul_f32_e32 v38, v27, v155
	v_mul_f32_e32 v39, v32, v157
	v_fmac_f32_e32 v38, v23, v154
	v_fmac_f32_e32 v39, v29, v156
	v_add_f32_e32 v37, v33, v37
	v_add_f32_e32 v38, v38, v39
	v_add_f32_e32 v37, v37, v38
	s_waitcnt lgkmcnt(1)
	v_mul_f32_e32 v38, v19, v159
	v_mul_f32_e32 v39, v25, v161
	v_fmac_f32_e32 v38, v24, v158
	v_fmac_f32_e32 v39, v22, v160
	v_add_f32_e32 v38, v38, v39
	v_add_f32_e32 v37, v37, v38
	s_waitcnt lgkmcnt(0)
	ds_read_b128 v[166:169], v35 offset:192
	ds_read_b128 v[170:173], v35 offset:208
	ds_read_b128 v[174:177], v35 offset:224
	ds_read_b128 v[178:181], v35 offset:240
	v_mul_f32_e32 v38, v17, v163
	v_mul_f32_e32 v39, v21, v165
	v_fmac_f32_e32 v38, v20, v162
	v_fmac_f32_e32 v39, v18, v164
	v_add_f32_e32 v38, v38, v39
	v_add_f32_e32 v37, v37, v38
	v_mul_f32_e64 v38, |v37|, s84
	v_exp_f32_e32 v38, v38
	v_min_f32_e32 v37, 0, v37
	v_add_f32_e32 v38, 1.0, v38
	v_cmp_gt_f32_e32 vcc, s85, v38
	s_nop 1
	v_cndmask_b32_e64 v39, 0, 32, vcc
	v_ldexp_f32 v38, v38, v39
	v_log_f32_e32 v38, v38
	s_nop 0
	v_mul_f32_e32 v39, 0x3f317217, v38
	v_fma_f32 v39, v38, s86, -v39
	v_fmac_f32_e32 v39, 0x3377d1cf, v38
	v_fmac_f32_e32 v39, 0x3f317217, v38
	v_cmp_lt_f32_e64 s[36:37], |v38|, s87
	s_nop 1
	v_cndmask_b32_e64 v38, v38, v39, s[36:37]
	v_cndmask_b32_e32 v39, 0, v95, vcc
	v_sub_f32_e32 v38, v38, v39
	v_sub_f32_e32 v37, v37, v38
	v_fmac_f32_e32 v36, 0x3d800000, v37
	ds_write_b32 v16, v36 offset:1056
	s_waitcnt lgkmcnt(3)
	v_mul_f32_e32 v37, v31, v167
	v_fmac_f32_e32 v37, v28, v166
	v_mul_f32_e32 v38, v30, v169
	v_fmac_f32_e32 v38, v26, v168
	v_add_f32_e32 v37, v37, v38
	s_waitcnt lgkmcnt(2)
	v_mul_f32_e32 v38, v27, v171
	v_mul_f32_e32 v39, v32, v173
	v_fmac_f32_e32 v38, v23, v170
	v_fmac_f32_e32 v39, v29, v172
	v_add_f32_e32 v37, v33, v37
	v_add_f32_e32 v38, v38, v39
	v_add_f32_e32 v37, v37, v38
	s_waitcnt lgkmcnt(1)
	v_mul_f32_e32 v38, v19, v175
	v_mul_f32_e32 v39, v25, v177
	v_fmac_f32_e32 v38, v24, v174
	v_fmac_f32_e32 v39, v22, v176
	v_add_f32_e32 v38, v38, v39
	v_add_f32_e32 v37, v37, v38
	s_waitcnt lgkmcnt(0)
	ds_read_b128 v[150:153], v35 offset:256
	ds_read_b128 v[154:157], v35 offset:272
	ds_read_b128 v[158:161], v35 offset:288
	ds_read_b128 v[162:165], v35 offset:304
	v_mul_f32_e32 v38, v17, v179
	v_mul_f32_e32 v39, v21, v181
	v_fmac_f32_e32 v38, v20, v178
	v_fmac_f32_e32 v39, v18, v180
	v_add_f32_e32 v38, v38, v39
	v_add_f32_e32 v37, v37, v38
	v_mul_f32_e64 v38, |v37|, s84
	v_exp_f32_e32 v38, v38
	v_min_f32_e32 v37, 0, v37
	v_add_f32_e32 v38, 1.0, v38
	v_cmp_gt_f32_e32 vcc, s85, v38
	s_nop 1
	v_cndmask_b32_e64 v39, 0, 32, vcc
	v_ldexp_f32 v38, v38, v39
	v_log_f32_e32 v38, v38
	s_nop 0
	v_mul_f32_e32 v39, 0x3f317217, v38
	v_fma_f32 v39, v38, s86, -v39
	v_fmac_f32_e32 v39, 0x3377d1cf, v38
	v_fmac_f32_e32 v39, 0x3f317217, v38
	v_cmp_lt_f32_e64 s[36:37], |v38|, s87
	s_nop 1
	v_cndmask_b32_e64 v38, v38, v39, s[36:37]
	v_cndmask_b32_e32 v39, 0, v95, vcc
	v_sub_f32_e32 v38, v38, v39
	v_sub_f32_e32 v37, v37, v38
	v_fmac_f32_e32 v36, 0x3d800000, v37
	ds_write_b32 v16, v36 offset:1584
	s_waitcnt lgkmcnt(3)
	v_mul_f32_e32 v37, v31, v151
	v_fmac_f32_e32 v37, v28, v150
	v_mul_f32_e32 v38, v30, v153
	v_fmac_f32_e32 v38, v26, v152
	v_add_f32_e32 v37, v37, v38
	s_waitcnt lgkmcnt(2)
	v_mul_f32_e32 v38, v27, v155
	v_mul_f32_e32 v39, v32, v157
	v_fmac_f32_e32 v38, v23, v154
	v_fmac_f32_e32 v39, v29, v156
	v_add_f32_e32 v37, v33, v37
	v_add_f32_e32 v38, v38, v39
	v_add_f32_e32 v37, v37, v38
	s_waitcnt lgkmcnt(1)
	v_mul_f32_e32 v38, v19, v159
	v_mul_f32_e32 v39, v25, v161
	v_fmac_f32_e32 v38, v24, v158
	v_fmac_f32_e32 v39, v22, v160
	v_add_f32_e32 v38, v38, v39
	v_add_f32_e32 v37, v37, v38
	s_waitcnt lgkmcnt(0)
; #define LAS __attribute__((address_space(3)))
; __device__ __forceinline__ void gla_cumdecay(const Ptrs& A, int l, int n, int hd, LAS float* bl, const int wv0) {
;     ...
;     const LAS float* ga = gal + 16 * tq * 16;
;     float run = 0.f;
;     for (int tt = 0; tt < 16; ++tt) {
;         float pre = bias;
;         const f32x4 g0 = *(const LAS f32x4*)(ga + tt * 16), g1 = *(const LAS f32x4*)(ga + tt * 16 + 4), g2 = *(const LAS f32x4*)(ga + tt * 16 + 8), g3 = *(const LAS f32x4*)(ga + tt * 16 + 12);
;         pre += (g0.x * w[0] + g0.y * w[1]) + (g0.z * w[2] + g0.w * w[3]); pre += (g1.x * w[4] + g1.y * w[5]) + (g1.z * w[6] + g1.w * w[7]);
;         pre += (g2.x * w[8] + g2.y * w[9]) + (g2.z * w[10] + g2.w * w[11]); pre += (g3.x * w[12] + g3.y * w[13]) + (g3.z * w[14] + g3.w * w[15]);
;         const float la = (fminf(pre, 0.f) - __logf(1.0f + __expf(-fabsf(pre)))) * (1.0f / 16.0f);
;         run += la; bl[(16 * tq + tt) * BLS + d] = run;
;     }
	ds_read_b128 v[166:169], v35 offset:320
	ds_read_b128 v[170:173], v35 offset:336
	ds_read_b128 v[174:177], v35 offset:352
	ds_read_b128 v[178:181], v35 offset:368
	v_mul_f32_e32 v38, v17, v163
	v_mul_f32_e32 v39, v21, v165
	v_fmac_f32_e32 v38, v20, v162
	v_fmac_f32_e32 v39, v18, v164
	v_add_f32_e32 v38, v38, v39
	v_add_f32_e32 v37, v37, v38
	v_mul_f32_e64 v38, |v37|, s84
	v_exp_f32_e32 v38, v38
	v_min_f32_e32 v37, 0, v37
	v_add_f32_e32 v38, 1.0, v38
	v_cmp_gt_f32_e32 vcc, s85, v38
	s_nop 1
	v_cndmask_b32_e64 v39, 0, 32, vcc
	v_ldexp_f32 v38, v38, v39
	v_log_f32_e32 v38, v38
	s_nop 0
	v_mul_f32_e32 v39, 0x3f317217, v38
	v_fma_f32 v39, v38, s86, -v39
	v_fmac_f32_e32 v39, 0x3377d1cf, v38
	v_fmac_f32_e32 v39, 0x3f317217, v38
	v_cmp_lt_f32_e64 s[36:37], |v38|, s87
	s_nop 1
	v_cndmask_b32_e64 v38, v38, v39, s[36:37]
	v_cndmask_b32_e32 v39, 0, v95, vcc
	v_sub_f32_e32 v38, v38, v39
	v_sub_f32_e32 v37, v37, v38
	v_fmac_f32_e32 v36, 0x3d800000, v37
	ds_write_b32 v16, v36 offset:2112
	s_waitcnt lgkmcnt(3)
	v_mul_f32_e32 v37, v31, v167
	v_fmac_f32_e32 v37, v28, v166
	v_mul_f32_e32 v38, v30, v169
	v_fmac_f32_e32 v38, v26, v168
	v_add_f32_e32 v37, v37, v38
	s_waitcnt lgkmcnt(2)
	v_mul_f32_e32 v38, v27, v171
	v_mul_f32_e32 v39, v32, v173
	v_fmac_f32_e32 v38, v23, v170
	v_fmac_f32_e32 v39, v29, v172
	v_add_f32_e32 v37, v33, v37
	v_add_f32_e32 v38, v38, v39
	v_add_f32_e32 v37, v37, v38
	s_waitcnt lgkmcnt(1)
	v_mul_f32_e32 v38, v19, v175
	v_mul_f32_e32 v39, v25, v177
	v_fmac_f32_e32 v38, v24, v174
	v_fmac_f32_e32 v39, v22, v176
	v_add_f32_e32 v38, v38, v39
	v_add_f32_e32 v37, v37, v38
	s_waitcnt lgkmcnt(0)
	ds_read_b128 v[150:153], v35 offset:384
	ds_read_b128 v[154:157], v35 offset:400
	ds_read_b128 v[158:161], v35 offset:416
	ds_read_b128 v[162:165], v35 offset:432
	v_mul_f32_e32 v38, v17, v179
	v_mul_f32_e32 v39, v21, v181
	v_fmac_f32_e32 v38, v20, v178
	v_fmac_f32_e32 v39, v18, v180
	v_add_f32_e32 v38, v38, v39
	v_add_f32_e32 v37, v37, v38
	v_mul_f32_e64 v38, |v37|, s84
	v_exp_f32_e32 v38, v38
	v_min_f32_e32 v37, 0, v37
	v_add_f32_e32 v38, 1.0, v38
	v_cmp_gt_f32_e32 vcc, s85, v38
	s_nop 1
	v_cndmask_b32_e64 v39, 0, 32, vcc
	v_ldexp_f32 v38, v38, v39
	v_log_f32_e32 v38, v38
	s_nop 0
	v_mul_f32_e32 v39, 0x3f317217, v38
	v_fma_f32 v39, v38, s86, -v39
	v_fmac_f32_e32 v39, 0x3377d1cf, v38
	v_fmac_f32_e32 v39, 0x3f317217, v38
	v_cmp_lt_f32_e64 s[36:37], |v38|, s87
	s_nop 1
	v_cndmask_b32_e64 v38, v38, v39, s[36:37]
	v_cndmask_b32_e32 v39, 0, v95, vcc
	v_sub_f32_e32 v38, v38, v39
	v_sub_f32_e32 v37, v37, v38
	v_fmac_f32_e32 v36, 0x3d800000, v37
	ds_write_b32 v16, v36 offset:2640
	s_waitcnt lgkmcnt(3)
	v_mul_f32_e32 v37, v31, v151
	v_fmac_f32_e32 v37, v28, v150
	v_mul_f32_e32 v38, v30, v153
	v_fmac_f32_e32 v38, v26, v152
	v_add_f32_e32 v37, v37, v38
	s_waitcnt lgkmcnt(2)
	v_mul_f32_e32 v38, v27, v155
	v_mul_f32_e32 v39, v32, v157
	v_fmac_f32_e32 v38, v23, v154
	v_fmac_f32_e32 v39, v29, v156
	v_add_f32_e32 v37, v33, v37
	v_add_f32_e32 v38, v38, v39
	v_add_f32_e32 v37, v37, v38
	s_waitcnt lgkmcnt(1)
	v_mul_f32_e32 v38, v19, v159
	v_mul_f32_e32 v39, v25, v161
	v_fmac_f32_e32 v38, v24, v158
	v_fmac_f32_e32 v39, v22, v160
	v_add_f32_e32 v38, v38, v39
	v_add_f32_e32 v37, v37, v38
	s_waitcnt lgkmcnt(0)
	ds_read_b128 v[166:169], v35 offset:448
	ds_read_b128 v[170:173], v35 offset:464
	ds_read_b128 v[174:177], v35 offset:480
	ds_read_b128 v[178:181], v35 offset:496
	v_mul_f32_e32 v38, v17, v163
	v_mul_f32_e32 v39, v21, v165
	v_fmac_f32_e32 v38, v20, v162
	v_fmac_f32_e32 v39, v18, v164
	v_add_f32_e32 v38, v38, v39
	v_add_f32_e32 v37, v37, v38
	v_mul_f32_e64 v38, |v37|, s84
	v_exp_f32_e32 v38, v38
	v_min_f32_e32 v37, 0, v37
	v_add_f32_e32 v38, 1.0, v38
	v_cmp_gt_f32_e32 vcc, s85, v38
	s_nop 1
	v_cndmask_b32_e64 v39, 0, 32, vcc
	v_ldexp_f32 v38, v38, v39
	v_log_f32_e32 v38, v38
	s_nop 0
	v_mul_f32_e32 v39, 0x3f317217, v38
	v_fma_f32 v39, v38, s86, -v39
	v_fmac_f32_e32 v39, 0x3377d1cf, v38
	v_fmac_f32_e32 v39, 0x3f317217, v38
	v_cmp_lt_f32_e64 s[36:37], |v38|, s87
	s_nop 1
	v_cndmask_b32_e64 v38, v38, v39, s[36:37]
	v_cndmask_b32_e32 v39, 0, v95, vcc
	v_sub_f32_e32 v38, v38, v39
	v_sub_f32_e32 v37, v37, v38
	v_fmac_f32_e32 v36, 0x3d800000, v37
	ds_write_b32 v16, v36 offset:3168
	s_waitcnt lgkmcnt(3)
	v_mul_f32_e32 v37, v31, v167
	v_fmac_f32_e32 v37, v28, v166
	v_mul_f32_e32 v38, v30, v169
	v_fmac_f32_e32 v38, v26, v168
	v_add_f32_e32 v37, v37, v38
	s_waitcnt lgkmcnt(2)
	v_mul_f32_e32 v38, v27, v171
	v_mul_f32_e32 v39, v32, v173
	v_fmac_f32_e32 v38, v23, v170
	v_fmac_f32_e32 v39, v29, v172
	v_add_f32_e32 v37, v33, v37
	v_add_f32_e32 v38, v38, v39
	v_add_f32_e32 v37, v37, v38
	s_waitcnt lgkmcnt(1)
	v_mul_f32_e32 v38, v19, v175
	v_mul_f32_e32 v39, v25, v177
	v_fmac_f32_e32 v38, v24, v174
	v_fmac_f32_e32 v39, v22, v176
	v_add_f32_e32 v38, v38, v39
	v_add_f32_e32 v37, v37, v38
	s_waitcnt lgkmcnt(0)
	ds_read_b128 v[150:153], v35 offset:512
	ds_read_b128 v[154:157], v35 offset:528
	ds_read_b128 v[158:161], v35 offset:544
	ds_read_b128 v[162:165], v35 offset:560
	v_mul_f32_e32 v38, v17, v179
	v_mul_f32_e32 v39, v21, v181
	v_fmac_f32_e32 v38, v20, v178
	v_fmac_f32_e32 v39, v18, v180
	v_add_f32_e32 v38, v38, v39
	v_add_f32_e32 v37, v37, v38
	v_mul_f32_e64 v38, |v37|, s84
	v_exp_f32_e32 v38, v38
	v_min_f32_e32 v37, 0, v37
	v_add_f32_e32 v38, 1.0, v38
	v_cmp_gt_f32_e32 vcc, s85, v38
	s_nop 1
	v_cndmask_b32_e64 v39, 0, 32, vcc
	v_ldexp_f32 v38, v38, v39
	v_log_f32_e32 v38, v38
	s_nop 0
	v_mul_f32_e32 v39, 0x3f317217, v38
	v_fma_f32 v39, v38, s86, -v39
	v_fmac_f32_e32 v39, 0x3377d1cf, v38
	v_fmac_f32_e32 v39, 0x3f317217, v38
	v_cmp_lt_f32_e64 s[36:37], |v38|, s87
	s_nop 1
	v_cndmask_b32_e64 v38, v38, v39, s[36:37]
	v_cndmask_b32_e32 v39, 0, v95, vcc
	v_sub_f32_e32 v38, v38, v39
	v_sub_f32_e32 v37, v37, v38
	v_fmac_f32_e32 v36, 0x3d800000, v37
	ds_write_b32 v16, v36 offset:3696
	s_waitcnt lgkmcnt(3)
; #define LAS __attribute__((address_space(3)))
; __device__ __forceinline__ void gla_cumdecay(const Ptrs& A, int l, int n, int hd, LAS float* bl, const int wv0) {
;     ...
;     const LAS float* ga = gal + 16 * tq * 16;
;     float run = 0.f;
;     for (int tt = 0; tt < 16; ++tt) {
;         float pre = bias;
;         const f32x4 g0 = *(const LAS f32x4*)(ga + tt * 16), g1 = *(const LAS f32x4*)(ga + tt * 16 + 4), g2 = *(const LAS f32x4*)(ga + tt * 16 + 8), g3 = *(const LAS f32x4*)(ga + tt * 16 + 12);
;         pre += (g0.x * w[0] + g0.y * w[1]) + (g0.z * w[2] + g0.w * w[3]); pre += (g1.x * w[4] + g1.y * w[5]) + (g1.z * w[6] + g1.w * w[7]);
;         pre += (g2.x * w[8] + g2.y * w[9]) + (g2.z * w[10] + g2.w * w[11]); pre += (g3.x * w[12] + g3.y * w[13]) + (g3.z * w[14] + g3.w * w[15]);
;         const float la = (fminf(pre, 0.f) - __logf(1.0f + __expf(-fabsf(pre)))) * (1.0f / 16.0f);
;         run += la; bl[(16 * tq + tt) * BLS + d] = run;
;     }
	v_mul_f32_e32 v37, v31, v151
	v_fmac_f32_e32 v37, v28, v150
	v_mul_f32_e32 v38, v30, v153
	v_fmac_f32_e32 v38, v26, v152
	v_add_f32_e32 v37, v37, v38
	s_waitcnt lgkmcnt(2)
	v_mul_f32_e32 v38, v27, v155
	v_mul_f32_e32 v39, v32, v157
	v_fmac_f32_e32 v38, v23, v154
	v_fmac_f32_e32 v39, v29, v156
	v_add_f32_e32 v37, v33, v37
	v_add_f32_e32 v38, v38, v39
	v_add_f32_e32 v37, v37, v38
	s_waitcnt lgkmcnt(1)
	v_mul_f32_e32 v38, v19, v159
	v_mul_f32_e32 v39, v25, v161
	v_fmac_f32_e32 v38, v24, v158
	v_fmac_f32_e32 v39, v22, v160
	v_add_f32_e32 v38, v38, v39
	v_add_f32_e32 v37, v37, v38
	s_waitcnt lgkmcnt(0)
	ds_read_b128 v[166:169], v35 offset:576
	ds_read_b128 v[170:173], v35 offset:592
	ds_read_b128 v[174:177], v35 offset:608
	ds_read_b128 v[178:181], v35 offset:624
	v_mul_f32_e32 v38, v17, v163
	v_mul_f32_e32 v39, v21, v165
	v_fmac_f32_e32 v38, v20, v162
	v_fmac_f32_e32 v39, v18, v164
	v_add_f32_e32 v38, v38, v39
	v_add_f32_e32 v37, v37, v38
	v_mul_f32_e64 v38, |v37|, s84
	v_exp_f32_e32 v38, v38
	v_min_f32_e32 v37, 0, v37
	v_add_f32_e32 v38, 1.0, v38
	v_cmp_gt_f32_e32 vcc, s85, v38
	s_nop 1
	v_cndmask_b32_e64 v39, 0, 32, vcc
	v_ldexp_f32 v38, v38, v39
	v_log_f32_e32 v38, v38
	s_nop 0
	v_mul_f32_e32 v39, 0x3f317217, v38
	v_fma_f32 v39, v38, s86, -v39
	v_fmac_f32_e32 v39, 0x3377d1cf, v38
	v_fmac_f32_e32 v39, 0x3f317217, v38
	v_cmp_lt_f32_e64 s[36:37], |v38|, s87
	s_nop 1
	v_cndmask_b32_e64 v38, v38, v39, s[36:37]
	v_cndmask_b32_e32 v39, 0, v95, vcc
	v_sub_f32_e32 v38, v38, v39
	v_sub_f32_e32 v37, v37, v38
	v_fmac_f32_e32 v36, 0x3d800000, v37
	ds_write_b32 v16, v36 offset:4224
	s_waitcnt lgkmcnt(3)
	v_mul_f32_e32 v37, v31, v167
	v_fmac_f32_e32 v37, v28, v166
	v_mul_f32_e32 v38, v30, v169
	v_fmac_f32_e32 v38, v26, v168
	v_add_f32_e32 v37, v37, v38
	s_waitcnt lgkmcnt(2)
	v_mul_f32_e32 v38, v27, v171
	v_mul_f32_e32 v39, v32, v173
	v_fmac_f32_e32 v38, v23, v170
	v_fmac_f32_e32 v39, v29, v172
	v_add_f32_e32 v37, v33, v37
	v_add_f32_e32 v38, v38, v39
	v_add_f32_e32 v37, v37, v38
	s_waitcnt lgkmcnt(1)
	v_mul_f32_e32 v38, v19, v175
	v_mul_f32_e32 v39, v25, v177
	v_fmac_f32_e32 v38, v24, v174
	v_fmac_f32_e32 v39, v22, v176
	v_add_f32_e32 v38, v38, v39
	v_add_f32_e32 v37, v37, v38
	s_waitcnt lgkmcnt(0)
	ds_read_b128 v[150:153], v35 offset:640
	ds_read_b128 v[154:157], v35 offset:656
	ds_read_b128 v[158:161], v35 offset:672
	ds_read_b128 v[162:165], v35 offset:688
	v_mul_f32_e32 v38, v17, v179
	v_mul_f32_e32 v39, v21, v181
	v_fmac_f32_e32 v38, v20, v178
	v_fmac_f32_e32 v39, v18, v180
	v_add_f32_e32 v38, v38, v39
	v_add_f32_e32 v37, v37, v38
	v_mul_f32_e64 v38, |v37|, s84
	v_exp_f32_e32 v38, v38
	v_min_f32_e32 v37, 0, v37
	v_add_f32_e32 v38, 1.0, v38
	v_cmp_gt_f32_e32 vcc, s85, v38
	s_nop 1
	v_cndmask_b32_e64 v39, 0, 32, vcc
	v_ldexp_f32 v38, v38, v39
	v_log_f32_e32 v38, v38
	s_nop 0
	v_mul_f32_e32 v39, 0x3f317217, v38
	v_fma_f32 v39, v38, s86, -v39
	v_fmac_f32_e32 v39, 0x3377d1cf, v38
	v_fmac_f32_e32 v39, 0x3f317217, v38
	v_cmp_lt_f32_e64 s[36:37], |v38|, s87
	s_nop 1
	v_cndmask_b32_e64 v38, v38, v39, s[36:37]
	v_cndmask_b32_e32 v39, 0, v95, vcc
	v_sub_f32_e32 v38, v38, v39
	v_sub_f32_e32 v37, v37, v38
	v_fmac_f32_e32 v36, 0x3d800000, v37
	ds_write_b32 v16, v36 offset:4752
	s_waitcnt lgkmcnt(3)
	v_mul_f32_e32 v37, v31, v151
	v_fmac_f32_e32 v37, v28, v150
	v_mul_f32_e32 v38, v30, v153
	v_fmac_f32_e32 v38, v26, v152
	v_add_f32_e32 v37, v37, v38
	s_waitcnt lgkmcnt(2)
	v_mul_f32_e32 v38, v27, v155
	v_mul_f32_e32 v39, v32, v157
	v_fmac_f32_e32 v38, v23, v154
	v_fmac_f32_e32 v39, v29, v156
	v_add_f32_e32 v37, v33, v37
	v_add_f32_e32 v38, v38, v39
	v_add_f32_e32 v37, v37, v38
	s_waitcnt lgkmcnt(1)
	v_mul_f32_e32 v38, v19, v159
	v_mul_f32_e32 v39, v25, v161
	v_fmac_f32_e32 v38, v24, v158
	v_fmac_f32_e32 v39, v22, v160
	v_add_f32_e32 v38, v38, v39
	v_add_f32_e32 v37, v37, v38
	s_waitcnt lgkmcnt(0)
	ds_read_b128 v[166:169], v35 offset:704
	ds_read_b128 v[170:173], v35 offset:720
	ds_read_b128 v[174:177], v35 offset:736
	ds_read_b128 v[178:181], v35 offset:752
	v_mul_f32_e32 v38, v17, v163
	v_mul_f32_e32 v39, v21, v165
	v_fmac_f32_e32 v38, v20, v162
	v_fmac_f32_e32 v39, v18, v164
	v_add_f32_e32 v38, v38, v39
	v_add_f32_e32 v37, v37, v38
	v_mul_f32_e64 v38, |v37|, s84
	v_exp_f32_e32 v38, v38
	v_min_f32_e32 v37, 0, v37
	v_add_f32_e32 v38, 1.0, v38
	v_cmp_gt_f32_e32 vcc, s85, v38
	s_nop 1
	v_cndmask_b32_e64 v39, 0, 32, vcc
	v_ldexp_f32 v38, v38, v39
	v_log_f32_e32 v38, v38
	s_nop 0
	v_mul_f32_e32 v39, 0x3f317217, v38
	v_fma_f32 v39, v38, s86, -v39
	v_fmac_f32_e32 v39, 0x3377d1cf, v38
	v_fmac_f32_e32 v39, 0x3f317217, v38
	v_cmp_lt_f32_e64 s[36:37], |v38|, s87
	s_nop 1
	v_cndmask_b32_e64 v38, v38, v39, s[36:37]
	v_cndmask_b32_e32 v39, 0, v95, vcc
	v_sub_f32_e32 v38, v38, v39
	v_sub_f32_e32 v37, v37, v38
	v_fmac_f32_e32 v36, 0x3d800000, v37
	ds_write_b32 v16, v36 offset:5280
	s_waitcnt lgkmcnt(3)
	v_mul_f32_e32 v37, v31, v167
	v_fmac_f32_e32 v37, v28, v166
	v_mul_f32_e32 v38, v30, v169
	v_fmac_f32_e32 v38, v26, v168
	v_add_f32_e32 v37, v37, v38
	s_waitcnt lgkmcnt(2)
	v_mul_f32_e32 v38, v27, v171
	v_mul_f32_e32 v39, v32, v173
	v_fmac_f32_e32 v38, v23, v170
	v_fmac_f32_e32 v39, v29, v172
	v_add_f32_e32 v37, v33, v37
	v_add_f32_e32 v38, v38, v39
	v_add_f32_e32 v37, v37, v38
	s_waitcnt lgkmcnt(1)
	v_mul_f32_e32 v38, v19, v175
	v_mul_f32_e32 v39, v25, v177
	v_fmac_f32_e32 v38, v24, v174
	v_fmac_f32_e32 v39, v22, v176
	v_add_f32_e32 v38, v38, v39
	v_add_f32_e32 v37, v37, v38
	s_waitcnt lgkmcnt(0)
; #define LAS __attribute__((address_space(3)))
; __device__ __forceinline__ void gla_cumdecay(const Ptrs& A, int l, int n, int hd, LAS float* bl, const int wv0) {
;     ...
;     const LAS float* ga = gal + 16 * tq * 16;
;     float run = 0.f;
;     for (int tt = 0; tt < 16; ++tt) {
;         float pre = bias;
;         const f32x4 g0 = *(const LAS f32x4*)(ga + tt * 16), g1 = *(const LAS f32x4*)(ga + tt * 16 + 4), g2 = *(const LAS f32x4*)(ga + tt * 16 + 8), g3 = *(const LAS f32x4*)(ga + tt * 16 + 12);
;         pre += (g0.x * w[0] + g0.y * w[1]) + (g0.z * w[2] + g0.w * w[3]); pre += (g1.x * w[4] + g1.y * w[5]) + (g1.z * w[6] + g1.w * w[7]);
;         pre += (g2.x * w[8] + g2.y * w[9]) + (g2.z * w[10] + g2.w * w[11]); pre += (g3.x * w[12] + g3.y * w[13]) + (g3.z * w[14] + g3.w * w[15]);
;         const float la = (fminf(pre, 0.f) - __logf(1.0f + __expf(-fabsf(pre)))) * (1.0f / 16.0f);
;         run += la; bl[(16 * tq + tt) * BLS + d] = run;
;     }
	ds_read_b128 v[150:153], v35 offset:768
	ds_read_b128 v[154:157], v35 offset:784
	ds_read_b128 v[158:161], v35 offset:800
	ds_read_b128 v[162:165], v35 offset:816
	v_mul_f32_e32 v38, v17, v179
	v_mul_f32_e32 v39, v21, v181
	v_fmac_f32_e32 v38, v20, v178
	v_fmac_f32_e32 v39, v18, v180
	v_add_f32_e32 v38, v38, v39
	v_add_f32_e32 v37, v37, v38
	v_mul_f32_e64 v38, |v37|, s84
	v_exp_f32_e32 v38, v38
	v_min_f32_e32 v37, 0, v37
	v_add_f32_e32 v38, 1.0, v38
	v_cmp_gt_f32_e32 vcc, s85, v38
	s_nop 1
	v_cndmask_b32_e64 v39, 0, 32, vcc
	v_ldexp_f32 v38, v38, v39
	v_log_f32_e32 v38, v38
	s_nop 0
	v_mul_f32_e32 v39, 0x3f317217, v38
	v_fma_f32 v39, v38, s86, -v39
	v_fmac_f32_e32 v39, 0x3377d1cf, v38
	v_fmac_f32_e32 v39, 0x3f317217, v38
	v_cmp_lt_f32_e64 s[36:37], |v38|, s87
	s_nop 1
	v_cndmask_b32_e64 v38, v38, v39, s[36:37]
	v_cndmask_b32_e32 v39, 0, v95, vcc
	v_sub_f32_e32 v38, v38, v39
	v_sub_f32_e32 v37, v37, v38
	v_fmac_f32_e32 v36, 0x3d800000, v37
	ds_write_b32 v16, v36 offset:5808
	s_waitcnt lgkmcnt(3)
	v_mul_f32_e32 v37, v31, v151
	v_fmac_f32_e32 v37, v28, v150
	v_mul_f32_e32 v38, v30, v153
	v_fmac_f32_e32 v38, v26, v152
	v_add_f32_e32 v37, v37, v38
	s_waitcnt lgkmcnt(2)
	v_mul_f32_e32 v38, v27, v155
	v_mul_f32_e32 v39, v32, v157
	v_fmac_f32_e32 v38, v23, v154
	v_fmac_f32_e32 v39, v29, v156
	v_add_f32_e32 v37, v33, v37
	v_add_f32_e32 v38, v38, v39
	v_add_f32_e32 v37, v37, v38
	s_waitcnt lgkmcnt(1)
	v_mul_f32_e32 v38, v19, v159
	v_mul_f32_e32 v39, v25, v161
	v_fmac_f32_e32 v38, v24, v158
	v_fmac_f32_e32 v39, v22, v160
	v_add_f32_e32 v38, v38, v39
	v_add_f32_e32 v37, v37, v38
	s_waitcnt lgkmcnt(0)
	ds_read_b128 v[166:169], v35 offset:832
	ds_read_b128 v[170:173], v35 offset:848
	ds_read_b128 v[174:177], v35 offset:864
	ds_read_b128 v[178:181], v35 offset:880
	v_mul_f32_e32 v38, v17, v163
	v_mul_f32_e32 v39, v21, v165
	v_fmac_f32_e32 v38, v20, v162
	v_fmac_f32_e32 v39, v18, v164
	v_add_f32_e32 v38, v38, v39
	v_add_f32_e32 v37, v37, v38
	v_mul_f32_e64 v38, |v37|, s84
	v_exp_f32_e32 v38, v38
	v_min_f32_e32 v37, 0, v37
	v_add_f32_e32 v38, 1.0, v38
	v_cmp_gt_f32_e32 vcc, s85, v38
	s_nop 1
	v_cndmask_b32_e64 v39, 0, 32, vcc
	v_ldexp_f32 v38, v38, v39
	v_log_f32_e32 v38, v38
	s_nop 0
	v_mul_f32_e32 v39, 0x3f317217, v38
	v_fma_f32 v39, v38, s86, -v39
	v_fmac_f32_e32 v39, 0x3377d1cf, v38
	v_fmac_f32_e32 v39, 0x3f317217, v38
	v_cmp_lt_f32_e64 s[36:37], |v38|, s87
	s_nop 1
	v_cndmask_b32_e64 v38, v38, v39, s[36:37]
	v_cndmask_b32_e32 v39, 0, v95, vcc
	v_sub_f32_e32 v38, v38, v39
	v_sub_f32_e32 v37, v37, v38
	v_fmac_f32_e32 v36, 0x3d800000, v37
	ds_write_b32 v16, v36 offset:6336
	s_waitcnt lgkmcnt(3)
	v_mul_f32_e32 v37, v31, v167
	v_fmac_f32_e32 v37, v28, v166
	v_mul_f32_e32 v38, v30, v169
	v_fmac_f32_e32 v38, v26, v168
	v_add_f32_e32 v37, v37, v38
	s_waitcnt lgkmcnt(2)
	v_mul_f32_e32 v38, v27, v171
	v_mul_f32_e32 v39, v32, v173
	v_fmac_f32_e32 v38, v23, v170
	v_fmac_f32_e32 v39, v29, v172
	v_add_f32_e32 v37, v33, v37
	v_add_f32_e32 v38, v38, v39
	v_add_f32_e32 v37, v37, v38
	s_waitcnt lgkmcnt(1)
	v_mul_f32_e32 v38, v19, v175
	v_mul_f32_e32 v39, v25, v177
	v_fmac_f32_e32 v38, v24, v174
	v_fmac_f32_e32 v39, v22, v176
	v_add_f32_e32 v38, v38, v39
	v_add_f32_e32 v37, v37, v38
	s_waitcnt lgkmcnt(0)
	ds_read_b128 v[150:153], v35 offset:896
	ds_read_b128 v[154:157], v35 offset:912
	ds_read_b128 v[158:161], v35 offset:928
	ds_read_b128 v[162:165], v35 offset:944
	v_mul_f32_e32 v38, v17, v179
	v_mul_f32_e32 v39, v21, v181
	v_fmac_f32_e32 v38, v20, v178
	v_fmac_f32_e32 v39, v18, v180
	v_add_f32_e32 v38, v38, v39
	v_add_f32_e32 v37, v37, v38
	v_mul_f32_e64 v38, |v37|, s84
	v_exp_f32_e32 v38, v38
	v_min_f32_e32 v37, 0, v37
	v_add_f32_e32 v38, 1.0, v38
	v_cmp_gt_f32_e32 vcc, s85, v38
	s_nop 1
	v_cndmask_b32_e64 v39, 0, 32, vcc
	v_ldexp_f32 v38, v38, v39
	v_log_f32_e32 v38, v38
	s_nop 0
	v_mul_f32_e32 v39, 0x3f317217, v38
	v_fma_f32 v39, v38, s86, -v39
	v_fmac_f32_e32 v39, 0x3377d1cf, v38
	v_fmac_f32_e32 v39, 0x3f317217, v38
	v_cmp_lt_f32_e64 s[36:37], |v38|, s87
	s_nop 1
	v_cndmask_b32_e64 v38, v38, v39, s[36:37]
	v_cndmask_b32_e32 v39, 0, v95, vcc
	v_sub_f32_e32 v38, v38, v39
	v_sub_f32_e32 v37, v37, v38
	v_fmac_f32_e32 v36, 0x3d800000, v37
	ds_write_b32 v16, v36 offset:6864
	s_waitcnt lgkmcnt(3)
; #define LAS __attribute__((address_space(3)))
; __device__ __forceinline__ void gla_cumdecay(const Ptrs& A, int l, int n, int hd, LAS float* bl, const int wv0) {
;     ...
;     for (int tt = 0; tt < 16; ++tt) {
;         float pre = bias;
;         const f32x4 g0 = *(const LAS f32x4*)(ga + tt * 16), g1 = *(const LAS f32x4*)(ga + tt * 16 + 4), g2 = *(const LAS f32x4*)(ga + tt * 16 + 8), g3 = *(const LAS f32x4*)(ga + tt * 16 + 12);
;         pre += (g0.x * w[0] + g0.y * w[1]) + (g0.z * w[2] + g0.w * w[3]); pre += (g1.x * w[4] + g1.y * w[5]) + (g1.z * w[6] + g1.w * w[7]);
;         pre += (g2.x * w[8] + g2.y * w[9]) + (g2.z * w[10] + g2.w * w[11]); pre += (g3.x * w[12] + g3.y * w[13]) + (g3.z * w[14] + g3.w * w[15]);
;         const float la = (fminf(pre, 0.f) - __logf(1.0f + __expf(-fabsf(pre)))) * (1.0f / 16.0f);
;         run += la; bl[(16 * tq + tt) * BLS + d] = run;
;     }
;     __syncthreads();
;     float add = 0.f;
; #pragma unroll
;     for (int q = 0; q < 3; ++q) if (q < tq) add += bl[(16 * q + 15) * BLS + d];
;     __syncthreads();
	v_mul_f32_e32 v37, v31, v151
	v_fmac_f32_e32 v37, v28, v150
	v_mul_f32_e32 v38, v30, v153
	v_fmac_f32_e32 v38, v26, v152
	v_add_f32_e32 v37, v37, v38
	s_waitcnt lgkmcnt(2)
	v_mul_f32_e32 v38, v27, v155
	v_mul_f32_e32 v39, v32, v157
	v_fmac_f32_e32 v38, v23, v154
	v_fmac_f32_e32 v39, v29, v156
	v_add_f32_e32 v37, v33, v37
	v_add_f32_e32 v38, v38, v39
	v_add_f32_e32 v37, v37, v38
	s_waitcnt lgkmcnt(1)
	v_mul_f32_e32 v38, v19, v159
	v_mul_f32_e32 v39, v25, v161
	v_fmac_f32_e32 v38, v24, v158
	v_fmac_f32_e32 v39, v22, v160
	v_add_f32_e32 v38, v38, v39
	v_add_f32_e32 v37, v37, v38
	s_waitcnt lgkmcnt(0)
	ds_read_b128 v[166:169], v35 offset:960
	ds_read_b128 v[170:173], v35 offset:976
	ds_read_b128 v[174:177], v35 offset:992
	ds_read_b128 v[178:181], v35 offset:1008
	v_mul_f32_e32 v38, v17, v163
	v_mul_f32_e32 v39, v21, v165
	v_fmac_f32_e32 v38, v20, v162
	v_fmac_f32_e32 v39, v18, v164
	v_add_f32_e32 v38, v38, v39
	v_add_f32_e32 v37, v37, v38
	v_mul_f32_e64 v38, |v37|, s84
	v_exp_f32_e32 v38, v38
	v_min_f32_e32 v37, 0, v37
	v_add_f32_e32 v38, 1.0, v38
	v_cmp_gt_f32_e32 vcc, s85, v38
	s_nop 1
	v_cndmask_b32_e64 v39, 0, 32, vcc
	v_ldexp_f32 v38, v38, v39
	v_log_f32_e32 v38, v38
	s_nop 0
	v_mul_f32_e32 v39, 0x3f317217, v38
	v_fma_f32 v39, v38, s86, -v39
	v_fmac_f32_e32 v39, 0x3377d1cf, v38
	v_fmac_f32_e32 v39, 0x3f317217, v38
	v_cmp_lt_f32_e64 s[36:37], |v38|, s87
	s_nop 1
	v_cndmask_b32_e64 v38, v38, v39, s[36:37]
	v_cndmask_b32_e32 v39, 0, v95, vcc
	v_sub_f32_e32 v38, v38, v39
	v_sub_f32_e32 v37, v37, v38
	v_fmac_f32_e32 v36, 0x3d800000, v37
	ds_write_b32 v16, v36 offset:7392
	s_waitcnt lgkmcnt(3)
	v_mul_f32_e32 v31, v31, v167
	v_fmac_f32_e32 v31, v28, v166
	v_mul_f32_e32 v28, v30, v169
	s_waitcnt lgkmcnt(2)
	v_mul_f32_e32 v27, v27, v171
	v_fmac_f32_e32 v28, v26, v168
	v_fmac_f32_e32 v27, v23, v170
	v_mul_f32_e32 v23, v32, v173
	s_waitcnt lgkmcnt(1)
	v_mul_f32_e32 v19, v19, v175
	v_add_f32_e32 v26, v31, v28
	v_fmac_f32_e32 v23, v29, v172
	v_fmac_f32_e32 v19, v24, v174
	v_mul_f32_e32 v24, v25, v177
	s_waitcnt lgkmcnt(0)
	v_mul_f32_e32 v17, v17, v179
	v_add_f32_e32 v26, v33, v26
	v_add_f32_e32 v23, v27, v23
	v_fmac_f32_e32 v24, v22, v176
	v_fmac_f32_e32 v17, v20, v178
	v_mul_f32_e32 v20, v21, v181
	v_add_f32_e32 v23, v26, v23
	v_add_f32_e32 v19, v19, v24
	v_fmac_f32_e32 v20, v18, v180
	v_add_f32_e32 v19, v23, v19
	v_add_f32_e32 v17, v17, v20
	v_add_f32_e32 v17, v19, v17
	v_mul_f32_e64 v18, |v17|, s84
	v_exp_f32_e32 v18, v18
	v_min_f32_e32 v17, 0, v17
	v_add_f32_e32 v18, 1.0, v18
	v_cmp_gt_f32_e32 vcc, s85, v18
	s_nop 1
	v_cndmask_b32_e64 v19, 0, 32, vcc
	v_ldexp_f32 v18, v18, v19
	v_log_f32_e32 v18, v18
	s_nop 0
	v_mul_f32_e32 v19, 0x3f317217, v18
	v_fma_f32 v19, v18, s86, -v19
	v_fmac_f32_e32 v19, 0x3377d1cf, v18
	v_fmac_f32_e32 v19, 0x3f317217, v18
	v_cmp_lt_f32_e64 s[36:37], |v18|, s87
	s_nop 1
	v_cndmask_b32_e64 v18, v18, v19, s[36:37]
	v_cndmask_b32_e32 v19, 0, v95, vcc
	v_sub_f32_e32 v18, v18, v19
	v_sub_f32_e32 v17, v17, v18
	s_cselect_b64 s[36:37], -1, 0
	v_fmac_f32_e32 v36, 0x3d800000, v17
	s_and_b64 vcc, exec, s[36:37]
	v_mov_b32_e32 v17, 0
	ds_write_b32 v16, v36 offset:7920
	s_waitcnt lgkmcnt(0)
	s_barrier
	s_cbranch_vccz .LBB0_1326
	ds_read_b32 v17, v34 offset:7920
	s_waitcnt lgkmcnt(0)
	v_add_f32_e32 v17, 0, v17

; #define LAS __attribute__((address_space(3)))
; __device__ __forceinline__ unsigned pk2(float lo, float hi) { return f2bf(lo) | (f2bf(hi) << 16); }
; __device__ __forceinline__ void gla_load_vt(const bf16* GVc, LAS bf16* VTl, int wave, int lane) {
;     u32x4 vv[4];
; #pragma unroll
;     for (int i = 0; i < 4; ++i) vv[i] = *(const u32x4*)(GVc + (size_t)lane * 1024 + (wave + 8 * i) * 8);
; #pragma unroll
;     for (int i = 0; i < 4; ++i) { const int v0 = (wave + 8 * i) * 8; LAS bf16* p = VTl + v0 * 72 + lane;
;         p[0] = (bf16)(vv[i].x & 0xffff); p[72] = (bf16)(vv[i].x >> 16); p[144] = (bf16)(vv[i].y & 0xffff); p[216] = (bf16)(vv[i].y >> 16);
;         p[288] = (bf16)(vv[i].z & 0xffff); p[360] = (bf16)(vv[i].z >> 16); p[432] = (bf16)(vv[i].w & 0xffff); p[504] = (bf16)(vv[i].w >> 16); }
; }
; __device__ __forceinline__ void gla_out(const Ptrs& A, int l, LAS unsigned char* lds, int c, int G, int wave, int lane_, const int wv0) {
;     ...
;         for (int i = 0; i < 2; ++i) { const int d0 = (wave + 8 * i) * 8; float xq[8], xk[8]; unpack8(qq[i], xq); unpack8(kk[i], xk);
;             const f32x4 b0 = *(const LAS f32x4*)(bl + lane * BLS + d0), b1 = *(const LAS f32x4*)(bl + lane * BLS + d0 + 4);
;             float eb[8]; eb[0] = __expf(b0.x); eb[1] = __expf(b0.y); eb[2] = __expf(b0.z); eb[3] = __expf(b0.w); eb[4] = __expf(b1.x); eb[5] = __expf(b1.y); eb[6] = __expf(b1.z); eb[7] = __expf(b1.w);
;             u32x4 oq, ok;
;             oq.x = pk2(xq[0] * 0.08838834764831845f * eb[0], xq[1] * 0.08838834764831845f * eb[1]); oq.y = pk2(xq[2] * 0.08838834764831845f * eb[2], xq[3] * 0.08838834764831845f * eb[3]);
;             oq.z = pk2(xq[4] * 0.08838834764831845f * eb[4], xq[5] * 0.08838834764831845f * eb[5]); oq.w = pk2(xq[6] * 0.08838834764831845f * eb[6], xq[7] * 0.08838834764831845f * eb[7]);
;             ok.x = pk2(xk[0] * __builtin_amdgcn_rcpf(eb[0]), xk[1] * __builtin_amdgcn_rcpf(eb[1])); ok.y = pk2(xk[2] * __builtin_amdgcn_rcpf(eb[2]), xk[3] * __builtin_amdgcn_rcpf(eb[3]));
;             ok.z = pk2(xk[4] * __builtin_amdgcn_rcpf(eb[4]), xk[5] * __builtin_amdgcn_rcpf(eb[5])); ok.w = pk2(xk[6] * __builtin_amdgcn_rcpf(eb[6]), xk[7] * __builtin_amdgcn_rcpf(eb[7]));
;             *(LAS u32x4*)(QE + lane * 136 + d0) = oq; *(LAS u32x4*)(KE + lane * 136 + d0) = ok; }
.LBB0_1332:
	s_ashr_i32 s69, s68, 31
	s_lshl_b64 s[36:37], s[68:69], 11
	s_add_u32 s36, s67, s36
	s_addc_u32 s37, s70, s37
	s_add_u32 s36, s36, s40
	s_addc_u32 s37, s37, 0
	v_mov_b32_e32 v59, v49
	v_lshl_add_u64 v[16:17], s[36:37], 0, v[58:59]
	v_lshl_add_u64 v[28:29], s[54:55], 1, v[16:17]
	s_waitcnt lgkmcnt(0)
	s_barrier
	global_load_dwordx4 v[16:19], v[28:29], off
	global_load_dwordx4 v[20:23], v[28:29], off offset:128
	global_load_dwordx4 v[24:27], v[28:29], off offset:256
	s_nop 0
	global_load_dwordx4 v[28:31], v[28:29], off offset:384
	s_waitcnt vmcnt(4)
	v_add_u32_e32 v44, s71, v63
	v_add_u32_e32 v45, s72, v63
	v_lshlrev_b32_e32 v33, 16, v13
	v_lshlrev_b32_e32 v32, 16, v12
	v_and_b32_e32 v13, 0xffff0000, v13
	v_and_b32_e32 v12, 0xffff0000, v12
	v_lshlrev_b32_e32 v35, 16, v15
	v_lshlrev_b32_e32 v34, 16, v14
	v_and_b32_e32 v15, 0xffff0000, v15
	v_and_b32_e32 v14, 0xffff0000, v14
	v_lshlrev_b32_e32 v37, 16, v9
	v_lshlrev_b32_e32 v36, 16, v8
	v_and_b32_e32 v39, 0xffff0000, v9
	v_and_b32_e32 v38, 0xffff0000, v8
	v_lshlrev_b32_e32 v41, 16, v11
	v_lshlrev_b32_e32 v40, 16, v10
	v_and_b32_e32 v43, 0xffff0000, v11
	v_and_b32_e32 v42, 0xffff0000, v10
	v_pk_mul_f32 v[32:33], v[32:33], s[66:67] op_sel_hi:[1,0]
	s_andn2_b64 vcc, exec, s[58:59]
	s_waitcnt vmcnt(3)
	ds_write_b16 v44, v16
	ds_write_b16_d16_hi v44, v16 offset:144
	ds_write_b16 v44, v17 offset:288
	ds_write_b16_d16_hi v44, v17 offset:432
	ds_write_b16 v44, v18 offset:576
	ds_write_b16_d16_hi v44, v18 offset:720
	ds_write_b16 v44, v19 offset:864
	ds_write_b16_d16_hi v44, v19 offset:1008
	s_waitcnt vmcnt(2)
	ds_write_b16 v45, v20
	ds_write_b16_d16_hi v45, v20 offset:144
	ds_write_b16 v45, v21 offset:288
	ds_write_b16_d16_hi v45, v21 offset:432
	ds_write_b16 v45, v22 offset:576
	ds_write_b16_d16_hi v45, v22 offset:720
	ds_write_b16 v45, v23 offset:864
	ds_write_b16_d16_hi v45, v23 offset:1008
	s_waitcnt vmcnt(1)
	ds_write_b16 v45, v24 offset:9216
	ds_write_b16_d16_hi v45, v24 offset:9360
	ds_write_b16 v45, v25 offset:9504
	ds_write_b16_d16_hi v45, v25 offset:9648
	ds_write_b16 v45, v26 offset:9792
	ds_write_b16_d16_hi v45, v26 offset:9936
	ds_write_b16 v45, v27 offset:10080
	ds_write_b16_d16_hi v45, v27 offset:10224
	s_waitcnt vmcnt(0)
	ds_write_b16 v45, v28 offset:18432
	ds_write_b16_d16_hi v45, v28 offset:18576
	ds_write_b16 v45, v29 offset:18720
	ds_write_b16_d16_hi v45, v29 offset:18864
	ds_write_b16 v45, v30 offset:19008
	ds_write_b16_d16_hi v45, v30 offset:19152
	ds_write_b16 v45, v31 offset:19296
	ds_write_b16_d16_hi v45, v31 offset:19440
	ds_read_b128 v[8:11], v72
	v_pk_mul_f32 v[16:17], v[12:13], s[66:67] op_sel_hi:[1,0]
	v_pk_mul_f32 v[20:21], v[14:15], s[66:67] op_sel_hi:[1,0]
	ds_read_b128 v[12:15], v72 offset:16
	v_pk_mul_f32 v[18:19], v[34:35], s[66:67] op_sel_hi:[1,0]
	s_waitcnt lgkmcnt(1)
	v_mul_f32_e32 v9, 0x3fb8aa3b, v9
	v_mul_f32_e32 v11, 0x3fb8aa3b, v11
	v_mul_f32_e32 v10, 0x3fb8aa3b, v10
	s_waitcnt lgkmcnt(0)
	v_mul_f32_e32 v22, 0x3fb8aa3b, v12
	v_mul_f32_e32 v23, 0x3fb8aa3b, v13
	v_mul_f32_e32 v25, 0x3fb8aa3b, v14
	v_mul_f32_e32 v26, 0x3fb8aa3b, v15
	v_exp_f32_e32 v14, v9
	v_exp_f32_e32 v15, v11
	v_exp_f32_e32 v22, v22
	v_exp_f32_e32 v24, v23
	v_exp_f32_e32 v23, v25
	v_exp_f32_e32 v25, v26
	v_mul_f32_e32 v8, 0x3fb8aa3b, v8
	v_exp_f32_e32 v13, v10
	v_pk_mul_f32 v[10:11], v[16:17], v[14:15]
	v_pk_mul_f32 v[16:17], v[18:19], v[22:23]
	v_pk_mul_f32 v[18:19], v[20:21], v[24:25]
	v_exp_f32_e32 v12, v8
	v_bfe_u32 v20, v19, 16, 1
	v_bfe_u32 v21, v18, 16, 1
	v_bfe_u32 v26, v11, 16, 1
	v_bfe_u32 v27, v10, 16, 1
	v_add3_u32 v27, v10, v27, s90
	v_add3_u32 v26, v11, v26, s90
	v_add3_u32 v10, v18, v21, s90
	v_add3_u32 v11, v19, v20, s90
	v_bfe_u32 v18, v16, 16, 1
	v_bfe_u32 v19, v17, 16, 1
	v_add3_u32 v17, v17, v19, s90
	v_add3_u32 v16, v16, v18, s90
	v_lshrrev_b32_e32 v16, 16, v16
	v_lshrrev_b32_e32 v17, 16, v17
	v_rcp_f32_e32 v14, v14
	v_rcp_f32_e32 v15, v15
	v_rcp_f32_e32 v18, v24
	v_rcp_f32_e32 v19, v25
	v_pk_mul_f32 v[8:9], v[32:33], v[12:13]
	v_and_or_b32 v11, v11, s89, v17
	v_and_or_b32 v10, v10, s89, v16
	v_rcp_f32_e32 v12, v12
	v_rcp_f32_e32 v13, v13
	v_rcp_f32_e32 v16, v22
	v_rcp_f32_e32 v17, v23
	v_pk_mul_f32 v[14:15], v[14:15], v[38:39]
	v_pk_mul_f32 v[18:19], v[18:19], v[42:43]
	v_bfe_u32 v28, v8, 16, 1
	v_bfe_u32 v29, v9, 16, 1
	v_pk_mul_f32 v[12:13], v[12:13], v[36:37]
	v_pk_mul_f32 v[16:17], v[16:17], v[40:41]
	v_bfe_u32 v20, v19, 16, 1
	v_bfe_u32 v21, v18, 16, 1
	v_bfe_u32 v22, v15, 16, 1
	v_bfe_u32 v23, v14, 16, 1
	v_add3_u32 v9, v9, v29, s90
	v_add3_u32 v8, v8, v28, s90
	v_add3_u32 v23, v14, v23, s90
	v_add3_u32 v22, v15, v22, s90
	v_add3_u32 v14, v18, v21, s90
	v_add3_u32 v15, v19, v20, s90
	v_bfe_u32 v18, v12, 16, 1
	v_bfe_u32 v19, v13, 16, 1
	v_bfe_u32 v20, v16, 16, 1
	v_bfe_u32 v21, v17, 16, 1
	v_lshrrev_b32_e32 v8, 16, v8
	v_lshrrev_b32_e32 v9, 16, v9
	v_add3_u32 v17, v17, v21, s90
	v_add3_u32 v16, v16, v20, s90
	v_add3_u32 v13, v13, v19, s90
	v_add3_u32 v12, v12, v18, s90
	v_and_or_b32 v9, v26, s89, v9
	v_and_or_b32 v8, v27, s89, v8
	v_lshrrev_b32_e32 v12, 16, v12
	v_lshrrev_b32_e32 v13, 16, v13
	v_lshrrev_b32_e32 v16, 16, v16
	v_lshrrev_b32_e32 v17, 16, v17
	v_and_or_b32 v15, v15, s89, v17
	v_and_or_b32 v14, v14, s89, v16
	v_and_or_b32 v13, v22, s89, v13
	v_and_or_b32 v12, v23, s89, v12
	ds_write_b128 v73, v[8:11] offset:33792
	ds_write_b128 v73, v[12:15] offset:51200
	v_lshlrev_b32_e32 v9, 16, v5
	v_lshlrev_b32_e32 v8, 16, v4
	v_and_b32_e32 v11, 0xffff0000, v5
	v_and_b32_e32 v10, 0xffff0000, v4
	v_lshlrev_b32_e32 v13, 16, v7
	v_lshlrev_b32_e32 v12, 16, v6
	v_and_b32_e32 v15, 0xffff0000, v7
	v_and_b32_e32 v14, 0xffff0000, v6
	ds_read_b128 v[4:7], v72 offset:256
	v_lshlrev_b32_e32 v17, 16, v1
	v_lshlrev_b32_e32 v16, 16, v0
	v_and_b32_e32 v19, 0xffff0000, v1
	v_and_b32_e32 v18, 0xffff0000, v0
	v_lshlrev_b32_e32 v21, 16, v3
	v_lshlrev_b32_e32 v20, 16, v2
	v_and_b32_e32 v23, 0xffff0000, v3
	v_and_b32_e32 v22, 0xffff0000, v2
	ds_read_b128 v[0:3], v72 offset:272
	s_waitcnt lgkmcnt(1)
; #define LAS __attribute__((address_space(3)))
; __device__ __forceinline__ unsigned f2bf(float f) { unsigned u = __builtin_bit_cast(unsigned, f); return (u + 0x7fffu + ((u >> 16) & 1u)) >> 16; }
; __device__ __forceinline__ void gla_out(const Ptrs& A, int l, LAS unsigned char* lds, int c, int G, int wave, int lane_, const int wv0) {
;     ...
;         for (int i = 0; i < 2; ++i) { const int d0 = (wave + 8 * i) * 8; float xq[8], xk[8]; unpack8(qq[i], xq); unpack8(kk[i], xk);
;             const f32x4 b0 = *(const LAS f32x4*)(bl + lane * BLS + d0), b1 = *(const LAS f32x4*)(bl + lane * BLS + d0 + 4);
;             float eb[8]; eb[0] = __expf(b0.x); eb[1] = __expf(b0.y); eb[2] = __expf(b0.z); eb[3] = __expf(b0.w); eb[4] = __expf(b1.x); eb[5] = __expf(b1.y); eb[6] = __expf(b1.z); eb[7] = __expf(b1.w);
;             u32x4 oq, ok;
;             oq.x = pk2(xq[0] * 0.08838834764831845f * eb[0], xq[1] * 0.08838834764831845f * eb[1]); oq.y = pk2(xq[2] * 0.08838834764831845f * eb[2], xq[3] * 0.08838834764831845f * eb[3]);
;             oq.z = pk2(xq[4] * 0.08838834764831845f * eb[4], xq[5] * 0.08838834764831845f * eb[5]); oq.w = pk2(xq[6] * 0.08838834764831845f * eb[6], xq[7] * 0.08838834764831845f * eb[7]);
;             ok.x = pk2(xk[0] * __builtin_amdgcn_rcpf(eb[0]), xk[1] * __builtin_amdgcn_rcpf(eb[1])); ok.y = pk2(xk[2] * __builtin_amdgcn_rcpf(eb[2]), xk[3] * __builtin_amdgcn_rcpf(eb[3]));
;             ok.z = pk2(xk[4] * __builtin_amdgcn_rcpf(eb[4]), xk[5] * __builtin_amdgcn_rcpf(eb[5])); ok.w = pk2(xk[6] * __builtin_amdgcn_rcpf(eb[6]), xk[7] * __builtin_amdgcn_rcpf(eb[7]));
;             *(LAS u32x4*)(QE + lane * 136 + d0) = oq; *(LAS u32x4*)(KE + lane * 136 + d0) = ok; }
;         __syncthreads();
;         if (wave < 4) { const int ti = wave >> 1, tj = wave & 1; f32x16 acc = {};
;             if (tj <= ti) {
; #pragma unroll
;                 for (int ks = 0; ks < 8; ++ks) { const bf16x8 a = *(const LAS bf16x8*)(QE + (32 * ti + r32) * 136 + 16 * ks + 8 * hi), b = *(const LAS bf16x8*)(KE + (32 * tj + r32) * 136 + 16 * ks + 8 * hi);
;                     acc = __builtin_amdgcn_mfma_f32_32x32x16_bf16(a, b, acc, 0, 0, 0); } }
; #pragma unroll
;             for (int r = 0; r < 16; ++r) { const int t = 32 * ti + crow(r, hi), sx = 32 * tj + r32; SM[t * 72 + sx] = (bf16)f2bf(sx <= t ? acc[r] : 0.f); } }
	v_mul_f32_e32 v5, 0x3fb8aa3b, v5
	v_exp_f32_e32 v24, v5
	v_mul_f32_e32 v5, 0x3fb8aa3b, v6
	v_mul_f32_e32 v6, 0x3fb8aa3b, v7
	s_waitcnt lgkmcnt(0)
	v_mul_f32_e32 v0, 0x3fb8aa3b, v0
	v_exp_f32_e32 v25, v6
	v_exp_f32_e32 v6, v0
	v_mul_f32_e32 v0, 0x3fb8aa3b, v1
	v_exp_f32_e32 v26, v0
	v_mul_f32_e32 v0, 0x3fb8aa3b, v2
	v_exp_f32_e32 v7, v0
	v_mul_f32_e32 v0, 0x3fb8aa3b, v3
	v_exp_f32_e32 v27, v0
	v_mul_f32_e32 v4, 0x3fb8aa3b, v4
	v_exp_f32_e32 v4, v4
	v_exp_f32_e32 v5, v5
	v_pk_mul_f32 v[2:3], v[10:11], s[66:67] op_sel_hi:[1,0]
	v_pk_mul_f32 v[10:11], v[14:15], s[66:67] op_sel_hi:[1,0]
	v_pk_mul_f32 v[0:1], v[8:9], s[66:67] op_sel_hi:[1,0]
	v_pk_mul_f32 v[2:3], v[2:3], v[24:25]
	v_pk_mul_f32 v[8:9], v[12:13], s[66:67] op_sel_hi:[1,0]
	v_pk_mul_f32 v[10:11], v[10:11], v[26:27]
	v_pk_mul_f32 v[8:9], v[8:9], v[6:7]
	v_bfe_u32 v12, v11, 16, 1
	v_bfe_u32 v13, v10, 16, 1
	v_bfe_u32 v14, v3, 16, 1
	v_bfe_u32 v15, v2, 16, 1
	v_add3_u32 v15, v2, v15, s90
	v_add3_u32 v14, v3, v14, s90
	v_add3_u32 v2, v10, v13, s90
	v_add3_u32 v3, v11, v12, s90
	v_bfe_u32 v12, v8, 16, 1
	v_bfe_u32 v13, v9, 16, 1
	v_pk_mul_f32 v[0:1], v[0:1], v[4:5]
	v_add3_u32 v9, v9, v13, s90
	v_add3_u32 v8, v8, v12, s90
	v_bfe_u32 v10, v0, 16, 1
	v_bfe_u32 v11, v1, 16, 1
	v_lshrrev_b32_e32 v8, 16, v8
	v_lshrrev_b32_e32 v9, 16, v9
	v_add3_u32 v1, v1, v11, s90
	v_add3_u32 v0, v0, v10, s90
	v_and_or_b32 v3, v3, s89, v9
	v_and_or_b32 v2, v2, s89, v8
	v_rcp_f32_e32 v8, v24
	v_rcp_f32_e32 v9, v25
	v_rcp_f32_e32 v10, v26
	v_rcp_f32_e32 v11, v27
	v_rcp_f32_e32 v4, v4
	v_rcp_f32_e32 v5, v5
	v_rcp_f32_e32 v6, v6
	v_rcp_f32_e32 v7, v7
	v_lshrrev_b32_e32 v0, 16, v0
	v_lshrrev_b32_e32 v1, 16, v1
	v_pk_mul_f32 v[8:9], v[8:9], v[18:19]
	v_pk_mul_f32 v[10:11], v[10:11], v[22:23]
	v_and_or_b32 v1, v14, s89, v1
	v_and_or_b32 v0, v15, s89, v0
	v_pk_mul_f32 v[4:5], v[4:5], v[16:17]
	v_pk_mul_f32 v[6:7], v[6:7], v[20:21]
	v_bfe_u32 v12, v11, 16, 1
	v_bfe_u32 v13, v10, 16, 1
	v_bfe_u32 v14, v9, 16, 1
	v_bfe_u32 v15, v8, 16, 1
	v_add3_u32 v8, v8, v15, s90
	v_add3_u32 v9, v9, v14, s90
	v_add3_u32 v10, v10, v13, s90
	v_add3_u32 v11, v11, v12, s90
	v_bfe_u32 v12, v4, 16, 1
	v_bfe_u32 v13, v5, 16, 1
	v_bfe_u32 v14, v6, 16, 1
	v_bfe_u32 v15, v7, 16, 1
	v_add3_u32 v7, v7, v15, s90
	v_add3_u32 v6, v6, v14, s90
	v_add3_u32 v5, v5, v13, s90
	v_add3_u32 v4, v4, v12, s90
	v_lshrrev_b32_e32 v4, 16, v4
	v_lshrrev_b32_e32 v5, 16, v5
	v_lshrrev_b32_e32 v6, 16, v6
	v_lshrrev_b32_e32 v7, 16, v7
	v_and_or_b32 v7, v11, s89, v7
	v_and_or_b32 v6, v10, s89, v6
	v_and_or_b32 v5, v9, s89, v5
	v_and_or_b32 v4, v8, s89, v4
	ds_write_b128 v73, v[0:3] offset:33920
	ds_write_b128 v73, v[4:7] offset:51328
	s_waitcnt lgkmcnt(0)
	s_barrier
	s_cbranch_vccnz .LBB0_1336
	v_mov_b32_e32 v0, 0
	s_andn2_b64 vcc, exec, s[60:61]
	v_mov_b32_e32 v1, 0
	v_mov_b32_e32 v2, 0
	v_mov_b32_e32 v3, 0
	v_mov_b32_e32 v4, 0
	v_mov_b32_e32 v5, 0
	v_mov_b32_e32 v6, 0
	v_mov_b32_e32 v7, 0
	v_mov_b32_e32 v8, 0
	v_mov_b32_e32 v9, 0
	v_mov_b32_e32 v10, 0
	v_mov_b32_e32 v11, 0
	v_mov_b32_e32 v12, 0
	v_mov_b32_e32 v13, 0
	v_mov_b32_e32 v14, 0
	v_mov_b32_e32 v15, 0
	s_cbranch_vccnz .LBB0_1335
	ds_read_b128 v[0:3], v65 offset:33792
	ds_read_b128 v[4:7], v66 offset:51200
	ds_read_b128 v[16:19], v65 offset:33824
	ds_read_b128 v[20:23], v66 offset:51232
	s_waitcnt lgkmcnt(2)
	v_mfma_f32_32x32x16_bf16 v[0:15], v[0:3], v[4:7], 0
	s_waitcnt lgkmcnt(0)
	v_mfma_f32_32x32x16_bf16 v[0:15], v[16:19], v[20:23], v[0:15]
	ds_read_b128 v[16:19], v65 offset:33856
	ds_read_b128 v[20:23], v66 offset:51264
	ds_read_b128 v[24:27], v65 offset:33888
	ds_read_b128 v[28:31], v66 offset:51296
	s_waitcnt lgkmcnt(2)
	v_mfma_f32_32x32x16_bf16 v[0:15], v[16:19], v[20:23], v[0:15]
	s_waitcnt lgkmcnt(0)
	v_mfma_f32_32x32x16_bf16 v[0:15], v[24:27], v[28:31], v[0:15]
	ds_read_b128 v[16:19], v65 offset:33920
	ds_read_b128 v[20:23], v66 offset:51328
	ds_read_b128 v[24:27], v65 offset:33952
	ds_read_b128 v[28:31], v66 offset:51360
	s_waitcnt lgkmcnt(2)
	v_mfma_f32_32x32x16_bf16 v[0:15], v[16:19], v[20:23], v[0:15]
	s_waitcnt lgkmcnt(0)
	v_mfma_f32_32x32x16_bf16 v[0:15], v[24:27], v[28:31], v[0:15]
	ds_read_b128 v[16:19], v65 offset:33984
	ds_read_b128 v[20:23], v66 offset:51392
	ds_read_b128 v[24:27], v65 offset:34016
	ds_read_b128 v[28:31], v66 offset:51424
	s_waitcnt lgkmcnt(2)
	v_mfma_f32_32x32x16_bf16 v[0:15], v[16:19], v[20:23], v[0:15]
	s_waitcnt lgkmcnt(0)
	v_mfma_f32_32x32x16_bf16 v[0:15], v[24:27], v[28:31], v[0:15]
